# G2 triangular solve transposed (lane = RHS column, one v_readlane per A[i][j], unrolled, same fma order); GEMM tile boundary: removed spurious vmcnt(0) in accumulator zeroing
# speedup vs baseline: 1.0321x; 1.0117x over previous
.LBB0_364:
	v_cndmask_b32_e64 v0, v91, 1.0, s[26:27]
	s_xor_b64 s[28:29], s[26:27], -1
	v_mov_b32_e32 v1, v0
	v_and_b32_e32 v3, 63, v210
	v_lshlrev_b32_e32 v3, 8, v3
	v_sub_u32_e32 v3, v231, v3
	ds_read_b32 v21, v3
	ds_read_b32 v23, v3 offset:260
	ds_read_b32 v25, v3 offset:520
	ds_read_b32 v27, v3 offset:780
	ds_read_b32 v29, v3 offset:1040
	ds_read_b32 v31, v3 offset:1300
	ds_read_b32 v33, v3 offset:1560
	ds_read_b32 v35, v3 offset:1820
	ds_read_b32 v37, v3 offset:2080
	ds_read_b32 v39, v3 offset:2340
	ds_read_b32 v41, v3 offset:2600
	ds_read_b32 v43, v3 offset:2860
	s_waitcnt lgkmcnt(11)
	ds_read_b32 v45, v3 offset:3120
	s_waitcnt lgkmcnt(11)
	ds_read_b32 v47, v3 offset:3380
	s_waitcnt lgkmcnt(11)
	ds_read_b32 v49, v3 offset:3640
	s_waitcnt lgkmcnt(11)
	ds_read_b32 v51, v3 offset:3900
	s_waitcnt lgkmcnt(11)
	ds_read_b32 v53, v3 offset:4160
	s_waitcnt lgkmcnt(11)
	ds_read_b32 v55, v3 offset:4420
	s_waitcnt lgkmcnt(11)
	ds_read_b32 v57, v3 offset:4680
	s_waitcnt lgkmcnt(11)
	ds_read_b32 v119, v3 offset:4940
	s_waitcnt lgkmcnt(11)
	ds_read_b32 v121, v3 offset:5200
	s_waitcnt lgkmcnt(11)
	ds_read_b32 v123, v3 offset:5460
	s_waitcnt lgkmcnt(11)
	ds_read_b32 v125, v3 offset:5720
	s_waitcnt lgkmcnt(11)
	ds_read_b32 v127, v3 offset:5980
	s_waitcnt lgkmcnt(11)
	ds_read_b32 v129, v3 offset:6240
	s_waitcnt lgkmcnt(11)
	ds_read_b32 v131, v3 offset:6500
	s_waitcnt lgkmcnt(11)
	ds_read_b32 v133, v3 offset:6760
	s_waitcnt lgkmcnt(11)
	ds_read_b32 v135, v3 offset:7020
	s_waitcnt lgkmcnt(11)
	ds_read_b32 v137, v3 offset:7280
	s_waitcnt lgkmcnt(11)
	ds_read_b32 v139, v3 offset:7540
	s_waitcnt lgkmcnt(11)
	ds_read_b32 v141, v3 offset:7800
	s_waitcnt lgkmcnt(11)
	ds_read_b32 v143, v3 offset:8060
	s_waitcnt lgkmcnt(11)
	ds_read_b32 v145, v3 offset:8320
	s_waitcnt lgkmcnt(11)
	ds_read_b32 v147, v3 offset:8580
	s_waitcnt lgkmcnt(11)
	ds_read_b32 v149, v3 offset:8840
	s_waitcnt lgkmcnt(11)
	ds_read_b32 v151, v3 offset:9100
	s_waitcnt lgkmcnt(11)
	ds_read_b32 v153, v3 offset:9360
	s_waitcnt lgkmcnt(11)
	ds_read_b32 v155, v3 offset:9620
	s_waitcnt lgkmcnt(11)
	ds_read_b32 v157, v3 offset:9880
	s_waitcnt lgkmcnt(11)
	ds_read_b32 v159, v3 offset:10140
	s_waitcnt lgkmcnt(11)
	ds_read_b32 v161, v3 offset:10400
	s_waitcnt lgkmcnt(11)
	ds_read_b32 v163, v3 offset:10660
	s_waitcnt lgkmcnt(11)
	ds_read_b32 v165, v3 offset:10920
	s_waitcnt lgkmcnt(11)
	ds_read_b32 v167, v3 offset:11180
	s_waitcnt lgkmcnt(11)
	ds_read_b32 v169, v3 offset:11440
	s_waitcnt lgkmcnt(11)
	ds_read_b32 v171, v3 offset:11700
	s_waitcnt lgkmcnt(11)
	ds_read_b32 v173, v3 offset:11960
	s_waitcnt lgkmcnt(11)
	ds_read_b32 v175, v3 offset:12220
	s_waitcnt lgkmcnt(11)
	ds_read_b32 v177, v3 offset:12480
	s_waitcnt lgkmcnt(11)
	ds_read_b32 v179, v3 offset:12740
	s_waitcnt lgkmcnt(11)
	ds_read_b32 v181, v3 offset:13000
	s_waitcnt lgkmcnt(11)
	ds_read_b32 v183, v3 offset:13260
	s_waitcnt lgkmcnt(11)
	ds_read_b32 v185, v3 offset:13520
	s_waitcnt lgkmcnt(11)
	ds_read_b32 v187, v3 offset:13780
	s_waitcnt lgkmcnt(11)
	ds_read_b32 v189, v3 offset:14040
	s_waitcnt lgkmcnt(11)
	ds_read_b32 v191, v3 offset:14300
	s_waitcnt lgkmcnt(11)
	ds_read_b32 v193, v3 offset:14560
	s_waitcnt lgkmcnt(11)
	ds_read_b32 v195, v3 offset:14820
	s_waitcnt lgkmcnt(11)
	ds_read_b32 v197, v3 offset:15080
	s_waitcnt lgkmcnt(11)
	ds_read_b32 v199, v3 offset:15340
	s_waitcnt lgkmcnt(11)
	ds_read_b32 v201, v3 offset:15600
	s_waitcnt lgkmcnt(11)
	ds_read_b32 v203, v3 offset:15860
	s_waitcnt lgkmcnt(11)
	ds_read_b32 v205, v3 offset:16120
	s_waitcnt lgkmcnt(11)
	ds_read_b32 v214, v3 offset:16380
	s_waitcnt lgkmcnt(0)
	s_nop 0
	v_readlane_b32 s30, v0, 0
	v_readlane_b32 s31, v0, 1
	v_readlane_b32 s42, v0, 2
	v_readlane_b32 s43, v0, 3
	v_mul_f32_e32 v21, s30, v21
	v_readlane_b32 s98, v0, 4
	v_mul_f32_e32 v23, s31, v23
	v_readlane_b32 s99, v0, 5
	v_mul_f32_e32 v25, s42, v25
	v_readlane_b32 s100, v0, 6
	v_mul_f32_e32 v27, s43, v27
	v_readlane_b32 s101, v0, 7
	v_mul_f32_e32 v29, s98, v29
	v_readlane_b32 s30, v0, 8
	v_mul_f32_e32 v31, s99, v31
	v_readlane_b32 s31, v0, 9
	v_mul_f32_e32 v33, s100, v33
	v_readlane_b32 s42, v0, 10
	v_mul_f32_e32 v35, s101, v35
	v_readlane_b32 s43, v0, 11
	v_mul_f32_e32 v37, s30, v37
	v_readlane_b32 s98, v0, 12
	v_mul_f32_e32 v39, s31, v39
	v_readlane_b32 s99, v0, 13
	v_mul_f32_e32 v41, s42, v41
	v_readlane_b32 s100, v0, 14
	v_mul_f32_e32 v43, s43, v43
	v_readlane_b32 s101, v0, 15
	v_mul_f32_e32 v45, s98, v45
	v_readlane_b32 s30, v0, 16
	v_mul_f32_e32 v47, s99, v47
	v_readlane_b32 s31, v0, 17
	v_mul_f32_e32 v49, s100, v49
	v_readlane_b32 s42, v0, 18
	v_mul_f32_e32 v51, s101, v51
	v_readlane_b32 s43, v0, 19
	v_mul_f32_e32 v53, s30, v53
	v_readlane_b32 s98, v0, 20
	v_mul_f32_e32 v55, s31, v55
	v_readlane_b32 s99, v0, 21
	v_mul_f32_e32 v57, s42, v57
	v_readlane_b32 s100, v0, 22
	v_mul_f32_e32 v119, s43, v119
	v_readlane_b32 s101, v0, 23
	v_mul_f32_e32 v121, s98, v121
	v_readlane_b32 s30, v0, 24
	v_mul_f32_e32 v123, s99, v123
	v_readlane_b32 s31, v0, 25
	v_mul_f32_e32 v125, s100, v125
	v_readlane_b32 s42, v0, 26
	v_mul_f32_e32 v127, s101, v127
	v_readlane_b32 s43, v0, 27
	v_mul_f32_e32 v129, s30, v129
	v_readlane_b32 s98, v0, 28
	v_mul_f32_e32 v131, s31, v131
	v_readlane_b32 s99, v0, 29
	v_mul_f32_e32 v133, s42, v133
	v_readlane_b32 s100, v0, 30
	v_mul_f32_e32 v135, s43, v135
	v_readlane_b32 s101, v0, 31
	v_mul_f32_e32 v137, s98, v137
	v_readlane_b32 s30, v0, 32
	v_mul_f32_e32 v139, s99, v139
	v_readlane_b32 s31, v0, 33
	v_mul_f32_e32 v141, s100, v141
	v_readlane_b32 s42, v0, 34
	v_mul_f32_e32 v143, s101, v143
	v_readlane_b32 s43, v0, 35
	v_mul_f32_e32 v145, s30, v145
	v_readlane_b32 s98, v0, 36
	v_mul_f32_e32 v147, s31, v147
	v_readlane_b32 s99, v0, 37
	v_mul_f32_e32 v149, s42, v149
	v_readlane_b32 s100, v0, 38
	v_mul_f32_e32 v151, s43, v151
	v_readlane_b32 s101, v0, 39
	v_mul_f32_e32 v153, s98, v153
	v_readlane_b32 s30, v0, 40
	v_mul_f32_e32 v155, s99, v155
	v_readlane_b32 s31, v0, 41
	v_mul_f32_e32 v157, s100, v157
	v_readlane_b32 s42, v0, 42
	v_mul_f32_e32 v159, s101, v159
	v_readlane_b32 s43, v0, 43
	v_mul_f32_e32 v161, s30, v161
	v_readlane_b32 s98, v0, 44
	v_mul_f32_e32 v163, s31, v163
	v_readlane_b32 s99, v0, 45
	v_mul_f32_e32 v165, s42, v165
	v_readlane_b32 s100, v0, 46
	v_mul_f32_e32 v167, s43, v167
	v_readlane_b32 s101, v0, 47
	v_mul_f32_e32 v169, s98, v169
	v_readlane_b32 s30, v0, 48
	v_mul_f32_e32 v171, s99, v171
	v_readlane_b32 s31, v0, 49
	v_mul_f32_e32 v173, s100, v173
	v_readlane_b32 s42, v0, 50
	v_mul_f32_e32 v175, s101, v175
	v_readlane_b32 s43, v0, 51
	v_mul_f32_e32 v177, s30, v177
	v_readlane_b32 s98, v0, 52
	v_mul_f32_e32 v179, s31, v179
	v_readlane_b32 s99, v0, 53
	v_mul_f32_e32 v181, s42, v181
	v_readlane_b32 s100, v0, 54
	v_mul_f32_e32 v183, s43, v183
	v_readlane_b32 s101, v0, 55
	v_mul_f32_e32 v185, s98, v185
	v_readlane_b32 s30, v0, 56
	v_mul_f32_e32 v187, s99, v187
	v_readlane_b32 s31, v0, 57
	v_mul_f32_e32 v189, s100, v189
	v_readlane_b32 s42, v0, 58
	v_mul_f32_e32 v191, s101, v191
	v_readlane_b32 s43, v0, 59
	v_mul_f32_e32 v193, s30, v193
	v_readlane_b32 s98, v0, 60
	v_mul_f32_e32 v195, s31, v195
	v_readlane_b32 s99, v0, 61
	v_mul_f32_e32 v197, s42, v197
	v_readlane_b32 s100, v0, 62
	v_mul_f32_e32 v199, s43, v199
	v_readlane_b32 s101, v0, 63
	v_mul_f32_e32 v201, s98, v201
	v_readlane_b32 s30, v20, 1
	v_mul_f32_e32 v203, s99, v203
	v_readlane_b32 s31, v20, 2
	v_mul_f32_e32 v205, s100, v205
	v_readlane_b32 s42, v20, 3
	v_mul_f32_e32 v214, s101, v214
	v_readlane_b32 s43, v22, 2
	v_fma_f32 v23, s30, v21, v23
	v_readlane_b32 s98, v22, 3
	v_fma_f32 v25, s31, v21, v25
	v_readlane_b32 s99, v24, 3
	v_fma_f32 v27, s42, v21, v27
	v_readlane_b32 s100, v20, 4
	v_fma_f32 v25, s43, v23, v25
	v_readlane_b32 s101, v20, 5
	v_fma_f32 v27, s98, v23, v27
	v_readlane_b32 s30, v20, 6
	v_fma_f32 v27, s99, v25, v27
	v_readlane_b32 s31, v20, 7
	v_fma_f32 v29, s100, v21, v29
	v_readlane_b32 s42, v22, 4
	v_fma_f32 v31, s101, v21, v31
	v_readlane_b32 s43, v22, 5
	v_fma_f32 v33, s30, v21, v33
	v_readlane_b32 s98, v22, 6
	v_fma_f32 v35, s31, v21, v35
	v_readlane_b32 s99, v22, 7
	v_fma_f32 v29, s42, v23, v29
	v_readlane_b32 s100, v24, 4
	v_fma_f32 v31, s43, v23, v31
	v_readlane_b32 s101, v24, 5
	v_fma_f32 v33, s98, v23, v33
	v_readlane_b32 s30, v24, 6
	v_fma_f32 v35, s99, v23, v35
	v_readlane_b32 s31, v24, 7
	v_fma_f32 v29, s100, v25, v29
	v_readlane_b32 s42, v26, 4
	v_fma_f32 v31, s101, v25, v31
	v_readlane_b32 s43, v26, 5
	v_fma_f32 v33, s30, v25, v33
	v_readlane_b32 s98, v26, 6
	v_fma_f32 v35, s31, v25, v35
	v_readlane_b32 s99, v26, 7
	v_fma_f32 v29, s42, v27, v29
	v_readlane_b32 s100, v28, 5
	v_fma_f32 v31, s43, v27, v31
	v_readlane_b32 s101, v28, 6
	v_fma_f32 v33, s98, v27, v33
	v_readlane_b32 s30, v28, 7
	v_fma_f32 v35, s99, v27, v35
	v_readlane_b32 s31, v30, 6
	v_fma_f32 v31, s100, v29, v31
	v_readlane_b32 s42, v30, 7
	v_fma_f32 v33, s101, v29, v33
	v_readlane_b32 s43, v32, 7
	v_fma_f32 v35, s30, v29, v35
	v_readlane_b32 s98, v20, 8
	v_fma_f32 v33, s31, v31, v33
	v_readlane_b32 s99, v20, 9
	v_fma_f32 v35, s42, v31, v35
	v_readlane_b32 s100, v20, 10
	v_fma_f32 v35, s43, v33, v35
	v_readlane_b32 s101, v20, 11
	v_fma_f32 v37, s98, v21, v37
	v_readlane_b32 s30, v22, 8
	v_fma_f32 v39, s99, v21, v39
	v_readlane_b32 s31, v22, 9
	v_fma_f32 v41, s100, v21, v41
	v_readlane_b32 s42, v22, 10
	v_fma_f32 v43, s101, v21, v43
	v_readlane_b32 s43, v22, 11
	v_fma_f32 v37, s30, v23, v37
	v_readlane_b32 s98, v24, 8
	v_fma_f32 v39, s31, v23, v39
	v_readlane_b32 s99, v24, 9
	v_fma_f32 v41, s42, v23, v41
	v_readlane_b32 s100, v24, 10
	v_fma_f32 v43, s43, v23, v43
	v_readlane_b32 s101, v24, 11
	v_fma_f32 v37, s98, v25, v37
	v_readlane_b32 s30, v26, 8
	v_fma_f32 v39, s99, v25, v39
	v_readlane_b32 s31, v26, 9
	v_fma_f32 v41, s100, v25, v41
	v_readlane_b32 s42, v26, 10
	v_fma_f32 v43, s101, v25, v43
	v_readlane_b32 s43, v26, 11
	v_fma_f32 v37, s30, v27, v37
	v_readlane_b32 s98, v28, 8
	v_fma_f32 v39, s31, v27, v39
	v_readlane_b32 s99, v28, 9
	v_fma_f32 v41, s42, v27, v41
	v_readlane_b32 s100, v28, 10
	v_fma_f32 v43, s43, v27, v43
	v_readlane_b32 s101, v28, 11
	v_fma_f32 v37, s98, v29, v37
	v_readlane_b32 s30, v30, 8
	v_fma_f32 v39, s99, v29, v39
	v_readlane_b32 s31, v30, 9
	v_fma_f32 v41, s100, v29, v41
	v_readlane_b32 s42, v30, 10
	v_fma_f32 v43, s101, v29, v43
	v_readlane_b32 s43, v30, 11
	v_fma_f32 v37, s30, v31, v37
	v_readlane_b32 s98, v32, 8
	v_fma_f32 v39, s31, v31, v39
	v_readlane_b32 s99, v32, 9
	v_fma_f32 v41, s42, v31, v41
	v_readlane_b32 s100, v32, 10
	v_fma_f32 v43, s43, v31, v43
	v_readlane_b32 s101, v32, 11
	v_fma_f32 v37, s98, v33, v37
	v_readlane_b32 s30, v34, 8
	v_fma_f32 v39, s99, v33, v39
	v_readlane_b32 s31, v34, 9
	v_fma_f32 v41, s100, v33, v41
	v_readlane_b32 s42, v34, 10
	v_fma_f32 v43, s101, v33, v43
	v_readlane_b32 s43, v34, 11
	v_fma_f32 v37, s30, v35, v37
	v_readlane_b32 s98, v36, 9
	v_fma_f32 v39, s31, v35, v39
	v_readlane_b32 s99, v36, 10
	v_fma_f32 v41, s42, v35, v41
	v_readlane_b32 s100, v36, 11
	v_fma_f32 v43, s43, v35, v43
	v_readlane_b32 s101, v38, 10
	v_fma_f32 v39, s98, v37, v39
	v_readlane_b32 s30, v38, 11
	v_fma_f32 v41, s99, v37, v41
	v_readlane_b32 s31, v40, 11
	v_fma_f32 v43, s100, v37, v43
	v_readlane_b32 s42, v20, 12
	v_fma_f32 v41, s101, v39, v41
	v_readlane_b32 s43, v20, 13
	v_fma_f32 v43, s30, v39, v43
	v_readlane_b32 s98, v20, 14
	v_fma_f32 v43, s31, v41, v43
	v_readlane_b32 s99, v20, 15
	v_fma_f32 v45, s42, v21, v45
	v_readlane_b32 s100, v22, 12
	v_fma_f32 v47, s43, v21, v47
	v_readlane_b32 s101, v22, 13
	v_fma_f32 v49, s98, v21, v49
	v_readlane_b32 s30, v22, 14
	v_fma_f32 v51, s99, v21, v51
	v_readlane_b32 s31, v22, 15
	v_fma_f32 v45, s100, v23, v45
	v_readlane_b32 s42, v24, 12
	v_fma_f32 v47, s101, v23, v47
	v_readlane_b32 s43, v24, 13
	v_fma_f32 v49, s30, v23, v49
	v_readlane_b32 s98, v24, 14
	v_fma_f32 v51, s31, v23, v51
	v_readlane_b32 s99, v24, 15
	v_fma_f32 v45, s42, v25, v45
	v_readlane_b32 s100, v26, 12
	v_fma_f32 v47, s43, v25, v47
	v_readlane_b32 s101, v26, 13
	v_fma_f32 v49, s98, v25, v49
	v_readlane_b32 s30, v26, 14
	v_fma_f32 v51, s99, v25, v51
	v_readlane_b32 s31, v26, 15
	v_fma_f32 v45, s100, v27, v45
	v_readlane_b32 s42, v28, 12
	v_fma_f32 v47, s101, v27, v47
	v_readlane_b32 s43, v28, 13
	v_fma_f32 v49, s30, v27, v49
	v_readlane_b32 s98, v28, 14
	v_fma_f32 v51, s31, v27, v51
	v_readlane_b32 s99, v28, 15
	v_fma_f32 v45, s42, v29, v45
	v_readlane_b32 s100, v30, 12
	v_fma_f32 v47, s43, v29, v47
	v_readlane_b32 s101, v30, 13
	v_fma_f32 v49, s98, v29, v49
	v_readlane_b32 s30, v30, 14
	v_fma_f32 v51, s99, v29, v51
	v_readlane_b32 s31, v30, 15
	v_fma_f32 v45, s100, v31, v45
	v_readlane_b32 s42, v32, 12
	v_fma_f32 v47, s101, v31, v47
	v_readlane_b32 s43, v32, 13
	v_fma_f32 v49, s30, v31, v49
	v_readlane_b32 s98, v32, 14
	v_fma_f32 v51, s31, v31, v51
	v_readlane_b32 s99, v32, 15
	v_fma_f32 v45, s42, v33, v45
	v_readlane_b32 s100, v34, 12
	v_fma_f32 v47, s43, v33, v47
	v_readlane_b32 s101, v34, 13
	v_fma_f32 v49, s98, v33, v49
	v_readlane_b32 s30, v34, 14
	v_fma_f32 v51, s99, v33, v51
	v_readlane_b32 s31, v34, 15
	v_fma_f32 v45, s100, v35, v45
	v_readlane_b32 s42, v36, 12
	v_fma_f32 v47, s101, v35, v47
	v_readlane_b32 s43, v36, 13
	v_fma_f32 v49, s30, v35, v49
	v_readlane_b32 s98, v36, 14
	v_fma_f32 v51, s31, v35, v51
	v_readlane_b32 s99, v36, 15
	v_fma_f32 v45, s42, v37, v45
	v_readlane_b32 s100, v38, 12
	v_fma_f32 v47, s43, v37, v47
	v_readlane_b32 s101, v38, 13
	v_fma_f32 v49, s98, v37, v49
	v_readlane_b32 s30, v38, 14
	v_fma_f32 v51, s99, v37, v51
	v_readlane_b32 s31, v38, 15
	v_fma_f32 v45, s100, v39, v45
	v_readlane_b32 s42, v40, 12
	v_fma_f32 v47, s101, v39, v47
	v_readlane_b32 s43, v40, 13
	v_fma_f32 v49, s30, v39, v49
	v_readlane_b32 s98, v40, 14
	v_fma_f32 v51, s31, v39, v51
	v_readlane_b32 s99, v40, 15
	v_fma_f32 v45, s42, v41, v45
	v_readlane_b32 s100, v42, 12
	v_fma_f32 v47, s43, v41, v47
	v_readlane_b32 s101, v42, 13
	v_fma_f32 v49, s98, v41, v49
	v_readlane_b32 s30, v42, 14
	v_fma_f32 v51, s99, v41, v51
	v_readlane_b32 s31, v42, 15
	v_fma_f32 v45, s100, v43, v45
	v_readlane_b32 s42, v44, 13
	v_fma_f32 v47, s101, v43, v47
	v_readlane_b32 s43, v44, 14
	v_fma_f32 v49, s30, v43, v49
	v_readlane_b32 s98, v44, 15
	v_fma_f32 v51, s31, v43, v51
	v_readlane_b32 s99, v46, 14
	v_fma_f32 v47, s42, v45, v47
	v_readlane_b32 s100, v46, 15
	v_fma_f32 v49, s43, v45, v49
	v_readlane_b32 s101, v48, 15
	v_fma_f32 v51, s98, v45, v51
	v_readlane_b32 s30, v20, 16
	v_fma_f32 v49, s99, v47, v49
	v_readlane_b32 s31, v20, 17
	v_fma_f32 v51, s100, v47, v51
	v_readlane_b32 s42, v20, 18
	v_fma_f32 v51, s101, v49, v51
	v_readlane_b32 s43, v20, 19
	v_fma_f32 v53, s30, v21, v53
	v_readlane_b32 s98, v22, 16
	v_fma_f32 v55, s31, v21, v55
	v_readlane_b32 s99, v22, 17
	v_fma_f32 v57, s42, v21, v57
	v_readlane_b32 s100, v22, 18
	v_fma_f32 v119, s43, v21, v119
	v_readlane_b32 s101, v22, 19
	v_fma_f32 v53, s98, v23, v53
	v_readlane_b32 s30, v24, 16
	v_fma_f32 v55, s99, v23, v55
	v_readlane_b32 s31, v24, 17
	v_fma_f32 v57, s100, v23, v57
	v_readlane_b32 s42, v24, 18
	v_fma_f32 v119, s101, v23, v119
	v_readlane_b32 s43, v24, 19
	v_fma_f32 v53, s30, v25, v53
	v_readlane_b32 s98, v26, 16
	v_fma_f32 v55, s31, v25, v55
	v_readlane_b32 s99, v26, 17
	v_fma_f32 v57, s42, v25, v57
	v_readlane_b32 s100, v26, 18
	v_fma_f32 v119, s43, v25, v119
	v_readlane_b32 s101, v26, 19
	v_fma_f32 v53, s98, v27, v53
	v_readlane_b32 s30, v28, 16
	v_fma_f32 v55, s99, v27, v55
	v_readlane_b32 s31, v28, 17
	v_fma_f32 v57, s100, v27, v57
	v_readlane_b32 s42, v28, 18
	v_fma_f32 v119, s101, v27, v119
	v_readlane_b32 s43, v28, 19
	v_fma_f32 v53, s30, v29, v53
	v_readlane_b32 s98, v30, 16
	v_fma_f32 v55, s31, v29, v55
	v_readlane_b32 s99, v30, 17
	v_fma_f32 v57, s42, v29, v57
	v_readlane_b32 s100, v30, 18
	v_fma_f32 v119, s43, v29, v119
	v_readlane_b32 s101, v30, 19
	v_fma_f32 v53, s98, v31, v53
	v_readlane_b32 s30, v32, 16
	v_fma_f32 v55, s99, v31, v55
	v_readlane_b32 s31, v32, 17
	v_fma_f32 v57, s100, v31, v57
	v_readlane_b32 s42, v32, 18
	v_fma_f32 v119, s101, v31, v119
	v_readlane_b32 s43, v32, 19
	v_fma_f32 v53, s30, v33, v53
	v_readlane_b32 s98, v34, 16
	v_fma_f32 v55, s31, v33, v55
	v_readlane_b32 s99, v34, 17
	v_fma_f32 v57, s42, v33, v57
	v_readlane_b32 s100, v34, 18
	v_fma_f32 v119, s43, v33, v119
	v_readlane_b32 s101, v34, 19
	v_fma_f32 v53, s98, v35, v53
	v_readlane_b32 s30, v36, 16
	v_fma_f32 v55, s99, v35, v55
	v_readlane_b32 s31, v36, 17
	v_fma_f32 v57, s100, v35, v57
	v_readlane_b32 s42, v36, 18
	v_fma_f32 v119, s101, v35, v119
	v_readlane_b32 s43, v36, 19
	v_fma_f32 v53, s30, v37, v53
	v_readlane_b32 s98, v38, 16
	v_fma_f32 v55, s31, v37, v55
	v_readlane_b32 s99, v38, 17
	v_fma_f32 v57, s42, v37, v57
	v_readlane_b32 s100, v38, 18
	v_fma_f32 v119, s43, v37, v119
	v_readlane_b32 s101, v38, 19
	v_fma_f32 v53, s98, v39, v53
	v_readlane_b32 s30, v40, 16
	v_fma_f32 v55, s99, v39, v55
	v_readlane_b32 s31, v40, 17
	v_fma_f32 v57, s100, v39, v57
	v_readlane_b32 s42, v40, 18
	v_fma_f32 v119, s101, v39, v119
	v_readlane_b32 s43, v40, 19
	v_fma_f32 v53, s30, v41, v53
	v_readlane_b32 s98, v42, 16
	v_fma_f32 v55, s31, v41, v55
	v_readlane_b32 s99, v42, 17
	v_fma_f32 v57, s42, v41, v57
	v_readlane_b32 s100, v42, 18
	v_fma_f32 v119, s43, v41, v119
	v_readlane_b32 s101, v42, 19
	v_fma_f32 v53, s98, v43, v53
	v_readlane_b32 s30, v44, 16
	v_fma_f32 v55, s99, v43, v55
	v_readlane_b32 s31, v44, 17
	v_fma_f32 v57, s100, v43, v57
	v_readlane_b32 s42, v44, 18
	v_fma_f32 v119, s101, v43, v119
	v_readlane_b32 s43, v44, 19
	v_fma_f32 v53, s30, v45, v53
	v_readlane_b32 s98, v46, 16
	v_fma_f32 v55, s31, v45, v55
	v_readlane_b32 s99, v46, 17
	v_fma_f32 v57, s42, v45, v57
	v_readlane_b32 s100, v46, 18
	v_fma_f32 v119, s43, v45, v119
	v_readlane_b32 s101, v46, 19
	v_fma_f32 v53, s98, v47, v53
	v_readlane_b32 s30, v48, 16
	v_fma_f32 v55, s99, v47, v55
	v_readlane_b32 s31, v48, 17
	v_fma_f32 v57, s100, v47, v57
	v_readlane_b32 s42, v48, 18
	v_fma_f32 v119, s101, v47, v119
	v_readlane_b32 s43, v48, 19
	v_fma_f32 v53, s30, v49, v53
	v_readlane_b32 s98, v50, 16
	v_fma_f32 v55, s31, v49, v55
	v_readlane_b32 s99, v50, 17
	v_fma_f32 v57, s42, v49, v57
	v_readlane_b32 s100, v50, 18
	v_fma_f32 v119, s43, v49, v119
	v_readlane_b32 s101, v50, 19
	v_fma_f32 v53, s98, v51, v53
	v_readlane_b32 s30, v52, 17
	v_fma_f32 v55, s99, v51, v55
	v_readlane_b32 s31, v52, 18
	v_fma_f32 v57, s100, v51, v57
	v_readlane_b32 s42, v52, 19
	v_fma_f32 v119, s101, v51, v119
	v_readlane_b32 s43, v54, 18
	v_fma_f32 v55, s30, v53, v55
	v_readlane_b32 s98, v54, 19
	v_fma_f32 v57, s31, v53, v57
	v_readlane_b32 s99, v56, 19
	v_fma_f32 v119, s42, v53, v119
	v_readlane_b32 s100, v20, 20
	v_fma_f32 v57, s43, v55, v57
	v_readlane_b32 s101, v20, 21
	v_fma_f32 v119, s98, v55, v119
	v_readlane_b32 s30, v20, 22
	v_fma_f32 v119, s99, v57, v119
	v_readlane_b32 s31, v20, 23
	v_fma_f32 v121, s100, v21, v121
	v_readlane_b32 s42, v22, 20
	v_fma_f32 v123, s101, v21, v123
	v_readlane_b32 s43, v22, 21
	v_fma_f32 v125, s30, v21, v125
	v_readlane_b32 s98, v22, 22
	v_fma_f32 v127, s31, v21, v127
	v_readlane_b32 s99, v22, 23
	v_fma_f32 v121, s42, v23, v121
	v_readlane_b32 s100, v24, 20
	v_fma_f32 v123, s43, v23, v123
	v_readlane_b32 s101, v24, 21
	v_fma_f32 v125, s98, v23, v125
	v_readlane_b32 s30, v24, 22
	v_fma_f32 v127, s99, v23, v127
	v_readlane_b32 s31, v24, 23
	v_fma_f32 v121, s100, v25, v121
	v_readlane_b32 s42, v26, 20
	v_fma_f32 v123, s101, v25, v123
	v_readlane_b32 s43, v26, 21
	v_fma_f32 v125, s30, v25, v125
	v_readlane_b32 s98, v26, 22
	v_fma_f32 v127, s31, v25, v127
	v_readlane_b32 s99, v26, 23
	v_fma_f32 v121, s42, v27, v121
	v_readlane_b32 s100, v28, 20
	v_fma_f32 v123, s43, v27, v123
	v_readlane_b32 s101, v28, 21
	v_fma_f32 v125, s98, v27, v125
	v_readlane_b32 s30, v28, 22
	v_fma_f32 v127, s99, v27, v127
	v_readlane_b32 s31, v28, 23
	v_fma_f32 v121, s100, v29, v121
	v_readlane_b32 s42, v30, 20
	v_fma_f32 v123, s101, v29, v123
	v_readlane_b32 s43, v30, 21
	v_fma_f32 v125, s30, v29, v125
	v_readlane_b32 s98, v30, 22
	v_fma_f32 v127, s31, v29, v127
	v_readlane_b32 s99, v30, 23
	v_fma_f32 v121, s42, v31, v121
	v_readlane_b32 s100, v32, 20
	v_fma_f32 v123, s43, v31, v123
	v_readlane_b32 s101, v32, 21
	v_fma_f32 v125, s98, v31, v125
	v_readlane_b32 s30, v32, 22
	v_fma_f32 v127, s99, v31, v127
	v_readlane_b32 s31, v32, 23
	v_fma_f32 v121, s100, v33, v121
	v_readlane_b32 s42, v34, 20
	v_fma_f32 v123, s101, v33, v123
	v_readlane_b32 s43, v34, 21
	v_fma_f32 v125, s30, v33, v125
	v_readlane_b32 s98, v34, 22
	v_fma_f32 v127, s31, v33, v127
	v_readlane_b32 s99, v34, 23
	v_fma_f32 v121, s42, v35, v121
	v_readlane_b32 s100, v36, 20
	v_fma_f32 v123, s43, v35, v123
	v_readlane_b32 s101, v36, 21
	v_fma_f32 v125, s98, v35, v125
	v_readlane_b32 s30, v36, 22
	v_fma_f32 v127, s99, v35, v127
	v_readlane_b32 s31, v36, 23
	v_fma_f32 v121, s100, v37, v121
	v_readlane_b32 s42, v38, 20
	v_fma_f32 v123, s101, v37, v123
	v_readlane_b32 s43, v38, 21
	v_fma_f32 v125, s30, v37, v125
	v_readlane_b32 s98, v38, 22
	v_fma_f32 v127, s31, v37, v127
	v_readlane_b32 s99, v38, 23
	v_fma_f32 v121, s42, v39, v121
	v_readlane_b32 s100, v40, 20
	v_fma_f32 v123, s43, v39, v123
	v_readlane_b32 s101, v40, 21
	v_fma_f32 v125, s98, v39, v125
	v_readlane_b32 s30, v40, 22
	v_fma_f32 v127, s99, v39, v127
	v_readlane_b32 s31, v40, 23
	v_fma_f32 v121, s100, v41, v121
	v_readlane_b32 s42, v42, 20
	v_fma_f32 v123, s101, v41, v123
	v_readlane_b32 s43, v42, 21
	v_fma_f32 v125, s30, v41, v125
	v_readlane_b32 s98, v42, 22
	v_fma_f32 v127, s31, v41, v127
	v_readlane_b32 s99, v42, 23
	v_fma_f32 v121, s42, v43, v121
	v_readlane_b32 s100, v44, 20
	v_fma_f32 v123, s43, v43, v123
	v_readlane_b32 s101, v44, 21
	v_fma_f32 v125, s98, v43, v125
	v_readlane_b32 s30, v44, 22
	v_fma_f32 v127, s99, v43, v127
	v_readlane_b32 s31, v44, 23
	v_fma_f32 v121, s100, v45, v121
	v_readlane_b32 s42, v46, 20
	v_fma_f32 v123, s101, v45, v123
	v_readlane_b32 s43, v46, 21
	v_fma_f32 v125, s30, v45, v125
	v_readlane_b32 s98, v46, 22
	v_fma_f32 v127, s31, v45, v127
	v_readlane_b32 s99, v46, 23
	v_fma_f32 v121, s42, v47, v121
	v_readlane_b32 s100, v48, 20
	v_fma_f32 v123, s43, v47, v123
	v_readlane_b32 s101, v48, 21
	v_fma_f32 v125, s98, v47, v125
	v_readlane_b32 s30, v48, 22
	v_fma_f32 v127, s99, v47, v127
	v_readlane_b32 s31, v48, 23
	v_fma_f32 v121, s100, v49, v121
	v_readlane_b32 s42, v50, 20
	v_fma_f32 v123, s101, v49, v123
	v_readlane_b32 s43, v50, 21
	v_fma_f32 v125, s30, v49, v125
	v_readlane_b32 s98, v50, 22
	v_fma_f32 v127, s31, v49, v127
	v_readlane_b32 s99, v50, 23
	v_fma_f32 v121, s42, v51, v121
	v_readlane_b32 s100, v52, 20
	v_fma_f32 v123, s43, v51, v123
	v_readlane_b32 s101, v52, 21
	v_fma_f32 v125, s98, v51, v125
	v_readlane_b32 s30, v52, 22
	v_fma_f32 v127, s99, v51, v127
	v_readlane_b32 s31, v52, 23
	v_fma_f32 v121, s100, v53, v121
	v_readlane_b32 s42, v54, 20
	v_fma_f32 v123, s101, v53, v123
	v_readlane_b32 s43, v54, 21
	v_fma_f32 v125, s30, v53, v125
	v_readlane_b32 s98, v54, 22
	v_fma_f32 v127, s31, v53, v127
	v_readlane_b32 s99, v54, 23
	v_fma_f32 v121, s42, v55, v121
	v_readlane_b32 s100, v56, 20
	v_fma_f32 v123, s43, v55, v123
	v_readlane_b32 s101, v56, 21
	v_fma_f32 v125, s98, v55, v125
	v_readlane_b32 s30, v56, 22
	v_fma_f32 v127, s99, v55, v127
	v_readlane_b32 s31, v56, 23
	v_fma_f32 v121, s100, v57, v121
	v_readlane_b32 s42, v118, 20
	v_fma_f32 v123, s101, v57, v123
	v_readlane_b32 s43, v118, 21
	v_fma_f32 v125, s30, v57, v125
	v_readlane_b32 s98, v118, 22
	v_fma_f32 v127, s31, v57, v127
	v_readlane_b32 s99, v118, 23
	v_fma_f32 v121, s42, v119, v121
	v_readlane_b32 s100, v120, 21
	v_fma_f32 v123, s43, v119, v123
	v_readlane_b32 s101, v120, 22
	v_fma_f32 v125, s98, v119, v125
	v_readlane_b32 s30, v120, 23
	v_fma_f32 v127, s99, v119, v127
	v_readlane_b32 s31, v122, 22
	v_fma_f32 v123, s100, v121, v123
	v_readlane_b32 s42, v122, 23
	v_fma_f32 v125, s101, v121, v125
	v_readlane_b32 s43, v124, 23
	v_fma_f32 v127, s30, v121, v127
	v_readlane_b32 s98, v20, 24
	v_fma_f32 v125, s31, v123, v125
	v_readlane_b32 s99, v20, 25
	v_fma_f32 v127, s42, v123, v127
	v_readlane_b32 s100, v20, 26
	v_fma_f32 v127, s43, v125, v127
	v_readlane_b32 s101, v20, 27
	v_fma_f32 v129, s98, v21, v129
	v_readlane_b32 s30, v22, 24
	v_fma_f32 v131, s99, v21, v131
	v_readlane_b32 s31, v22, 25
	v_fma_f32 v133, s100, v21, v133
	v_readlane_b32 s42, v22, 26
	v_fma_f32 v135, s101, v21, v135
	v_readlane_b32 s43, v22, 27
	v_fma_f32 v129, s30, v23, v129
	v_readlane_b32 s98, v24, 24
	v_fma_f32 v131, s31, v23, v131
	v_readlane_b32 s99, v24, 25
	v_fma_f32 v133, s42, v23, v133
	v_readlane_b32 s100, v24, 26
	v_fma_f32 v135, s43, v23, v135
	v_readlane_b32 s101, v24, 27
	v_fma_f32 v129, s98, v25, v129
	v_readlane_b32 s30, v26, 24
	v_fma_f32 v131, s99, v25, v131
	v_readlane_b32 s31, v26, 25
	v_fma_f32 v133, s100, v25, v133
	v_readlane_b32 s42, v26, 26
	v_fma_f32 v135, s101, v25, v135
	v_readlane_b32 s43, v26, 27
	v_fma_f32 v129, s30, v27, v129
	v_readlane_b32 s98, v28, 24
	v_fma_f32 v131, s31, v27, v131
	v_readlane_b32 s99, v28, 25
	v_fma_f32 v133, s42, v27, v133
	v_readlane_b32 s100, v28, 26
	v_fma_f32 v135, s43, v27, v135
	v_readlane_b32 s101, v28, 27
	v_fma_f32 v129, s98, v29, v129
	v_readlane_b32 s30, v30, 24
	v_fma_f32 v131, s99, v29, v131
	v_readlane_b32 s31, v30, 25
	v_fma_f32 v133, s100, v29, v133
	v_readlane_b32 s42, v30, 26
	v_fma_f32 v135, s101, v29, v135
	v_readlane_b32 s43, v30, 27
	v_fma_f32 v129, s30, v31, v129
	v_readlane_b32 s98, v32, 24
	v_fma_f32 v131, s31, v31, v131
	v_readlane_b32 s99, v32, 25
	v_fma_f32 v133, s42, v31, v133
	v_readlane_b32 s100, v32, 26
	v_fma_f32 v135, s43, v31, v135
	v_readlane_b32 s101, v32, 27
	v_fma_f32 v129, s98, v33, v129
	v_readlane_b32 s30, v34, 24
	v_fma_f32 v131, s99, v33, v131
	v_readlane_b32 s31, v34, 25
	v_fma_f32 v133, s100, v33, v133
	v_readlane_b32 s42, v34, 26
	v_fma_f32 v135, s101, v33, v135
	v_readlane_b32 s43, v34, 27
	v_fma_f32 v129, s30, v35, v129
	v_readlane_b32 s98, v36, 24
	v_fma_f32 v131, s31, v35, v131
	v_readlane_b32 s99, v36, 25
	v_fma_f32 v133, s42, v35, v133
	v_readlane_b32 s100, v36, 26
	v_fma_f32 v135, s43, v35, v135
	v_readlane_b32 s101, v36, 27
	v_fma_f32 v129, s98, v37, v129
	v_readlane_b32 s30, v38, 24
	v_fma_f32 v131, s99, v37, v131
	v_readlane_b32 s31, v38, 25
	v_fma_f32 v133, s100, v37, v133
	v_readlane_b32 s42, v38, 26
	v_fma_f32 v135, s101, v37, v135
	v_readlane_b32 s43, v38, 27
	v_fma_f32 v129, s30, v39, v129
	v_readlane_b32 s98, v40, 24
	v_fma_f32 v131, s31, v39, v131
	v_readlane_b32 s99, v40, 25
	v_fma_f32 v133, s42, v39, v133
	v_readlane_b32 s100, v40, 26
	v_fma_f32 v135, s43, v39, v135
	v_readlane_b32 s101, v40, 27
	v_fma_f32 v129, s98, v41, v129
	v_readlane_b32 s30, v42, 24
	v_fma_f32 v131, s99, v41, v131
	v_readlane_b32 s31, v42, 25
	v_fma_f32 v133, s100, v41, v133
	v_readlane_b32 s42, v42, 26
	v_fma_f32 v135, s101, v41, v135
	v_readlane_b32 s43, v42, 27
	v_fma_f32 v129, s30, v43, v129
	v_readlane_b32 s98, v44, 24
	v_fma_f32 v131, s31, v43, v131
	v_readlane_b32 s99, v44, 25
	v_fma_f32 v133, s42, v43, v133
	v_readlane_b32 s100, v44, 26
	v_fma_f32 v135, s43, v43, v135
	v_readlane_b32 s101, v44, 27
	v_fma_f32 v129, s98, v45, v129
	v_readlane_b32 s30, v46, 24
	v_fma_f32 v131, s99, v45, v131
	v_readlane_b32 s31, v46, 25
	v_fma_f32 v133, s100, v45, v133
	v_readlane_b32 s42, v46, 26
	v_fma_f32 v135, s101, v45, v135
	v_readlane_b32 s43, v46, 27
	v_fma_f32 v129, s30, v47, v129
	v_readlane_b32 s98, v48, 24
	v_fma_f32 v131, s31, v47, v131
	v_readlane_b32 s99, v48, 25
	v_fma_f32 v133, s42, v47, v133
	v_readlane_b32 s100, v48, 26
	v_fma_f32 v135, s43, v47, v135
	v_readlane_b32 s101, v48, 27
	v_fma_f32 v129, s98, v49, v129
	v_readlane_b32 s30, v50, 24
	v_fma_f32 v131, s99, v49, v131
	v_readlane_b32 s31, v50, 25
	v_fma_f32 v133, s100, v49, v133
	v_readlane_b32 s42, v50, 26
	v_fma_f32 v135, s101, v49, v135
	v_readlane_b32 s43, v50, 27
	v_fma_f32 v129, s30, v51, v129
	v_readlane_b32 s98, v52, 24
	v_fma_f32 v131, s31, v51, v131
	v_readlane_b32 s99, v52, 25
	v_fma_f32 v133, s42, v51, v133
	v_readlane_b32 s100, v52, 26
	v_fma_f32 v135, s43, v51, v135
	v_readlane_b32 s101, v52, 27
	v_fma_f32 v129, s98, v53, v129
	v_readlane_b32 s30, v54, 24
	v_fma_f32 v131, s99, v53, v131
	v_readlane_b32 s31, v54, 25
	v_fma_f32 v133, s100, v53, v133
	v_readlane_b32 s42, v54, 26
	v_fma_f32 v135, s101, v53, v135
	v_readlane_b32 s43, v54, 27
	v_fma_f32 v129, s30, v55, v129
	v_readlane_b32 s98, v56, 24
	v_fma_f32 v131, s31, v55, v131
	v_readlane_b32 s99, v56, 25
	v_fma_f32 v133, s42, v55, v133
	v_readlane_b32 s100, v56, 26
	v_fma_f32 v135, s43, v55, v135
	v_readlane_b32 s101, v56, 27
	v_fma_f32 v129, s98, v57, v129
	v_readlane_b32 s30, v118, 24
	v_fma_f32 v131, s99, v57, v131
	v_readlane_b32 s31, v118, 25
	v_fma_f32 v133, s100, v57, v133
	v_readlane_b32 s42, v118, 26
	v_fma_f32 v135, s101, v57, v135
	v_readlane_b32 s43, v118, 27
	v_fma_f32 v129, s30, v119, v129
	v_readlane_b32 s98, v120, 24
	v_fma_f32 v131, s31, v119, v131
	v_readlane_b32 s99, v120, 25
	v_fma_f32 v133, s42, v119, v133
	v_readlane_b32 s100, v120, 26
	v_fma_f32 v135, s43, v119, v135
	v_readlane_b32 s101, v120, 27
	v_fma_f32 v129, s98, v121, v129
	v_readlane_b32 s30, v122, 24
	v_fma_f32 v131, s99, v121, v131
	v_readlane_b32 s31, v122, 25
	v_fma_f32 v133, s100, v121, v133
	v_readlane_b32 s42, v122, 26
	v_fma_f32 v135, s101, v121, v135
	v_readlane_b32 s43, v122, 27
	v_fma_f32 v129, s30, v123, v129
	v_readlane_b32 s98, v124, 24
	v_fma_f32 v131, s31, v123, v131
	v_readlane_b32 s99, v124, 25
	v_fma_f32 v133, s42, v123, v133
	v_readlane_b32 s100, v124, 26
	v_fma_f32 v135, s43, v123, v135
	v_readlane_b32 s101, v124, 27
	v_fma_f32 v129, s98, v125, v129
	v_readlane_b32 s30, v126, 24
	v_fma_f32 v131, s99, v125, v131
	v_readlane_b32 s31, v126, 25
	v_fma_f32 v133, s100, v125, v133
	v_readlane_b32 s42, v126, 26
	v_fma_f32 v135, s101, v125, v135
	v_readlane_b32 s43, v126, 27
	v_fma_f32 v129, s30, v127, v129
	v_readlane_b32 s98, v128, 25
	v_fma_f32 v131, s31, v127, v131
	v_readlane_b32 s99, v128, 26
	v_fma_f32 v133, s42, v127, v133
	v_readlane_b32 s100, v128, 27
	v_fma_f32 v135, s43, v127, v135
	v_readlane_b32 s101, v130, 26
	v_fma_f32 v131, s98, v129, v131
	v_readlane_b32 s30, v130, 27
	v_fma_f32 v133, s99, v129, v133
	v_readlane_b32 s31, v132, 27
	v_fma_f32 v135, s100, v129, v135
	v_readlane_b32 s42, v20, 28
	v_fma_f32 v133, s101, v131, v133
	v_readlane_b32 s43, v20, 29
	v_fma_f32 v135, s30, v131, v135
	v_readlane_b32 s98, v20, 30
	v_fma_f32 v135, s31, v133, v135
	v_readlane_b32 s99, v20, 31
	v_fma_f32 v137, s42, v21, v137
	v_readlane_b32 s100, v22, 28
	v_fma_f32 v139, s43, v21, v139
	v_readlane_b32 s101, v22, 29
	v_fma_f32 v141, s98, v21, v141
	v_readlane_b32 s30, v22, 30
	v_fma_f32 v143, s99, v21, v143
	v_readlane_b32 s31, v22, 31
	v_fma_f32 v137, s100, v23, v137
	v_readlane_b32 s42, v24, 28
	v_fma_f32 v139, s101, v23, v139
	v_readlane_b32 s43, v24, 29
	v_fma_f32 v141, s30, v23, v141
	v_readlane_b32 s98, v24, 30
	v_fma_f32 v143, s31, v23, v143
	v_readlane_b32 s99, v24, 31
	v_fma_f32 v137, s42, v25, v137
	v_readlane_b32 s100, v26, 28
	v_fma_f32 v139, s43, v25, v139
	v_readlane_b32 s101, v26, 29
	v_fma_f32 v141, s98, v25, v141
	v_readlane_b32 s30, v26, 30
	v_fma_f32 v143, s99, v25, v143
	v_readlane_b32 s31, v26, 31
	v_fma_f32 v137, s100, v27, v137
	v_readlane_b32 s42, v28, 28
	v_fma_f32 v139, s101, v27, v139
	v_readlane_b32 s43, v28, 29
	v_fma_f32 v141, s30, v27, v141
	v_readlane_b32 s98, v28, 30
	v_fma_f32 v143, s31, v27, v143
	v_readlane_b32 s99, v28, 31
	v_fma_f32 v137, s42, v29, v137
	v_readlane_b32 s100, v30, 28
	v_fma_f32 v139, s43, v29, v139
	v_readlane_b32 s101, v30, 29
	v_fma_f32 v141, s98, v29, v141
	v_readlane_b32 s30, v30, 30
	v_fma_f32 v143, s99, v29, v143
	v_readlane_b32 s31, v30, 31
	v_fma_f32 v137, s100, v31, v137
	v_readlane_b32 s42, v32, 28
	v_fma_f32 v139, s101, v31, v139
	v_readlane_b32 s43, v32, 29
	v_fma_f32 v141, s30, v31, v141
	v_readlane_b32 s98, v32, 30
	v_fma_f32 v143, s31, v31, v143
	v_readlane_b32 s99, v32, 31
	v_fma_f32 v137, s42, v33, v137
	v_readlane_b32 s100, v34, 28
	v_fma_f32 v139, s43, v33, v139
	v_readlane_b32 s101, v34, 29
	v_fma_f32 v141, s98, v33, v141
	v_readlane_b32 s30, v34, 30
	v_fma_f32 v143, s99, v33, v143
	v_readlane_b32 s31, v34, 31
	v_fma_f32 v137, s100, v35, v137
	v_readlane_b32 s42, v36, 28
	v_fma_f32 v139, s101, v35, v139
	v_readlane_b32 s43, v36, 29
	v_fma_f32 v141, s30, v35, v141
	v_readlane_b32 s98, v36, 30
	v_fma_f32 v143, s31, v35, v143
	v_readlane_b32 s99, v36, 31
	v_fma_f32 v137, s42, v37, v137
	v_readlane_b32 s100, v38, 28
	v_fma_f32 v139, s43, v37, v139
	v_readlane_b32 s101, v38, 29
	v_fma_f32 v141, s98, v37, v141
	v_readlane_b32 s30, v38, 30
	v_fma_f32 v143, s99, v37, v143
	v_readlane_b32 s31, v38, 31
	v_fma_f32 v137, s100, v39, v137
	v_readlane_b32 s42, v40, 28
	v_fma_f32 v139, s101, v39, v139
	v_readlane_b32 s43, v40, 29
	v_fma_f32 v141, s30, v39, v141
	v_readlane_b32 s98, v40, 30
	v_fma_f32 v143, s31, v39, v143
	v_readlane_b32 s99, v40, 31
	v_fma_f32 v137, s42, v41, v137
	v_readlane_b32 s100, v42, 28
	v_fma_f32 v139, s43, v41, v139
	v_readlane_b32 s101, v42, 29
	v_fma_f32 v141, s98, v41, v141
	v_readlane_b32 s30, v42, 30
	v_fma_f32 v143, s99, v41, v143
	v_readlane_b32 s31, v42, 31
	v_fma_f32 v137, s100, v43, v137
	v_readlane_b32 s42, v44, 28
	v_fma_f32 v139, s101, v43, v139
	v_readlane_b32 s43, v44, 29
	v_fma_f32 v141, s30, v43, v141
	v_readlane_b32 s98, v44, 30
	v_fma_f32 v143, s31, v43, v143
	v_readlane_b32 s99, v44, 31
	v_fma_f32 v137, s42, v45, v137
	v_readlane_b32 s100, v46, 28
	v_fma_f32 v139, s43, v45, v139
	v_readlane_b32 s101, v46, 29
	v_fma_f32 v141, s98, v45, v141
	v_readlane_b32 s30, v46, 30
	v_fma_f32 v143, s99, v45, v143
	v_readlane_b32 s31, v46, 31
	v_fma_f32 v137, s100, v47, v137
	v_readlane_b32 s42, v48, 28
	v_fma_f32 v139, s101, v47, v139
	v_readlane_b32 s43, v48, 29
	v_fma_f32 v141, s30, v47, v141
	v_readlane_b32 s98, v48, 30
	v_fma_f32 v143, s31, v47, v143
	v_readlane_b32 s99, v48, 31
	v_fma_f32 v137, s42, v49, v137
	v_readlane_b32 s100, v50, 28
	v_fma_f32 v139, s43, v49, v139
	v_readlane_b32 s101, v50, 29
	v_fma_f32 v141, s98, v49, v141
	v_readlane_b32 s30, v50, 30
	v_fma_f32 v143, s99, v49, v143
	v_readlane_b32 s31, v50, 31
	v_fma_f32 v137, s100, v51, v137
	v_readlane_b32 s42, v52, 28
	v_fma_f32 v139, s101, v51, v139
	v_readlane_b32 s43, v52, 29
	v_fma_f32 v141, s30, v51, v141
	v_readlane_b32 s98, v52, 30
	v_fma_f32 v143, s31, v51, v143
	v_readlane_b32 s99, v52, 31
	v_fma_f32 v137, s42, v53, v137
	v_readlane_b32 s100, v54, 28
	v_fma_f32 v139, s43, v53, v139
	v_readlane_b32 s101, v54, 29
	v_fma_f32 v141, s98, v53, v141
	v_readlane_b32 s30, v54, 30
	v_fma_f32 v143, s99, v53, v143
	v_readlane_b32 s31, v54, 31
	v_fma_f32 v137, s100, v55, v137
	v_readlane_b32 s42, v56, 28
	v_fma_f32 v139, s101, v55, v139
	v_readlane_b32 s43, v56, 29
	v_fma_f32 v141, s30, v55, v141
	v_readlane_b32 s98, v56, 30
	v_fma_f32 v143, s31, v55, v143
	v_readlane_b32 s99, v56, 31
	v_fma_f32 v137, s42, v57, v137
	v_readlane_b32 s100, v118, 28
	v_fma_f32 v139, s43, v57, v139
	v_readlane_b32 s101, v118, 29
	v_fma_f32 v141, s98, v57, v141
	v_readlane_b32 s30, v118, 30
	v_fma_f32 v143, s99, v57, v143
	v_readlane_b32 s31, v118, 31
	v_fma_f32 v137, s100, v119, v137
	v_readlane_b32 s42, v120, 28
	v_fma_f32 v139, s101, v119, v139
	v_readlane_b32 s43, v120, 29
	v_fma_f32 v141, s30, v119, v141
	v_readlane_b32 s98, v120, 30
	v_fma_f32 v143, s31, v119, v143
	v_readlane_b32 s99, v120, 31
	v_fma_f32 v137, s42, v121, v137
	v_readlane_b32 s100, v122, 28
	v_fma_f32 v139, s43, v121, v139
	v_readlane_b32 s101, v122, 29
	v_fma_f32 v141, s98, v121, v141
	v_readlane_b32 s30, v122, 30
	v_fma_f32 v143, s99, v121, v143
	v_readlane_b32 s31, v122, 31
	v_fma_f32 v137, s100, v123, v137
	v_readlane_b32 s42, v124, 28
	v_fma_f32 v139, s101, v123, v139
	v_readlane_b32 s43, v124, 29
	v_fma_f32 v141, s30, v123, v141
	v_readlane_b32 s98, v124, 30
	v_fma_f32 v143, s31, v123, v143
	v_readlane_b32 s99, v124, 31
	v_fma_f32 v137, s42, v125, v137
	v_readlane_b32 s100, v126, 28
	v_fma_f32 v139, s43, v125, v139
	v_readlane_b32 s101, v126, 29
	v_fma_f32 v141, s98, v125, v141
	v_readlane_b32 s30, v126, 30
	v_fma_f32 v143, s99, v125, v143
	v_readlane_b32 s31, v126, 31
	v_fma_f32 v137, s100, v127, v137
	v_readlane_b32 s42, v128, 28
	v_fma_f32 v139, s101, v127, v139
	v_readlane_b32 s43, v128, 29
	v_fma_f32 v141, s30, v127, v141
	v_readlane_b32 s98, v128, 30
	v_fma_f32 v143, s31, v127, v143
	v_readlane_b32 s99, v128, 31
	v_fma_f32 v137, s42, v129, v137
	v_readlane_b32 s100, v130, 28
	v_fma_f32 v139, s43, v129, v139
	v_readlane_b32 s101, v130, 29
	v_fma_f32 v141, s98, v129, v141
	v_readlane_b32 s30, v130, 30
	v_fma_f32 v143, s99, v129, v143
	v_readlane_b32 s31, v130, 31
	v_fma_f32 v137, s100, v131, v137
	v_readlane_b32 s42, v132, 28
	v_fma_f32 v139, s101, v131, v139
	v_readlane_b32 s43, v132, 29
	v_fma_f32 v141, s30, v131, v141
	v_readlane_b32 s98, v132, 30
	v_fma_f32 v143, s31, v131, v143
	v_readlane_b32 s99, v132, 31
	v_fma_f32 v137, s42, v133, v137
	v_readlane_b32 s100, v134, 28
	v_fma_f32 v139, s43, v133, v139
	v_readlane_b32 s101, v134, 29
	v_fma_f32 v141, s98, v133, v141
	v_readlane_b32 s30, v134, 30
	v_fma_f32 v143, s99, v133, v143
	v_readlane_b32 s31, v134, 31
	v_fma_f32 v137, s100, v135, v137
	v_readlane_b32 s42, v136, 29
	v_fma_f32 v139, s101, v135, v139
	v_readlane_b32 s43, v136, 30
	v_fma_f32 v141, s30, v135, v141
	v_readlane_b32 s98, v136, 31
	v_fma_f32 v143, s31, v135, v143
	v_readlane_b32 s99, v138, 30
	v_fma_f32 v139, s42, v137, v139
	v_readlane_b32 s100, v138, 31
	v_fma_f32 v141, s43, v137, v141
	v_readlane_b32 s101, v140, 31
	v_fma_f32 v143, s98, v137, v143
	v_readlane_b32 s30, v20, 32
	v_fma_f32 v141, s99, v139, v141
	v_readlane_b32 s31, v20, 33
	v_fma_f32 v143, s100, v139, v143
	v_readlane_b32 s42, v20, 34
	v_fma_f32 v143, s101, v141, v143
	v_readlane_b32 s43, v20, 35
	v_fma_f32 v145, s30, v21, v145
	v_readlane_b32 s98, v22, 32
	v_fma_f32 v147, s31, v21, v147
	v_readlane_b32 s99, v22, 33
	v_fma_f32 v149, s42, v21, v149
	v_readlane_b32 s100, v22, 34
	v_fma_f32 v151, s43, v21, v151
	v_readlane_b32 s101, v22, 35
	v_fma_f32 v145, s98, v23, v145
	v_readlane_b32 s30, v24, 32
	v_fma_f32 v147, s99, v23, v147
	v_readlane_b32 s31, v24, 33
	v_fma_f32 v149, s100, v23, v149
	v_readlane_b32 s42, v24, 34
	v_fma_f32 v151, s101, v23, v151
	v_readlane_b32 s43, v24, 35
	v_fma_f32 v145, s30, v25, v145
	v_readlane_b32 s98, v26, 32
	v_fma_f32 v147, s31, v25, v147
	v_readlane_b32 s99, v26, 33
	v_fma_f32 v149, s42, v25, v149
	v_readlane_b32 s100, v26, 34
	v_fma_f32 v151, s43, v25, v151
	v_readlane_b32 s101, v26, 35
	v_fma_f32 v145, s98, v27, v145
	v_readlane_b32 s30, v28, 32
	v_fma_f32 v147, s99, v27, v147
	v_readlane_b32 s31, v28, 33
	v_fma_f32 v149, s100, v27, v149
	v_readlane_b32 s42, v28, 34
	v_fma_f32 v151, s101, v27, v151
	v_readlane_b32 s43, v28, 35
	v_fma_f32 v145, s30, v29, v145
	v_readlane_b32 s98, v30, 32
	v_fma_f32 v147, s31, v29, v147
	v_readlane_b32 s99, v30, 33
	v_fma_f32 v149, s42, v29, v149
	v_readlane_b32 s100, v30, 34
	v_fma_f32 v151, s43, v29, v151
	v_readlane_b32 s101, v30, 35
	v_fma_f32 v145, s98, v31, v145
	v_readlane_b32 s30, v32, 32
	v_fma_f32 v147, s99, v31, v147
	v_readlane_b32 s31, v32, 33
	v_fma_f32 v149, s100, v31, v149
	v_readlane_b32 s42, v32, 34
	v_fma_f32 v151, s101, v31, v151
	v_readlane_b32 s43, v32, 35
	v_fma_f32 v145, s30, v33, v145
	v_readlane_b32 s98, v34, 32
	v_fma_f32 v147, s31, v33, v147
	v_readlane_b32 s99, v34, 33
	v_fma_f32 v149, s42, v33, v149
	v_readlane_b32 s100, v34, 34
	v_fma_f32 v151, s43, v33, v151
	v_readlane_b32 s101, v34, 35
	v_fma_f32 v145, s98, v35, v145
	v_readlane_b32 s30, v36, 32
	v_fma_f32 v147, s99, v35, v147
	v_readlane_b32 s31, v36, 33
	v_fma_f32 v149, s100, v35, v149
	v_readlane_b32 s42, v36, 34
	v_fma_f32 v151, s101, v35, v151
	v_readlane_b32 s43, v36, 35
	v_fma_f32 v145, s30, v37, v145
	v_readlane_b32 s98, v38, 32
	v_fma_f32 v147, s31, v37, v147
	v_readlane_b32 s99, v38, 33
	v_fma_f32 v149, s42, v37, v149
	v_readlane_b32 s100, v38, 34
	v_fma_f32 v151, s43, v37, v151
	v_readlane_b32 s101, v38, 35
	v_fma_f32 v145, s98, v39, v145
	v_readlane_b32 s30, v40, 32
	v_fma_f32 v147, s99, v39, v147
	v_readlane_b32 s31, v40, 33
	v_fma_f32 v149, s100, v39, v149
	v_readlane_b32 s42, v40, 34
	v_fma_f32 v151, s101, v39, v151
	v_readlane_b32 s43, v40, 35
	v_fma_f32 v145, s30, v41, v145
	v_readlane_b32 s98, v42, 32
	v_fma_f32 v147, s31, v41, v147
	v_readlane_b32 s99, v42, 33
	v_fma_f32 v149, s42, v41, v149
	v_readlane_b32 s100, v42, 34
	v_fma_f32 v151, s43, v41, v151
	v_readlane_b32 s101, v42, 35
	v_fma_f32 v145, s98, v43, v145
	v_readlane_b32 s30, v44, 32
	v_fma_f32 v147, s99, v43, v147
	v_readlane_b32 s31, v44, 33
	v_fma_f32 v149, s100, v43, v149
	v_readlane_b32 s42, v44, 34
	v_fma_f32 v151, s101, v43, v151
	v_readlane_b32 s43, v44, 35
	v_fma_f32 v145, s30, v45, v145
	v_readlane_b32 s98, v46, 32
	v_fma_f32 v147, s31, v45, v147
	v_readlane_b32 s99, v46, 33
	v_fma_f32 v149, s42, v45, v149
	v_readlane_b32 s100, v46, 34
	v_fma_f32 v151, s43, v45, v151
	v_readlane_b32 s101, v46, 35
	v_fma_f32 v145, s98, v47, v145
	v_readlane_b32 s30, v48, 32
	v_fma_f32 v147, s99, v47, v147
	v_readlane_b32 s31, v48, 33
	v_fma_f32 v149, s100, v47, v149
	v_readlane_b32 s42, v48, 34
	v_fma_f32 v151, s101, v47, v151
	v_readlane_b32 s43, v48, 35
	v_fma_f32 v145, s30, v49, v145
	v_readlane_b32 s98, v50, 32
	v_fma_f32 v147, s31, v49, v147
	v_readlane_b32 s99, v50, 33
	v_fma_f32 v149, s42, v49, v149
	v_readlane_b32 s100, v50, 34
	v_fma_f32 v151, s43, v49, v151
	v_readlane_b32 s101, v50, 35
	v_fma_f32 v145, s98, v51, v145
	v_readlane_b32 s30, v52, 32
	v_fma_f32 v147, s99, v51, v147
	v_readlane_b32 s31, v52, 33
	v_fma_f32 v149, s100, v51, v149
	v_readlane_b32 s42, v52, 34
	v_fma_f32 v151, s101, v51, v151
	v_readlane_b32 s43, v52, 35
	v_fma_f32 v145, s30, v53, v145
	v_readlane_b32 s98, v54, 32
	v_fma_f32 v147, s31, v53, v147
	v_readlane_b32 s99, v54, 33
	v_fma_f32 v149, s42, v53, v149
	v_readlane_b32 s100, v54, 34
	v_fma_f32 v151, s43, v53, v151
	v_readlane_b32 s101, v54, 35
	v_fma_f32 v145, s98, v55, v145
	v_readlane_b32 s30, v56, 32
	v_fma_f32 v147, s99, v55, v147
	v_readlane_b32 s31, v56, 33
	v_fma_f32 v149, s100, v55, v149
	v_readlane_b32 s42, v56, 34
	v_fma_f32 v151, s101, v55, v151
	v_readlane_b32 s43, v56, 35
	v_fma_f32 v145, s30, v57, v145
	v_readlane_b32 s98, v118, 32
	v_fma_f32 v147, s31, v57, v147
	v_readlane_b32 s99, v118, 33
	v_fma_f32 v149, s42, v57, v149
	v_readlane_b32 s100, v118, 34
	v_fma_f32 v151, s43, v57, v151
	v_readlane_b32 s101, v118, 35
	v_fma_f32 v145, s98, v119, v145
	v_readlane_b32 s30, v120, 32
	v_fma_f32 v147, s99, v119, v147
	v_readlane_b32 s31, v120, 33
	v_fma_f32 v149, s100, v119, v149
	v_readlane_b32 s42, v120, 34
	v_fma_f32 v151, s101, v119, v151
	v_readlane_b32 s43, v120, 35
	v_fma_f32 v145, s30, v121, v145
	v_readlane_b32 s98, v122, 32
	v_fma_f32 v147, s31, v121, v147
	v_readlane_b32 s99, v122, 33
	v_fma_f32 v149, s42, v121, v149
	v_readlane_b32 s100, v122, 34
	v_fma_f32 v151, s43, v121, v151
	v_readlane_b32 s101, v122, 35
	v_fma_f32 v145, s98, v123, v145
	v_readlane_b32 s30, v124, 32
	v_fma_f32 v147, s99, v123, v147
	v_readlane_b32 s31, v124, 33
	v_fma_f32 v149, s100, v123, v149
	v_readlane_b32 s42, v124, 34
	v_fma_f32 v151, s101, v123, v151
	v_readlane_b32 s43, v124, 35
	v_fma_f32 v145, s30, v125, v145
	v_readlane_b32 s98, v126, 32
	v_fma_f32 v147, s31, v125, v147
	v_readlane_b32 s99, v126, 33
	v_fma_f32 v149, s42, v125, v149
	v_readlane_b32 s100, v126, 34
	v_fma_f32 v151, s43, v125, v151
	v_readlane_b32 s101, v126, 35
	v_fma_f32 v145, s98, v127, v145
	v_readlane_b32 s30, v128, 32
	v_fma_f32 v147, s99, v127, v147
	v_readlane_b32 s31, v128, 33
	v_fma_f32 v149, s100, v127, v149
	v_readlane_b32 s42, v128, 34
	v_fma_f32 v151, s101, v127, v151
	v_readlane_b32 s43, v128, 35
	v_fma_f32 v145, s30, v129, v145
	v_readlane_b32 s98, v130, 32
	v_fma_f32 v147, s31, v129, v147
	v_readlane_b32 s99, v130, 33
	v_fma_f32 v149, s42, v129, v149
	v_readlane_b32 s100, v130, 34
	v_fma_f32 v151, s43, v129, v151
	v_readlane_b32 s101, v130, 35
	v_fma_f32 v145, s98, v131, v145
	v_readlane_b32 s30, v132, 32
	v_fma_f32 v147, s99, v131, v147
	v_readlane_b32 s31, v132, 33
	v_fma_f32 v149, s100, v131, v149
	v_readlane_b32 s42, v132, 34
	v_fma_f32 v151, s101, v131, v151
	v_readlane_b32 s43, v132, 35
	v_fma_f32 v145, s30, v133, v145
	v_readlane_b32 s98, v134, 32
	v_fma_f32 v147, s31, v133, v147
	v_readlane_b32 s99, v134, 33
	v_fma_f32 v149, s42, v133, v149
	v_readlane_b32 s100, v134, 34
	v_fma_f32 v151, s43, v133, v151
	v_readlane_b32 s101, v134, 35
	v_fma_f32 v145, s98, v135, v145
	v_readlane_b32 s30, v136, 32
	v_fma_f32 v147, s99, v135, v147
	v_readlane_b32 s31, v136, 33
	v_fma_f32 v149, s100, v135, v149
	v_readlane_b32 s42, v136, 34
	v_fma_f32 v151, s101, v135, v151
	v_readlane_b32 s43, v136, 35
	v_fma_f32 v145, s30, v137, v145
	v_readlane_b32 s98, v138, 32
	v_fma_f32 v147, s31, v137, v147
	v_readlane_b32 s99, v138, 33
	v_fma_f32 v149, s42, v137, v149
	v_readlane_b32 s100, v138, 34
	v_fma_f32 v151, s43, v137, v151
	v_readlane_b32 s101, v138, 35
	v_fma_f32 v145, s98, v139, v145
	v_readlane_b32 s30, v140, 32
	v_fma_f32 v147, s99, v139, v147
	v_readlane_b32 s31, v140, 33
	v_fma_f32 v149, s100, v139, v149
	v_readlane_b32 s42, v140, 34
	v_fma_f32 v151, s101, v139, v151
	v_readlane_b32 s43, v140, 35
	v_fma_f32 v145, s30, v141, v145
	v_readlane_b32 s98, v142, 32
	v_fma_f32 v147, s31, v141, v147
	v_readlane_b32 s99, v142, 33
	v_fma_f32 v149, s42, v141, v149
	v_readlane_b32 s100, v142, 34
	v_fma_f32 v151, s43, v141, v151
	v_readlane_b32 s101, v142, 35
	v_fma_f32 v145, s98, v143, v145
	v_readlane_b32 s30, v144, 33
	v_fma_f32 v147, s99, v143, v147
	v_readlane_b32 s31, v144, 34
	v_fma_f32 v149, s100, v143, v149
	v_readlane_b32 s42, v144, 35
	v_fma_f32 v151, s101, v143, v151
	v_readlane_b32 s43, v146, 34
	v_fma_f32 v147, s30, v145, v147
	v_readlane_b32 s98, v146, 35
	v_fma_f32 v149, s31, v145, v149
	v_readlane_b32 s99, v148, 35
	v_fma_f32 v151, s42, v145, v151
	v_readlane_b32 s100, v20, 36
	v_fma_f32 v149, s43, v147, v149
	v_readlane_b32 s101, v20, 37
	v_fma_f32 v151, s98, v147, v151
	v_readlane_b32 s30, v20, 38
	v_fma_f32 v151, s99, v149, v151
	v_readlane_b32 s31, v20, 39
	v_fma_f32 v153, s100, v21, v153
	v_readlane_b32 s42, v22, 36
	v_fma_f32 v155, s101, v21, v155
	v_readlane_b32 s43, v22, 37
	v_fma_f32 v157, s30, v21, v157
	v_readlane_b32 s98, v22, 38
	v_fma_f32 v159, s31, v21, v159
	v_readlane_b32 s99, v22, 39
	v_fma_f32 v153, s42, v23, v153
	v_readlane_b32 s100, v24, 36
	v_fma_f32 v155, s43, v23, v155
	v_readlane_b32 s101, v24, 37
	v_fma_f32 v157, s98, v23, v157
	v_readlane_b32 s30, v24, 38
	v_fma_f32 v159, s99, v23, v159
	v_readlane_b32 s31, v24, 39
	v_fma_f32 v153, s100, v25, v153
	v_readlane_b32 s42, v26, 36
	v_fma_f32 v155, s101, v25, v155
	v_readlane_b32 s43, v26, 37
	v_fma_f32 v157, s30, v25, v157
	v_readlane_b32 s98, v26, 38
	v_fma_f32 v159, s31, v25, v159
	v_readlane_b32 s99, v26, 39
	v_fma_f32 v153, s42, v27, v153
	v_readlane_b32 s100, v28, 36
	v_fma_f32 v155, s43, v27, v155
	v_readlane_b32 s101, v28, 37
	v_fma_f32 v157, s98, v27, v157
	v_readlane_b32 s30, v28, 38
	v_fma_f32 v159, s99, v27, v159
	v_readlane_b32 s31, v28, 39
	v_fma_f32 v153, s100, v29, v153
	v_readlane_b32 s42, v30, 36
	v_fma_f32 v155, s101, v29, v155
	v_readlane_b32 s43, v30, 37
	v_fma_f32 v157, s30, v29, v157
	v_readlane_b32 s98, v30, 38
	v_fma_f32 v159, s31, v29, v159
	v_readlane_b32 s99, v30, 39
	v_fma_f32 v153, s42, v31, v153
	v_readlane_b32 s100, v32, 36
	v_fma_f32 v155, s43, v31, v155
	v_readlane_b32 s101, v32, 37
	v_fma_f32 v157, s98, v31, v157
	v_readlane_b32 s30, v32, 38
	v_fma_f32 v159, s99, v31, v159
	v_readlane_b32 s31, v32, 39
	v_fma_f32 v153, s100, v33, v153
	v_readlane_b32 s42, v34, 36
	v_fma_f32 v155, s101, v33, v155
	v_readlane_b32 s43, v34, 37
	v_fma_f32 v157, s30, v33, v157
	v_readlane_b32 s98, v34, 38
	v_fma_f32 v159, s31, v33, v159
	v_readlane_b32 s99, v34, 39
	v_fma_f32 v153, s42, v35, v153
	v_readlane_b32 s100, v36, 36
	v_fma_f32 v155, s43, v35, v155
	v_readlane_b32 s101, v36, 37
	v_fma_f32 v157, s98, v35, v157
	v_readlane_b32 s30, v36, 38
	v_fma_f32 v159, s99, v35, v159
	v_readlane_b32 s31, v36, 39
	v_fma_f32 v153, s100, v37, v153
	v_readlane_b32 s42, v38, 36
	v_fma_f32 v155, s101, v37, v155
	v_readlane_b32 s43, v38, 37
	v_fma_f32 v157, s30, v37, v157
	v_readlane_b32 s98, v38, 38
	v_fma_f32 v159, s31, v37, v159
	v_readlane_b32 s99, v38, 39
	v_fma_f32 v153, s42, v39, v153
	v_readlane_b32 s100, v40, 36
	v_fma_f32 v155, s43, v39, v155
	v_readlane_b32 s101, v40, 37
	v_fma_f32 v157, s98, v39, v157
	v_readlane_b32 s30, v40, 38
	v_fma_f32 v159, s99, v39, v159
	v_readlane_b32 s31, v40, 39
	v_fma_f32 v153, s100, v41, v153
	v_readlane_b32 s42, v42, 36
	v_fma_f32 v155, s101, v41, v155
	v_readlane_b32 s43, v42, 37
	v_fma_f32 v157, s30, v41, v157
	v_readlane_b32 s98, v42, 38
	v_fma_f32 v159, s31, v41, v159
	v_readlane_b32 s99, v42, 39
	v_fma_f32 v153, s42, v43, v153
	v_readlane_b32 s100, v44, 36
	v_fma_f32 v155, s43, v43, v155
	v_readlane_b32 s101, v44, 37
	v_fma_f32 v157, s98, v43, v157
	v_readlane_b32 s30, v44, 38
	v_fma_f32 v159, s99, v43, v159
	v_readlane_b32 s31, v44, 39
	v_fma_f32 v153, s100, v45, v153
	v_readlane_b32 s42, v46, 36
	v_fma_f32 v155, s101, v45, v155
	v_readlane_b32 s43, v46, 37
	v_fma_f32 v157, s30, v45, v157
	v_readlane_b32 s98, v46, 38
	v_fma_f32 v159, s31, v45, v159
	v_readlane_b32 s99, v46, 39
	v_fma_f32 v153, s42, v47, v153
	v_readlane_b32 s100, v48, 36
	v_fma_f32 v155, s43, v47, v155
	v_readlane_b32 s101, v48, 37
	v_fma_f32 v157, s98, v47, v157
	v_readlane_b32 s30, v48, 38
	v_fma_f32 v159, s99, v47, v159
	v_readlane_b32 s31, v48, 39
	v_fma_f32 v153, s100, v49, v153
	v_readlane_b32 s42, v50, 36
	v_fma_f32 v155, s101, v49, v155
	v_readlane_b32 s43, v50, 37
	v_fma_f32 v157, s30, v49, v157
	v_readlane_b32 s98, v50, 38
	v_fma_f32 v159, s31, v49, v159
	v_readlane_b32 s99, v50, 39
	v_fma_f32 v153, s42, v51, v153
	v_readlane_b32 s100, v52, 36
	v_fma_f32 v155, s43, v51, v155
	v_readlane_b32 s101, v52, 37
	v_fma_f32 v157, s98, v51, v157
	v_readlane_b32 s30, v52, 38
	v_fma_f32 v159, s99, v51, v159
	v_readlane_b32 s31, v52, 39
	v_fma_f32 v153, s100, v53, v153
	v_readlane_b32 s42, v54, 36
	v_fma_f32 v155, s101, v53, v155
	v_readlane_b32 s43, v54, 37
	v_fma_f32 v157, s30, v53, v157
	v_readlane_b32 s98, v54, 38
	v_fma_f32 v159, s31, v53, v159
	v_readlane_b32 s99, v54, 39
	v_fma_f32 v153, s42, v55, v153
	v_readlane_b32 s100, v56, 36
	v_fma_f32 v155, s43, v55, v155
	v_readlane_b32 s101, v56, 37
	v_fma_f32 v157, s98, v55, v157
	v_readlane_b32 s30, v56, 38
	v_fma_f32 v159, s99, v55, v159
	v_readlane_b32 s31, v56, 39
	v_fma_f32 v153, s100, v57, v153
	v_readlane_b32 s42, v118, 36
	v_fma_f32 v155, s101, v57, v155
	v_readlane_b32 s43, v118, 37
	v_fma_f32 v157, s30, v57, v157
	v_readlane_b32 s98, v118, 38
	v_fma_f32 v159, s31, v57, v159
	v_readlane_b32 s99, v118, 39
	v_fma_f32 v153, s42, v119, v153
	v_readlane_b32 s100, v120, 36
	v_fma_f32 v155, s43, v119, v155
	v_readlane_b32 s101, v120, 37
	v_fma_f32 v157, s98, v119, v157
	v_readlane_b32 s30, v120, 38
	v_fma_f32 v159, s99, v119, v159
	v_readlane_b32 s31, v120, 39
	v_fma_f32 v153, s100, v121, v153
	v_readlane_b32 s42, v122, 36
	v_fma_f32 v155, s101, v121, v155
	v_readlane_b32 s43, v122, 37
	v_fma_f32 v157, s30, v121, v157
	v_readlane_b32 s98, v122, 38
	v_fma_f32 v159, s31, v121, v159
	v_readlane_b32 s99, v122, 39
	v_fma_f32 v153, s42, v123, v153
	v_readlane_b32 s100, v124, 36
	v_fma_f32 v155, s43, v123, v155
	v_readlane_b32 s101, v124, 37
	v_fma_f32 v157, s98, v123, v157
	v_readlane_b32 s30, v124, 38
	v_fma_f32 v159, s99, v123, v159
	v_readlane_b32 s31, v124, 39
	v_fma_f32 v153, s100, v125, v153
	v_readlane_b32 s42, v126, 36
	v_fma_f32 v155, s101, v125, v155
	v_readlane_b32 s43, v126, 37
	v_fma_f32 v157, s30, v125, v157
	v_readlane_b32 s98, v126, 38
	v_fma_f32 v159, s31, v125, v159
	v_readlane_b32 s99, v126, 39
	v_fma_f32 v153, s42, v127, v153
	v_readlane_b32 s100, v128, 36
	v_fma_f32 v155, s43, v127, v155
	v_readlane_b32 s101, v128, 37
	v_fma_f32 v157, s98, v127, v157
	v_readlane_b32 s30, v128, 38
	v_fma_f32 v159, s99, v127, v159
	v_readlane_b32 s31, v128, 39
	v_fma_f32 v153, s100, v129, v153
	v_readlane_b32 s42, v130, 36
	v_fma_f32 v155, s101, v129, v155
	v_readlane_b32 s43, v130, 37
	v_fma_f32 v157, s30, v129, v157
	v_readlane_b32 s98, v130, 38
	v_fma_f32 v159, s31, v129, v159
	v_readlane_b32 s99, v130, 39
	v_fma_f32 v153, s42, v131, v153
	v_readlane_b32 s100, v132, 36
	v_fma_f32 v155, s43, v131, v155
	v_readlane_b32 s101, v132, 37
	v_fma_f32 v157, s98, v131, v157
	v_readlane_b32 s30, v132, 38
	v_fma_f32 v159, s99, v131, v159
	v_readlane_b32 s31, v132, 39
	v_fma_f32 v153, s100, v133, v153
	v_readlane_b32 s42, v134, 36
	v_fma_f32 v155, s101, v133, v155
	v_readlane_b32 s43, v134, 37
	v_fma_f32 v157, s30, v133, v157
	v_readlane_b32 s98, v134, 38
	v_fma_f32 v159, s31, v133, v159
	v_readlane_b32 s99, v134, 39
	v_fma_f32 v153, s42, v135, v153
	v_readlane_b32 s100, v136, 36
	v_fma_f32 v155, s43, v135, v155
	v_readlane_b32 s101, v136, 37
	v_fma_f32 v157, s98, v135, v157
	v_readlane_b32 s30, v136, 38
	v_fma_f32 v159, s99, v135, v159
	v_readlane_b32 s31, v136, 39
	v_fma_f32 v153, s100, v137, v153
	v_readlane_b32 s42, v138, 36
	v_fma_f32 v155, s101, v137, v155
	v_readlane_b32 s43, v138, 37
	v_fma_f32 v157, s30, v137, v157
	v_readlane_b32 s98, v138, 38
	v_fma_f32 v159, s31, v137, v159
	v_readlane_b32 s99, v138, 39
	v_fma_f32 v153, s42, v139, v153
	v_readlane_b32 s100, v140, 36
	v_fma_f32 v155, s43, v139, v155
	v_readlane_b32 s101, v140, 37
	v_fma_f32 v157, s98, v139, v157
	v_readlane_b32 s30, v140, 38
	v_fma_f32 v159, s99, v139, v159
	v_readlane_b32 s31, v140, 39
	v_fma_f32 v153, s100, v141, v153
	v_readlane_b32 s42, v142, 36
	v_fma_f32 v155, s101, v141, v155
	v_readlane_b32 s43, v142, 37
	v_fma_f32 v157, s30, v141, v157
	v_readlane_b32 s98, v142, 38
	v_fma_f32 v159, s31, v141, v159
	v_readlane_b32 s99, v142, 39
	v_fma_f32 v153, s42, v143, v153
	v_readlane_b32 s100, v144, 36
	v_fma_f32 v155, s43, v143, v155
	v_readlane_b32 s101, v144, 37
	v_fma_f32 v157, s98, v143, v157
	v_readlane_b32 s30, v144, 38
	v_fma_f32 v159, s99, v143, v159
	v_readlane_b32 s31, v144, 39
	v_fma_f32 v153, s100, v145, v153
	v_readlane_b32 s42, v146, 36
	v_fma_f32 v155, s101, v145, v155
	v_readlane_b32 s43, v146, 37
	v_fma_f32 v157, s30, v145, v157
	v_readlane_b32 s98, v146, 38
	v_fma_f32 v159, s31, v145, v159
	v_readlane_b32 s99, v146, 39
	v_fma_f32 v153, s42, v147, v153
	v_readlane_b32 s100, v148, 36
	v_fma_f32 v155, s43, v147, v155
	v_readlane_b32 s101, v148, 37
	v_fma_f32 v157, s98, v147, v157
	v_readlane_b32 s30, v148, 38
	v_fma_f32 v159, s99, v147, v159
	v_readlane_b32 s31, v148, 39
	v_fma_f32 v153, s100, v149, v153
	v_readlane_b32 s42, v150, 36
	v_fma_f32 v155, s101, v149, v155
	v_readlane_b32 s43, v150, 37
	v_fma_f32 v157, s30, v149, v157
	v_readlane_b32 s98, v150, 38
	v_fma_f32 v159, s31, v149, v159
	v_readlane_b32 s99, v150, 39
	v_fma_f32 v153, s42, v151, v153
	v_readlane_b32 s100, v152, 37
	v_fma_f32 v155, s43, v151, v155
	v_readlane_b32 s101, v152, 38
	v_fma_f32 v157, s98, v151, v157
	v_readlane_b32 s30, v152, 39
	v_fma_f32 v159, s99, v151, v159
	v_readlane_b32 s31, v154, 38
	v_fma_f32 v155, s100, v153, v155
	v_readlane_b32 s42, v154, 39
	v_fma_f32 v157, s101, v153, v157
	v_readlane_b32 s43, v156, 39
	v_fma_f32 v159, s30, v153, v159
	v_readlane_b32 s98, v20, 40
	v_fma_f32 v157, s31, v155, v157
	v_readlane_b32 s99, v20, 41
	v_fma_f32 v159, s42, v155, v159
	v_readlane_b32 s100, v20, 42
	v_fma_f32 v159, s43, v157, v159
	v_readlane_b32 s101, v20, 43
	v_fma_f32 v161, s98, v21, v161
	v_readlane_b32 s30, v22, 40
	v_fma_f32 v163, s99, v21, v163
	v_readlane_b32 s31, v22, 41
	v_fma_f32 v165, s100, v21, v165
	v_readlane_b32 s42, v22, 42
	v_fma_f32 v167, s101, v21, v167
	v_readlane_b32 s43, v22, 43
	v_fma_f32 v161, s30, v23, v161
	v_readlane_b32 s98, v24, 40
	v_fma_f32 v163, s31, v23, v163
	v_readlane_b32 s99, v24, 41
	v_fma_f32 v165, s42, v23, v165
	v_readlane_b32 s100, v24, 42
	v_fma_f32 v167, s43, v23, v167
	v_readlane_b32 s101, v24, 43
	v_fma_f32 v161, s98, v25, v161
	v_readlane_b32 s30, v26, 40
	v_fma_f32 v163, s99, v25, v163
	v_readlane_b32 s31, v26, 41
	v_fma_f32 v165, s100, v25, v165
	v_readlane_b32 s42, v26, 42
	v_fma_f32 v167, s101, v25, v167
	v_readlane_b32 s43, v26, 43
	v_fma_f32 v161, s30, v27, v161
	v_readlane_b32 s98, v28, 40
	v_fma_f32 v163, s31, v27, v163
	v_readlane_b32 s99, v28, 41
	v_fma_f32 v165, s42, v27, v165
	v_readlane_b32 s100, v28, 42
	v_fma_f32 v167, s43, v27, v167
	v_readlane_b32 s101, v28, 43
	v_fma_f32 v161, s98, v29, v161
	v_readlane_b32 s30, v30, 40
	v_fma_f32 v163, s99, v29, v163
	v_readlane_b32 s31, v30, 41
	v_fma_f32 v165, s100, v29, v165
	v_readlane_b32 s42, v30, 42
	v_fma_f32 v167, s101, v29, v167
	v_readlane_b32 s43, v30, 43
	v_fma_f32 v161, s30, v31, v161
	v_readlane_b32 s98, v32, 40
	v_fma_f32 v163, s31, v31, v163
	v_readlane_b32 s99, v32, 41
	v_fma_f32 v165, s42, v31, v165
	v_readlane_b32 s100, v32, 42
	v_fma_f32 v167, s43, v31, v167
	v_readlane_b32 s101, v32, 43
	v_fma_f32 v161, s98, v33, v161
	v_readlane_b32 s30, v34, 40
	v_fma_f32 v163, s99, v33, v163
	v_readlane_b32 s31, v34, 41
	v_fma_f32 v165, s100, v33, v165
	v_readlane_b32 s42, v34, 42
	v_fma_f32 v167, s101, v33, v167
	v_readlane_b32 s43, v34, 43
	v_fma_f32 v161, s30, v35, v161
	v_readlane_b32 s98, v36, 40
	v_fma_f32 v163, s31, v35, v163
	v_readlane_b32 s99, v36, 41
	v_fma_f32 v165, s42, v35, v165
	v_readlane_b32 s100, v36, 42
	v_fma_f32 v167, s43, v35, v167
	v_readlane_b32 s101, v36, 43
	v_fma_f32 v161, s98, v37, v161
	v_readlane_b32 s30, v38, 40
	v_fma_f32 v163, s99, v37, v163
	v_readlane_b32 s31, v38, 41
	v_fma_f32 v165, s100, v37, v165
	v_readlane_b32 s42, v38, 42
	v_fma_f32 v167, s101, v37, v167
	v_readlane_b32 s43, v38, 43
	v_fma_f32 v161, s30, v39, v161
	v_readlane_b32 s98, v40, 40
	v_fma_f32 v163, s31, v39, v163
	v_readlane_b32 s99, v40, 41
	v_fma_f32 v165, s42, v39, v165
	v_readlane_b32 s100, v40, 42
	v_fma_f32 v167, s43, v39, v167
	v_readlane_b32 s101, v40, 43
	v_fma_f32 v161, s98, v41, v161
	v_readlane_b32 s30, v42, 40
	v_fma_f32 v163, s99, v41, v163
	v_readlane_b32 s31, v42, 41
	v_fma_f32 v165, s100, v41, v165
	v_readlane_b32 s42, v42, 42
	v_fma_f32 v167, s101, v41, v167
	v_readlane_b32 s43, v42, 43
	v_fma_f32 v161, s30, v43, v161
	v_readlane_b32 s98, v44, 40
	v_fma_f32 v163, s31, v43, v163
	v_readlane_b32 s99, v44, 41
	v_fma_f32 v165, s42, v43, v165
	v_readlane_b32 s100, v44, 42
	v_fma_f32 v167, s43, v43, v167
	v_readlane_b32 s101, v44, 43
	v_fma_f32 v161, s98, v45, v161
	v_readlane_b32 s30, v46, 40
	v_fma_f32 v163, s99, v45, v163
	v_readlane_b32 s31, v46, 41
	v_fma_f32 v165, s100, v45, v165
	v_readlane_b32 s42, v46, 42
	v_fma_f32 v167, s101, v45, v167
	v_readlane_b32 s43, v46, 43
	v_fma_f32 v161, s30, v47, v161
	v_readlane_b32 s98, v48, 40
	v_fma_f32 v163, s31, v47, v163
	v_readlane_b32 s99, v48, 41
	v_fma_f32 v165, s42, v47, v165
	v_readlane_b32 s100, v48, 42
	v_fma_f32 v167, s43, v47, v167
	v_readlane_b32 s101, v48, 43
	v_fma_f32 v161, s98, v49, v161
	v_readlane_b32 s30, v50, 40
	v_fma_f32 v163, s99, v49, v163
	v_readlane_b32 s31, v50, 41
	v_fma_f32 v165, s100, v49, v165
	v_readlane_b32 s42, v50, 42
	v_fma_f32 v167, s101, v49, v167
	v_readlane_b32 s43, v50, 43
	v_fma_f32 v161, s30, v51, v161
	v_readlane_b32 s98, v52, 40
	v_fma_f32 v163, s31, v51, v163
	v_readlane_b32 s99, v52, 41
	v_fma_f32 v165, s42, v51, v165
	v_readlane_b32 s100, v52, 42
	v_fma_f32 v167, s43, v51, v167
	v_readlane_b32 s101, v52, 43
	v_fma_f32 v161, s98, v53, v161
	v_readlane_b32 s30, v54, 40
	v_fma_f32 v163, s99, v53, v163
	v_readlane_b32 s31, v54, 41
	v_fma_f32 v165, s100, v53, v165
	v_readlane_b32 s42, v54, 42
	v_fma_f32 v167, s101, v53, v167
	v_readlane_b32 s43, v54, 43
	v_fma_f32 v161, s30, v55, v161
	v_readlane_b32 s98, v56, 40
	v_fma_f32 v163, s31, v55, v163
	v_readlane_b32 s99, v56, 41
	v_fma_f32 v165, s42, v55, v165
	v_readlane_b32 s100, v56, 42
	v_fma_f32 v167, s43, v55, v167
	v_readlane_b32 s101, v56, 43
	v_fma_f32 v161, s98, v57, v161
	v_readlane_b32 s30, v118, 40
	v_fma_f32 v163, s99, v57, v163
	v_readlane_b32 s31, v118, 41
	v_fma_f32 v165, s100, v57, v165
	v_readlane_b32 s42, v118, 42
	v_fma_f32 v167, s101, v57, v167
	v_readlane_b32 s43, v118, 43
	v_fma_f32 v161, s30, v119, v161
	v_readlane_b32 s98, v120, 40
	v_fma_f32 v163, s31, v119, v163
	v_readlane_b32 s99, v120, 41
	v_fma_f32 v165, s42, v119, v165
	v_readlane_b32 s100, v120, 42
	v_fma_f32 v167, s43, v119, v167
	v_readlane_b32 s101, v120, 43
	v_fma_f32 v161, s98, v121, v161
	v_readlane_b32 s30, v122, 40
	v_fma_f32 v163, s99, v121, v163
	v_readlane_b32 s31, v122, 41
	v_fma_f32 v165, s100, v121, v165
	v_readlane_b32 s42, v122, 42
	v_fma_f32 v167, s101, v121, v167
	v_readlane_b32 s43, v122, 43
	v_fma_f32 v161, s30, v123, v161
	v_readlane_b32 s98, v124, 40
	v_fma_f32 v163, s31, v123, v163
	v_readlane_b32 s99, v124, 41
	v_fma_f32 v165, s42, v123, v165
	v_readlane_b32 s100, v124, 42
	v_fma_f32 v167, s43, v123, v167
	v_readlane_b32 s101, v124, 43
	v_fma_f32 v161, s98, v125, v161
	v_readlane_b32 s30, v126, 40
	v_fma_f32 v163, s99, v125, v163
	v_readlane_b32 s31, v126, 41
	v_fma_f32 v165, s100, v125, v165
	v_readlane_b32 s42, v126, 42
	v_fma_f32 v167, s101, v125, v167
	v_readlane_b32 s43, v126, 43
	v_fma_f32 v161, s30, v127, v161
	v_readlane_b32 s98, v128, 40
	v_fma_f32 v163, s31, v127, v163
	v_readlane_b32 s99, v128, 41
	v_fma_f32 v165, s42, v127, v165
	v_readlane_b32 s100, v128, 42
	v_fma_f32 v167, s43, v127, v167
	v_readlane_b32 s101, v128, 43
	v_fma_f32 v161, s98, v129, v161
	v_readlane_b32 s30, v130, 40
	v_fma_f32 v163, s99, v129, v163
	v_readlane_b32 s31, v130, 41
	v_fma_f32 v165, s100, v129, v165
	v_readlane_b32 s42, v130, 42
	v_fma_f32 v167, s101, v129, v167
	v_readlane_b32 s43, v130, 43
	v_fma_f32 v161, s30, v131, v161
	v_readlane_b32 s98, v132, 40
	v_fma_f32 v163, s31, v131, v163
	v_readlane_b32 s99, v132, 41
	v_fma_f32 v165, s42, v131, v165
	v_readlane_b32 s100, v132, 42
	v_fma_f32 v167, s43, v131, v167
	v_readlane_b32 s101, v132, 43
	v_fma_f32 v161, s98, v133, v161
	v_readlane_b32 s30, v134, 40
	v_fma_f32 v163, s99, v133, v163
	v_readlane_b32 s31, v134, 41
	v_fma_f32 v165, s100, v133, v165
	v_readlane_b32 s42, v134, 42
	v_fma_f32 v167, s101, v133, v167
	v_readlane_b32 s43, v134, 43
	v_fma_f32 v161, s30, v135, v161
	v_readlane_b32 s98, v136, 40
	v_fma_f32 v163, s31, v135, v163
	v_readlane_b32 s99, v136, 41
	v_fma_f32 v165, s42, v135, v165
	v_readlane_b32 s100, v136, 42
	v_fma_f32 v167, s43, v135, v167
	v_readlane_b32 s101, v136, 43
	v_fma_f32 v161, s98, v137, v161
	v_readlane_b32 s30, v138, 40
	v_fma_f32 v163, s99, v137, v163
	v_readlane_b32 s31, v138, 41
	v_fma_f32 v165, s100, v137, v165
	v_readlane_b32 s42, v138, 42
	v_fma_f32 v167, s101, v137, v167
	v_readlane_b32 s43, v138, 43
	v_fma_f32 v161, s30, v139, v161
	v_readlane_b32 s98, v140, 40
	v_fma_f32 v163, s31, v139, v163
	v_readlane_b32 s99, v140, 41
	v_fma_f32 v165, s42, v139, v165
	v_readlane_b32 s100, v140, 42
	v_fma_f32 v167, s43, v139, v167
	v_readlane_b32 s101, v140, 43
	v_fma_f32 v161, s98, v141, v161
	v_readlane_b32 s30, v142, 40
	v_fma_f32 v163, s99, v141, v163
	v_readlane_b32 s31, v142, 41
	v_fma_f32 v165, s100, v141, v165
	v_readlane_b32 s42, v142, 42
	v_fma_f32 v167, s101, v141, v167
	v_readlane_b32 s43, v142, 43
	v_fma_f32 v161, s30, v143, v161
	v_readlane_b32 s98, v144, 40
	v_fma_f32 v163, s31, v143, v163
	v_readlane_b32 s99, v144, 41
	v_fma_f32 v165, s42, v143, v165
	v_readlane_b32 s100, v144, 42
	v_fma_f32 v167, s43, v143, v167
	v_readlane_b32 s101, v144, 43
	v_fma_f32 v161, s98, v145, v161
	v_readlane_b32 s30, v146, 40
	v_fma_f32 v163, s99, v145, v163
	v_readlane_b32 s31, v146, 41
	v_fma_f32 v165, s100, v145, v165
	v_readlane_b32 s42, v146, 42
	v_fma_f32 v167, s101, v145, v167
	v_readlane_b32 s43, v146, 43
	v_fma_f32 v161, s30, v147, v161
	v_readlane_b32 s98, v148, 40
	v_fma_f32 v163, s31, v147, v163
	v_readlane_b32 s99, v148, 41
	v_fma_f32 v165, s42, v147, v165
	v_readlane_b32 s100, v148, 42
	v_fma_f32 v167, s43, v147, v167
	v_readlane_b32 s101, v148, 43
	v_fma_f32 v161, s98, v149, v161
	v_readlane_b32 s30, v150, 40
	v_fma_f32 v163, s99, v149, v163
	v_readlane_b32 s31, v150, 41
	v_fma_f32 v165, s100, v149, v165
	v_readlane_b32 s42, v150, 42
	v_fma_f32 v167, s101, v149, v167
	v_readlane_b32 s43, v150, 43
	v_fma_f32 v161, s30, v151, v161
	v_readlane_b32 s98, v152, 40
	v_fma_f32 v163, s31, v151, v163
	v_readlane_b32 s99, v152, 41
	v_fma_f32 v165, s42, v151, v165
	v_readlane_b32 s100, v152, 42
	v_fma_f32 v167, s43, v151, v167
	v_readlane_b32 s101, v152, 43
	v_fma_f32 v161, s98, v153, v161
	v_readlane_b32 s30, v154, 40
	v_fma_f32 v163, s99, v153, v163
	v_readlane_b32 s31, v154, 41
	v_fma_f32 v165, s100, v153, v165
	v_readlane_b32 s42, v154, 42
	v_fma_f32 v167, s101, v153, v167
	v_readlane_b32 s43, v154, 43
	v_fma_f32 v161, s30, v155, v161
	v_readlane_b32 s98, v156, 40
	v_fma_f32 v163, s31, v155, v163
	v_readlane_b32 s99, v156, 41
	v_fma_f32 v165, s42, v155, v165
	v_readlane_b32 s100, v156, 42
	v_fma_f32 v167, s43, v155, v167
	v_readlane_b32 s101, v156, 43
	v_fma_f32 v161, s98, v157, v161
	v_readlane_b32 s30, v158, 40
	v_fma_f32 v163, s99, v157, v163
	v_readlane_b32 s31, v158, 41
	v_fma_f32 v165, s100, v157, v165
	v_readlane_b32 s42, v158, 42
	v_fma_f32 v167, s101, v157, v167
	v_readlane_b32 s43, v158, 43
	v_fma_f32 v161, s30, v159, v161
	v_readlane_b32 s98, v160, 41
	v_fma_f32 v163, s31, v159, v163
	v_readlane_b32 s99, v160, 42
	v_fma_f32 v165, s42, v159, v165
	v_readlane_b32 s100, v160, 43
	v_fma_f32 v167, s43, v159, v167
	v_readlane_b32 s101, v162, 42
	v_fma_f32 v163, s98, v161, v163
	v_readlane_b32 s30, v162, 43
	v_fma_f32 v165, s99, v161, v165
	v_readlane_b32 s31, v164, 43
	v_fma_f32 v167, s100, v161, v167
	v_readlane_b32 s42, v20, 44
	v_fma_f32 v165, s101, v163, v165
	v_readlane_b32 s43, v20, 45
	v_fma_f32 v167, s30, v163, v167
	v_readlane_b32 s98, v20, 46
	v_fma_f32 v167, s31, v165, v167
	v_readlane_b32 s99, v20, 47
	v_fma_f32 v169, s42, v21, v169
	v_readlane_b32 s100, v22, 44
	v_fma_f32 v171, s43, v21, v171
	v_readlane_b32 s101, v22, 45
	v_fma_f32 v173, s98, v21, v173
	v_readlane_b32 s30, v22, 46
	v_fma_f32 v175, s99, v21, v175
	v_readlane_b32 s31, v22, 47
	v_fma_f32 v169, s100, v23, v169
	v_readlane_b32 s42, v24, 44
	v_fma_f32 v171, s101, v23, v171
	v_readlane_b32 s43, v24, 45
	v_fma_f32 v173, s30, v23, v173
	v_readlane_b32 s98, v24, 46
	v_fma_f32 v175, s31, v23, v175
	v_readlane_b32 s99, v24, 47
	v_fma_f32 v169, s42, v25, v169
	v_readlane_b32 s100, v26, 44
	v_fma_f32 v171, s43, v25, v171
	v_readlane_b32 s101, v26, 45
	v_fma_f32 v173, s98, v25, v173
	v_readlane_b32 s30, v26, 46
	v_fma_f32 v175, s99, v25, v175
	v_readlane_b32 s31, v26, 47
	v_fma_f32 v169, s100, v27, v169
	v_readlane_b32 s42, v28, 44
	v_fma_f32 v171, s101, v27, v171
	v_readlane_b32 s43, v28, 45
	v_fma_f32 v173, s30, v27, v173
	v_readlane_b32 s98, v28, 46
	v_fma_f32 v175, s31, v27, v175
	v_readlane_b32 s99, v28, 47
	v_fma_f32 v169, s42, v29, v169
	v_readlane_b32 s100, v30, 44
	v_fma_f32 v171, s43, v29, v171
	v_readlane_b32 s101, v30, 45
	v_fma_f32 v173, s98, v29, v173
	v_readlane_b32 s30, v30, 46
	v_fma_f32 v175, s99, v29, v175
	v_readlane_b32 s31, v30, 47
	v_fma_f32 v169, s100, v31, v169
	v_readlane_b32 s42, v32, 44
	v_fma_f32 v171, s101, v31, v171
	v_readlane_b32 s43, v32, 45
	v_fma_f32 v173, s30, v31, v173
	v_readlane_b32 s98, v32, 46
	v_fma_f32 v175, s31, v31, v175
	v_readlane_b32 s99, v32, 47
	v_fma_f32 v169, s42, v33, v169
	v_readlane_b32 s100, v34, 44
	v_fma_f32 v171, s43, v33, v171
	v_readlane_b32 s101, v34, 45
	v_fma_f32 v173, s98, v33, v173
	v_readlane_b32 s30, v34, 46
	v_fma_f32 v175, s99, v33, v175
	v_readlane_b32 s31, v34, 47
	v_fma_f32 v169, s100, v35, v169
	v_readlane_b32 s42, v36, 44
	v_fma_f32 v171, s101, v35, v171
	v_readlane_b32 s43, v36, 45
	v_fma_f32 v173, s30, v35, v173
	v_readlane_b32 s98, v36, 46
	v_fma_f32 v175, s31, v35, v175
	v_readlane_b32 s99, v36, 47
	v_fma_f32 v169, s42, v37, v169
	v_readlane_b32 s100, v38, 44
	v_fma_f32 v171, s43, v37, v171
	v_readlane_b32 s101, v38, 45
	v_fma_f32 v173, s98, v37, v173
	v_readlane_b32 s30, v38, 46
	v_fma_f32 v175, s99, v37, v175
	v_readlane_b32 s31, v38, 47
	v_fma_f32 v169, s100, v39, v169
	v_readlane_b32 s42, v40, 44
	v_fma_f32 v171, s101, v39, v171
	v_readlane_b32 s43, v40, 45
	v_fma_f32 v173, s30, v39, v173
	v_readlane_b32 s98, v40, 46
	v_fma_f32 v175, s31, v39, v175
	v_readlane_b32 s99, v40, 47
	v_fma_f32 v169, s42, v41, v169
	v_readlane_b32 s100, v42, 44
	v_fma_f32 v171, s43, v41, v171
	v_readlane_b32 s101, v42, 45
	v_fma_f32 v173, s98, v41, v173
	v_readlane_b32 s30, v42, 46
	v_fma_f32 v175, s99, v41, v175
	v_readlane_b32 s31, v42, 47
	v_fma_f32 v169, s100, v43, v169
	v_readlane_b32 s42, v44, 44
	v_fma_f32 v171, s101, v43, v171
	v_readlane_b32 s43, v44, 45
	v_fma_f32 v173, s30, v43, v173
	v_readlane_b32 s98, v44, 46
	v_fma_f32 v175, s31, v43, v175
	v_readlane_b32 s99, v44, 47
	v_fma_f32 v169, s42, v45, v169
	v_readlane_b32 s100, v46, 44
	v_fma_f32 v171, s43, v45, v171
	v_readlane_b32 s101, v46, 45
	v_fma_f32 v173, s98, v45, v173
	v_readlane_b32 s30, v46, 46
	v_fma_f32 v175, s99, v45, v175
	v_readlane_b32 s31, v46, 47
	v_fma_f32 v169, s100, v47, v169
	v_readlane_b32 s42, v48, 44
	v_fma_f32 v171, s101, v47, v171
	v_readlane_b32 s43, v48, 45
	v_fma_f32 v173, s30, v47, v173
	v_readlane_b32 s98, v48, 46
	v_fma_f32 v175, s31, v47, v175
	v_readlane_b32 s99, v48, 47
	v_fma_f32 v169, s42, v49, v169
	v_readlane_b32 s100, v50, 44
	v_fma_f32 v171, s43, v49, v171
	v_readlane_b32 s101, v50, 45
	v_fma_f32 v173, s98, v49, v173
	v_readlane_b32 s30, v50, 46
	v_fma_f32 v175, s99, v49, v175
	v_readlane_b32 s31, v50, 47
	v_fma_f32 v169, s100, v51, v169
	v_readlane_b32 s42, v52, 44
	v_fma_f32 v171, s101, v51, v171
	v_readlane_b32 s43, v52, 45
	v_fma_f32 v173, s30, v51, v173
	v_readlane_b32 s98, v52, 46
	v_fma_f32 v175, s31, v51, v175
	v_readlane_b32 s99, v52, 47
	v_fma_f32 v169, s42, v53, v169
	v_readlane_b32 s100, v54, 44
	v_fma_f32 v171, s43, v53, v171
	v_readlane_b32 s101, v54, 45
	v_fma_f32 v173, s98, v53, v173
	v_readlane_b32 s30, v54, 46
	v_fma_f32 v175, s99, v53, v175
	v_readlane_b32 s31, v54, 47
	v_fma_f32 v169, s100, v55, v169
	v_readlane_b32 s42, v56, 44
	v_fma_f32 v171, s101, v55, v171
	v_readlane_b32 s43, v56, 45
	v_fma_f32 v173, s30, v55, v173
	v_readlane_b32 s98, v56, 46
	v_fma_f32 v175, s31, v55, v175
	v_readlane_b32 s99, v56, 47
	v_fma_f32 v169, s42, v57, v169
	v_readlane_b32 s100, v118, 44
	v_fma_f32 v171, s43, v57, v171
	v_readlane_b32 s101, v118, 45
	v_fma_f32 v173, s98, v57, v173
	v_readlane_b32 s30, v118, 46
	v_fma_f32 v175, s99, v57, v175
	v_readlane_b32 s31, v118, 47
	v_fma_f32 v169, s100, v119, v169
	v_readlane_b32 s42, v120, 44
	v_fma_f32 v171, s101, v119, v171
	v_readlane_b32 s43, v120, 45
	v_fma_f32 v173, s30, v119, v173
	v_readlane_b32 s98, v120, 46
	v_fma_f32 v175, s31, v119, v175
	v_readlane_b32 s99, v120, 47
	v_fma_f32 v169, s42, v121, v169
	v_readlane_b32 s100, v122, 44
	v_fma_f32 v171, s43, v121, v171
	v_readlane_b32 s101, v122, 45
	v_fma_f32 v173, s98, v121, v173
	v_readlane_b32 s30, v122, 46
	v_fma_f32 v175, s99, v121, v175
	v_readlane_b32 s31, v122, 47
	v_fma_f32 v169, s100, v123, v169
	v_readlane_b32 s42, v124, 44
	v_fma_f32 v171, s101, v123, v171
	v_readlane_b32 s43, v124, 45
	v_fma_f32 v173, s30, v123, v173
	v_readlane_b32 s98, v124, 46
	v_fma_f32 v175, s31, v123, v175
	v_readlane_b32 s99, v124, 47
	v_fma_f32 v169, s42, v125, v169
	v_readlane_b32 s100, v126, 44
	v_fma_f32 v171, s43, v125, v171
	v_readlane_b32 s101, v126, 45
	v_fma_f32 v173, s98, v125, v173
	v_readlane_b32 s30, v126, 46
	v_fma_f32 v175, s99, v125, v175
	v_readlane_b32 s31, v126, 47
	v_fma_f32 v169, s100, v127, v169
	v_readlane_b32 s42, v128, 44
	v_fma_f32 v171, s101, v127, v171
	v_readlane_b32 s43, v128, 45
	v_fma_f32 v173, s30, v127, v173
	v_readlane_b32 s98, v128, 46
	v_fma_f32 v175, s31, v127, v175
	v_readlane_b32 s99, v128, 47
	v_fma_f32 v169, s42, v129, v169
	v_readlane_b32 s100, v130, 44
	v_fma_f32 v171, s43, v129, v171
	v_readlane_b32 s101, v130, 45
	v_fma_f32 v173, s98, v129, v173
	v_readlane_b32 s30, v130, 46
	v_fma_f32 v175, s99, v129, v175
	v_readlane_b32 s31, v130, 47
	v_fma_f32 v169, s100, v131, v169
	v_readlane_b32 s42, v132, 44
	v_fma_f32 v171, s101, v131, v171
	v_readlane_b32 s43, v132, 45
	v_fma_f32 v173, s30, v131, v173
	v_readlane_b32 s98, v132, 46
	v_fma_f32 v175, s31, v131, v175
	v_readlane_b32 s99, v132, 47
	v_fma_f32 v169, s42, v133, v169
	v_readlane_b32 s100, v134, 44
	v_fma_f32 v171, s43, v133, v171
	v_readlane_b32 s101, v134, 45
	v_fma_f32 v173, s98, v133, v173
	v_readlane_b32 s30, v134, 46
	v_fma_f32 v175, s99, v133, v175
	v_readlane_b32 s31, v134, 47
	v_fma_f32 v169, s100, v135, v169
	v_readlane_b32 s42, v136, 44
	v_fma_f32 v171, s101, v135, v171
	v_readlane_b32 s43, v136, 45
	v_fma_f32 v173, s30, v135, v173
	v_readlane_b32 s98, v136, 46
	v_fma_f32 v175, s31, v135, v175
	v_readlane_b32 s99, v136, 47
	v_fma_f32 v169, s42, v137, v169
	v_readlane_b32 s100, v138, 44
	v_fma_f32 v171, s43, v137, v171
	v_readlane_b32 s101, v138, 45
	v_fma_f32 v173, s98, v137, v173
	v_readlane_b32 s30, v138, 46
	v_fma_f32 v175, s99, v137, v175
	v_readlane_b32 s31, v138, 47
	v_fma_f32 v169, s100, v139, v169
	v_readlane_b32 s42, v140, 44
	v_fma_f32 v171, s101, v139, v171
	v_readlane_b32 s43, v140, 45
	v_fma_f32 v173, s30, v139, v173
	v_readlane_b32 s98, v140, 46
	v_fma_f32 v175, s31, v139, v175
	v_readlane_b32 s99, v140, 47
	v_fma_f32 v169, s42, v141, v169
	v_readlane_b32 s100, v142, 44
	v_fma_f32 v171, s43, v141, v171
	v_readlane_b32 s101, v142, 45
	v_fma_f32 v173, s98, v141, v173
	v_readlane_b32 s30, v142, 46
	v_fma_f32 v175, s99, v141, v175
	v_readlane_b32 s31, v142, 47
	v_fma_f32 v169, s100, v143, v169
	v_readlane_b32 s42, v144, 44
	v_fma_f32 v171, s101, v143, v171
	v_readlane_b32 s43, v144, 45
	v_fma_f32 v173, s30, v143, v173
	v_readlane_b32 s98, v144, 46
	v_fma_f32 v175, s31, v143, v175
	v_readlane_b32 s99, v144, 47
	v_fma_f32 v169, s42, v145, v169
	v_readlane_b32 s100, v146, 44
	v_fma_f32 v171, s43, v145, v171
	v_readlane_b32 s101, v146, 45
	v_fma_f32 v173, s98, v145, v173
	v_readlane_b32 s30, v146, 46
	v_fma_f32 v175, s99, v145, v175
	v_readlane_b32 s31, v146, 47
	v_fma_f32 v169, s100, v147, v169
	v_readlane_b32 s42, v148, 44
	v_fma_f32 v171, s101, v147, v171
	v_readlane_b32 s43, v148, 45
	v_fma_f32 v173, s30, v147, v173
	v_readlane_b32 s98, v148, 46
	v_fma_f32 v175, s31, v147, v175
	v_readlane_b32 s99, v148, 47
	v_fma_f32 v169, s42, v149, v169
	v_readlane_b32 s100, v150, 44
	v_fma_f32 v171, s43, v149, v171
	v_readlane_b32 s101, v150, 45
	v_fma_f32 v173, s98, v149, v173
	v_readlane_b32 s30, v150, 46
	v_fma_f32 v175, s99, v149, v175
	v_readlane_b32 s31, v150, 47
	v_fma_f32 v169, s100, v151, v169
	v_readlane_b32 s42, v152, 44
	v_fma_f32 v171, s101, v151, v171
	v_readlane_b32 s43, v152, 45
	v_fma_f32 v173, s30, v151, v173
	v_readlane_b32 s98, v152, 46
	v_fma_f32 v175, s31, v151, v175
	v_readlane_b32 s99, v152, 47
	v_fma_f32 v169, s42, v153, v169
	v_readlane_b32 s100, v154, 44
	v_fma_f32 v171, s43, v153, v171
	v_readlane_b32 s101, v154, 45
	v_fma_f32 v173, s98, v153, v173
	v_readlane_b32 s30, v154, 46
	v_fma_f32 v175, s99, v153, v175
	v_readlane_b32 s31, v154, 47
	v_fma_f32 v169, s100, v155, v169
	v_readlane_b32 s42, v156, 44
	v_fma_f32 v171, s101, v155, v171
	v_readlane_b32 s43, v156, 45
	v_fma_f32 v173, s30, v155, v173
	v_readlane_b32 s98, v156, 46
	v_fma_f32 v175, s31, v155, v175
	v_readlane_b32 s99, v156, 47
	v_fma_f32 v169, s42, v157, v169
	v_readlane_b32 s100, v158, 44
	v_fma_f32 v171, s43, v157, v171
	v_readlane_b32 s101, v158, 45
	v_fma_f32 v173, s98, v157, v173
	v_readlane_b32 s30, v158, 46
	v_fma_f32 v175, s99, v157, v175
	v_readlane_b32 s31, v158, 47
	v_fma_f32 v169, s100, v159, v169
	v_readlane_b32 s42, v160, 44
	v_fma_f32 v171, s101, v159, v171
	v_readlane_b32 s43, v160, 45
	v_fma_f32 v173, s30, v159, v173
	v_readlane_b32 s98, v160, 46
	v_fma_f32 v175, s31, v159, v175
	v_readlane_b32 s99, v160, 47
	v_fma_f32 v169, s42, v161, v169
	v_readlane_b32 s100, v162, 44
	v_fma_f32 v171, s43, v161, v171
	v_readlane_b32 s101, v162, 45
	v_fma_f32 v173, s98, v161, v173
	v_readlane_b32 s30, v162, 46
	v_fma_f32 v175, s99, v161, v175
	v_readlane_b32 s31, v162, 47
	v_fma_f32 v169, s100, v163, v169
	v_readlane_b32 s42, v164, 44
	v_fma_f32 v171, s101, v163, v171
	v_readlane_b32 s43, v164, 45
	v_fma_f32 v173, s30, v163, v173
	v_readlane_b32 s98, v164, 46
	v_fma_f32 v175, s31, v163, v175
	v_readlane_b32 s99, v164, 47
	v_fma_f32 v169, s42, v165, v169
	v_readlane_b32 s100, v166, 44
	v_fma_f32 v171, s43, v165, v171
	v_readlane_b32 s101, v166, 45
	v_fma_f32 v173, s98, v165, v173
	v_readlane_b32 s30, v166, 46
	v_fma_f32 v175, s99, v165, v175
	v_readlane_b32 s31, v166, 47
	v_fma_f32 v169, s100, v167, v169
	v_readlane_b32 s42, v168, 45
	v_fma_f32 v171, s101, v167, v171
	v_readlane_b32 s43, v168, 46
	v_fma_f32 v173, s30, v167, v173
	v_readlane_b32 s98, v168, 47
	v_fma_f32 v175, s31, v167, v175
	v_readlane_b32 s99, v170, 46
	v_fma_f32 v171, s42, v169, v171
	v_readlane_b32 s100, v170, 47
	v_fma_f32 v173, s43, v169, v173
	v_readlane_b32 s101, v172, 47
	v_fma_f32 v175, s98, v169, v175
	v_readlane_b32 s30, v20, 48
	v_fma_f32 v173, s99, v171, v173
	v_readlane_b32 s31, v20, 49
	v_fma_f32 v175, s100, v171, v175
	v_readlane_b32 s42, v20, 50
	v_fma_f32 v175, s101, v173, v175
	v_readlane_b32 s43, v20, 51
	v_fma_f32 v177, s30, v21, v177
	v_readlane_b32 s98, v22, 48
	v_fma_f32 v179, s31, v21, v179
	v_readlane_b32 s99, v22, 49
	v_fma_f32 v181, s42, v21, v181
	v_readlane_b32 s100, v22, 50
	v_fma_f32 v183, s43, v21, v183
	v_readlane_b32 s101, v22, 51
	v_fma_f32 v177, s98, v23, v177
	v_readlane_b32 s30, v24, 48
	v_fma_f32 v179, s99, v23, v179
	v_readlane_b32 s31, v24, 49
	v_fma_f32 v181, s100, v23, v181
	v_readlane_b32 s42, v24, 50
	v_fma_f32 v183, s101, v23, v183
	v_readlane_b32 s43, v24, 51
	v_fma_f32 v177, s30, v25, v177
	v_readlane_b32 s98, v26, 48
	v_fma_f32 v179, s31, v25, v179
	v_readlane_b32 s99, v26, 49
	v_fma_f32 v181, s42, v25, v181
	v_readlane_b32 s100, v26, 50
	v_fma_f32 v183, s43, v25, v183
	v_readlane_b32 s101, v26, 51
	v_fma_f32 v177, s98, v27, v177
	v_readlane_b32 s30, v28, 48
	v_fma_f32 v179, s99, v27, v179
	v_readlane_b32 s31, v28, 49
	v_fma_f32 v181, s100, v27, v181
	v_readlane_b32 s42, v28, 50
	v_fma_f32 v183, s101, v27, v183
	v_readlane_b32 s43, v28, 51
	v_fma_f32 v177, s30, v29, v177
	v_readlane_b32 s98, v30, 48
	v_fma_f32 v179, s31, v29, v179
	v_readlane_b32 s99, v30, 49
	v_fma_f32 v181, s42, v29, v181
	v_readlane_b32 s100, v30, 50
	v_fma_f32 v183, s43, v29, v183
	v_readlane_b32 s101, v30, 51
	v_fma_f32 v177, s98, v31, v177
	v_readlane_b32 s30, v32, 48
	v_fma_f32 v179, s99, v31, v179
	v_readlane_b32 s31, v32, 49
	v_fma_f32 v181, s100, v31, v181
	v_readlane_b32 s42, v32, 50
	v_fma_f32 v183, s101, v31, v183
	v_readlane_b32 s43, v32, 51
	v_fma_f32 v177, s30, v33, v177
	v_readlane_b32 s98, v34, 48
	v_fma_f32 v179, s31, v33, v179
	v_readlane_b32 s99, v34, 49
	v_fma_f32 v181, s42, v33, v181
	v_readlane_b32 s100, v34, 50
	v_fma_f32 v183, s43, v33, v183
	v_readlane_b32 s101, v34, 51
	v_fma_f32 v177, s98, v35, v177
	v_readlane_b32 s30, v36, 48
	v_fma_f32 v179, s99, v35, v179
	v_readlane_b32 s31, v36, 49
	v_fma_f32 v181, s100, v35, v181
	v_readlane_b32 s42, v36, 50
	v_fma_f32 v183, s101, v35, v183
	v_readlane_b32 s43, v36, 51
	v_fma_f32 v177, s30, v37, v177
	v_readlane_b32 s98, v38, 48
	v_fma_f32 v179, s31, v37, v179
	v_readlane_b32 s99, v38, 49
	v_fma_f32 v181, s42, v37, v181
	v_readlane_b32 s100, v38, 50
	v_fma_f32 v183, s43, v37, v183
	v_readlane_b32 s101, v38, 51
	v_fma_f32 v177, s98, v39, v177
	v_readlane_b32 s30, v40, 48
	v_fma_f32 v179, s99, v39, v179
	v_readlane_b32 s31, v40, 49
	v_fma_f32 v181, s100, v39, v181
	v_readlane_b32 s42, v40, 50
	v_fma_f32 v183, s101, v39, v183
	v_readlane_b32 s43, v40, 51
	v_fma_f32 v177, s30, v41, v177
	v_readlane_b32 s98, v42, 48
	v_fma_f32 v179, s31, v41, v179
	v_readlane_b32 s99, v42, 49
	v_fma_f32 v181, s42, v41, v181
	v_readlane_b32 s100, v42, 50
	v_fma_f32 v183, s43, v41, v183
	v_readlane_b32 s101, v42, 51
	v_fma_f32 v177, s98, v43, v177
	v_readlane_b32 s30, v44, 48
	v_fma_f32 v179, s99, v43, v179
	v_readlane_b32 s31, v44, 49
	v_fma_f32 v181, s100, v43, v181
	v_readlane_b32 s42, v44, 50
	v_fma_f32 v183, s101, v43, v183
	v_readlane_b32 s43, v44, 51
	v_fma_f32 v177, s30, v45, v177
	v_readlane_b32 s98, v46, 48
	v_fma_f32 v179, s31, v45, v179
	v_readlane_b32 s99, v46, 49
	v_fma_f32 v181, s42, v45, v181
	v_readlane_b32 s100, v46, 50
	v_fma_f32 v183, s43, v45, v183
	v_readlane_b32 s101, v46, 51
	v_fma_f32 v177, s98, v47, v177
	v_readlane_b32 s30, v48, 48
	v_fma_f32 v179, s99, v47, v179
	v_readlane_b32 s31, v48, 49
	v_fma_f32 v181, s100, v47, v181
	v_readlane_b32 s42, v48, 50
	v_fma_f32 v183, s101, v47, v183
	v_readlane_b32 s43, v48, 51
	v_fma_f32 v177, s30, v49, v177
	v_readlane_b32 s98, v50, 48
	v_fma_f32 v179, s31, v49, v179
	v_readlane_b32 s99, v50, 49
	v_fma_f32 v181, s42, v49, v181
	v_readlane_b32 s100, v50, 50
	v_fma_f32 v183, s43, v49, v183
	v_readlane_b32 s101, v50, 51
	v_fma_f32 v177, s98, v51, v177
	v_readlane_b32 s30, v52, 48
	v_fma_f32 v179, s99, v51, v179
	v_readlane_b32 s31, v52, 49
	v_fma_f32 v181, s100, v51, v181
	v_readlane_b32 s42, v52, 50
	v_fma_f32 v183, s101, v51, v183
	v_readlane_b32 s43, v52, 51
	v_fma_f32 v177, s30, v53, v177
	v_readlane_b32 s98, v54, 48
	v_fma_f32 v179, s31, v53, v179
	v_readlane_b32 s99, v54, 49
	v_fma_f32 v181, s42, v53, v181
	v_readlane_b32 s100, v54, 50
	v_fma_f32 v183, s43, v53, v183
	v_readlane_b32 s101, v54, 51
	v_fma_f32 v177, s98, v55, v177
	v_readlane_b32 s30, v56, 48
	v_fma_f32 v179, s99, v55, v179
	v_readlane_b32 s31, v56, 49
	v_fma_f32 v181, s100, v55, v181
	v_readlane_b32 s42, v56, 50
	v_fma_f32 v183, s101, v55, v183
	v_readlane_b32 s43, v56, 51
	v_fma_f32 v177, s30, v57, v177
	v_readlane_b32 s98, v118, 48
	v_fma_f32 v179, s31, v57, v179
	v_readlane_b32 s99, v118, 49
	v_fma_f32 v181, s42, v57, v181
	v_readlane_b32 s100, v118, 50
	v_fma_f32 v183, s43, v57, v183
	v_readlane_b32 s101, v118, 51
	v_fma_f32 v177, s98, v119, v177
	v_readlane_b32 s30, v120, 48
	v_fma_f32 v179, s99, v119, v179
	v_readlane_b32 s31, v120, 49
	v_fma_f32 v181, s100, v119, v181
	v_readlane_b32 s42, v120, 50
	v_fma_f32 v183, s101, v119, v183
	v_readlane_b32 s43, v120, 51
	v_fma_f32 v177, s30, v121, v177
	v_readlane_b32 s98, v122, 48
	v_fma_f32 v179, s31, v121, v179
	v_readlane_b32 s99, v122, 49
	v_fma_f32 v181, s42, v121, v181
	v_readlane_b32 s100, v122, 50
	v_fma_f32 v183, s43, v121, v183
	v_readlane_b32 s101, v122, 51
	v_fma_f32 v177, s98, v123, v177
	v_readlane_b32 s30, v124, 48
	v_fma_f32 v179, s99, v123, v179
	v_readlane_b32 s31, v124, 49
	v_fma_f32 v181, s100, v123, v181
	v_readlane_b32 s42, v124, 50
	v_fma_f32 v183, s101, v123, v183
	v_readlane_b32 s43, v124, 51
	v_fma_f32 v177, s30, v125, v177
	v_readlane_b32 s98, v126, 48
	v_fma_f32 v179, s31, v125, v179
	v_readlane_b32 s99, v126, 49
	v_fma_f32 v181, s42, v125, v181
	v_readlane_b32 s100, v126, 50
	v_fma_f32 v183, s43, v125, v183
	v_readlane_b32 s101, v126, 51
	v_fma_f32 v177, s98, v127, v177
	v_readlane_b32 s30, v128, 48
	v_fma_f32 v179, s99, v127, v179
	v_readlane_b32 s31, v128, 49
	v_fma_f32 v181, s100, v127, v181
	v_readlane_b32 s42, v128, 50
	v_fma_f32 v183, s101, v127, v183
	v_readlane_b32 s43, v128, 51
	v_fma_f32 v177, s30, v129, v177
	v_readlane_b32 s98, v130, 48
	v_fma_f32 v179, s31, v129, v179
	v_readlane_b32 s99, v130, 49
	v_fma_f32 v181, s42, v129, v181
	v_readlane_b32 s100, v130, 50
	v_fma_f32 v183, s43, v129, v183
	v_readlane_b32 s101, v130, 51
	v_fma_f32 v177, s98, v131, v177
	v_readlane_b32 s30, v132, 48
	v_fma_f32 v179, s99, v131, v179
	v_readlane_b32 s31, v132, 49
	v_fma_f32 v181, s100, v131, v181
	v_readlane_b32 s42, v132, 50
	v_fma_f32 v183, s101, v131, v183
	v_readlane_b32 s43, v132, 51
	v_fma_f32 v177, s30, v133, v177
	v_readlane_b32 s98, v134, 48
	v_fma_f32 v179, s31, v133, v179
	v_readlane_b32 s99, v134, 49
	v_fma_f32 v181, s42, v133, v181
	v_readlane_b32 s100, v134, 50
	v_fma_f32 v183, s43, v133, v183
	v_readlane_b32 s101, v134, 51
	v_fma_f32 v177, s98, v135, v177
	v_readlane_b32 s30, v136, 48
	v_fma_f32 v179, s99, v135, v179
	v_readlane_b32 s31, v136, 49
	v_fma_f32 v181, s100, v135, v181
	v_readlane_b32 s42, v136, 50
	v_fma_f32 v183, s101, v135, v183
	v_readlane_b32 s43, v136, 51
	v_fma_f32 v177, s30, v137, v177
	v_readlane_b32 s98, v138, 48
	v_fma_f32 v179, s31, v137, v179
	v_readlane_b32 s99, v138, 49
	v_fma_f32 v181, s42, v137, v181
	v_readlane_b32 s100, v138, 50
	v_fma_f32 v183, s43, v137, v183
	v_readlane_b32 s101, v138, 51
	v_fma_f32 v177, s98, v139, v177
	v_readlane_b32 s30, v140, 48
	v_fma_f32 v179, s99, v139, v179
	v_readlane_b32 s31, v140, 49
	v_fma_f32 v181, s100, v139, v181
	v_readlane_b32 s42, v140, 50
	v_fma_f32 v183, s101, v139, v183
	v_readlane_b32 s43, v140, 51
	v_fma_f32 v177, s30, v141, v177
	v_readlane_b32 s98, v142, 48
	v_fma_f32 v179, s31, v141, v179
	v_readlane_b32 s99, v142, 49
	v_fma_f32 v181, s42, v141, v181
	v_readlane_b32 s100, v142, 50
	v_fma_f32 v183, s43, v141, v183
	v_readlane_b32 s101, v142, 51
	v_fma_f32 v177, s98, v143, v177
	v_readlane_b32 s30, v144, 48
	v_fma_f32 v179, s99, v143, v179
	v_readlane_b32 s31, v144, 49
	v_fma_f32 v181, s100, v143, v181
	v_readlane_b32 s42, v144, 50
	v_fma_f32 v183, s101, v143, v183
	v_readlane_b32 s43, v144, 51
	v_fma_f32 v177, s30, v145, v177
	v_readlane_b32 s98, v146, 48
	v_fma_f32 v179, s31, v145, v179
	v_readlane_b32 s99, v146, 49
	v_fma_f32 v181, s42, v145, v181
	v_readlane_b32 s100, v146, 50
	v_fma_f32 v183, s43, v145, v183
	v_readlane_b32 s101, v146, 51
	v_fma_f32 v177, s98, v147, v177
	v_readlane_b32 s30, v148, 48
	v_fma_f32 v179, s99, v147, v179
	v_readlane_b32 s31, v148, 49
	v_fma_f32 v181, s100, v147, v181
	v_readlane_b32 s42, v148, 50
	v_fma_f32 v183, s101, v147, v183
	v_readlane_b32 s43, v148, 51
	v_fma_f32 v177, s30, v149, v177
	v_readlane_b32 s98, v150, 48
	v_fma_f32 v179, s31, v149, v179
	v_readlane_b32 s99, v150, 49
	v_fma_f32 v181, s42, v149, v181
	v_readlane_b32 s100, v150, 50
	v_fma_f32 v183, s43, v149, v183
	v_readlane_b32 s101, v150, 51
	v_fma_f32 v177, s98, v151, v177
	v_readlane_b32 s30, v152, 48
	v_fma_f32 v179, s99, v151, v179
	v_readlane_b32 s31, v152, 49
	v_fma_f32 v181, s100, v151, v181
	v_readlane_b32 s42, v152, 50
	v_fma_f32 v183, s101, v151, v183
	v_readlane_b32 s43, v152, 51
	v_fma_f32 v177, s30, v153, v177
	v_readlane_b32 s98, v154, 48
	v_fma_f32 v179, s31, v153, v179
	v_readlane_b32 s99, v154, 49
	v_fma_f32 v181, s42, v153, v181
	v_readlane_b32 s100, v154, 50
	v_fma_f32 v183, s43, v153, v183
	v_readlane_b32 s101, v154, 51
	v_fma_f32 v177, s98, v155, v177
	v_readlane_b32 s30, v156, 48
	v_fma_f32 v179, s99, v155, v179
	v_readlane_b32 s31, v156, 49
	v_fma_f32 v181, s100, v155, v181
	v_readlane_b32 s42, v156, 50
	v_fma_f32 v183, s101, v155, v183
	v_readlane_b32 s43, v156, 51
	v_fma_f32 v177, s30, v157, v177
	v_readlane_b32 s98, v158, 48
	v_fma_f32 v179, s31, v157, v179
	v_readlane_b32 s99, v158, 49
	v_fma_f32 v181, s42, v157, v181
	v_readlane_b32 s100, v158, 50
	v_fma_f32 v183, s43, v157, v183
	v_readlane_b32 s101, v158, 51
	v_fma_f32 v177, s98, v159, v177
	v_readlane_b32 s30, v160, 48
	v_fma_f32 v179, s99, v159, v179
	v_readlane_b32 s31, v160, 49
	v_fma_f32 v181, s100, v159, v181
	v_readlane_b32 s42, v160, 50
	v_fma_f32 v183, s101, v159, v183
	v_readlane_b32 s43, v160, 51
	v_fma_f32 v177, s30, v161, v177
	v_readlane_b32 s98, v162, 48
	v_fma_f32 v179, s31, v161, v179
	v_readlane_b32 s99, v162, 49
	v_fma_f32 v181, s42, v161, v181
	v_readlane_b32 s100, v162, 50
	v_fma_f32 v183, s43, v161, v183
	v_readlane_b32 s101, v162, 51
	v_fma_f32 v177, s98, v163, v177
	v_readlane_b32 s30, v164, 48
	v_fma_f32 v179, s99, v163, v179
	v_readlane_b32 s31, v164, 49
	v_fma_f32 v181, s100, v163, v181
	v_readlane_b32 s42, v164, 50
	v_fma_f32 v183, s101, v163, v183
	v_readlane_b32 s43, v164, 51
	v_fma_f32 v177, s30, v165, v177
	v_readlane_b32 s98, v166, 48
	v_fma_f32 v179, s31, v165, v179
	v_readlane_b32 s99, v166, 49
	v_fma_f32 v181, s42, v165, v181
	v_readlane_b32 s100, v166, 50
	v_fma_f32 v183, s43, v165, v183
	v_readlane_b32 s101, v166, 51
	v_fma_f32 v177, s98, v167, v177
	v_readlane_b32 s30, v168, 48
	v_fma_f32 v179, s99, v167, v179
	v_readlane_b32 s31, v168, 49
	v_fma_f32 v181, s100, v167, v181
	v_readlane_b32 s42, v168, 50
	v_fma_f32 v183, s101, v167, v183
	v_readlane_b32 s43, v168, 51
	v_fma_f32 v177, s30, v169, v177
	v_readlane_b32 s98, v170, 48
	v_fma_f32 v179, s31, v169, v179
	v_readlane_b32 s99, v170, 49
	v_fma_f32 v181, s42, v169, v181
	v_readlane_b32 s100, v170, 50
	v_fma_f32 v183, s43, v169, v183
	v_readlane_b32 s101, v170, 51
	v_fma_f32 v177, s98, v171, v177
	v_readlane_b32 s30, v172, 48
	v_fma_f32 v179, s99, v171, v179
	v_readlane_b32 s31, v172, 49
	v_fma_f32 v181, s100, v171, v181
	v_readlane_b32 s42, v172, 50
	v_fma_f32 v183, s101, v171, v183
	v_readlane_b32 s43, v172, 51
	v_fma_f32 v177, s30, v173, v177
	v_readlane_b32 s98, v174, 48
	v_fma_f32 v179, s31, v173, v179
	v_readlane_b32 s99, v174, 49
	v_fma_f32 v181, s42, v173, v181
	v_readlane_b32 s100, v174, 50
	v_fma_f32 v183, s43, v173, v183
	v_readlane_b32 s101, v174, 51
	v_fma_f32 v177, s98, v175, v177
	v_readlane_b32 s30, v176, 49
	v_fma_f32 v179, s99, v175, v179
	v_readlane_b32 s31, v176, 50
	v_fma_f32 v181, s100, v175, v181
	v_readlane_b32 s42, v176, 51
	v_fma_f32 v183, s101, v175, v183
	v_readlane_b32 s43, v178, 50
	v_fma_f32 v179, s30, v177, v179
	v_readlane_b32 s98, v178, 51
	v_fma_f32 v181, s31, v177, v181
	v_readlane_b32 s99, v180, 51
	v_fma_f32 v183, s42, v177, v183
	v_readlane_b32 s100, v20, 52
	v_fma_f32 v181, s43, v179, v181
	v_readlane_b32 s101, v20, 53
	v_fma_f32 v183, s98, v179, v183
	v_readlane_b32 s30, v20, 54
	v_fma_f32 v183, s99, v181, v183
	v_readlane_b32 s31, v20, 55
	v_fma_f32 v185, s100, v21, v185
	v_readlane_b32 s42, v22, 52
	v_fma_f32 v187, s101, v21, v187
	v_readlane_b32 s43, v22, 53
	v_fma_f32 v189, s30, v21, v189
	v_readlane_b32 s98, v22, 54
	v_fma_f32 v191, s31, v21, v191
	v_readlane_b32 s99, v22, 55
	v_fma_f32 v185, s42, v23, v185
	v_readlane_b32 s100, v24, 52
	v_fma_f32 v187, s43, v23, v187
	v_readlane_b32 s101, v24, 53
	v_fma_f32 v189, s98, v23, v189
	v_readlane_b32 s30, v24, 54
	v_fma_f32 v191, s99, v23, v191
	v_readlane_b32 s31, v24, 55
	v_fma_f32 v185, s100, v25, v185
	v_readlane_b32 s42, v26, 52
	v_fma_f32 v187, s101, v25, v187
	v_readlane_b32 s43, v26, 53
	v_fma_f32 v189, s30, v25, v189
	v_readlane_b32 s98, v26, 54
	v_fma_f32 v191, s31, v25, v191
	v_readlane_b32 s99, v26, 55
	v_fma_f32 v185, s42, v27, v185
	v_readlane_b32 s100, v28, 52
	v_fma_f32 v187, s43, v27, v187
	v_readlane_b32 s101, v28, 53
	v_fma_f32 v189, s98, v27, v189
	v_readlane_b32 s30, v28, 54
	v_fma_f32 v191, s99, v27, v191
	v_readlane_b32 s31, v28, 55
	v_fma_f32 v185, s100, v29, v185
	v_readlane_b32 s42, v30, 52
	v_fma_f32 v187, s101, v29, v187
	v_readlane_b32 s43, v30, 53
	v_fma_f32 v189, s30, v29, v189
	v_readlane_b32 s98, v30, 54
	v_fma_f32 v191, s31, v29, v191
	v_readlane_b32 s99, v30, 55
	v_fma_f32 v185, s42, v31, v185
	v_readlane_b32 s100, v32, 52
	v_fma_f32 v187, s43, v31, v187
	v_readlane_b32 s101, v32, 53
	v_fma_f32 v189, s98, v31, v189
	v_readlane_b32 s30, v32, 54
	v_fma_f32 v191, s99, v31, v191
	v_readlane_b32 s31, v32, 55
	v_fma_f32 v185, s100, v33, v185
	v_readlane_b32 s42, v34, 52
	v_fma_f32 v187, s101, v33, v187
	v_readlane_b32 s43, v34, 53
	v_fma_f32 v189, s30, v33, v189
	v_readlane_b32 s98, v34, 54
	v_fma_f32 v191, s31, v33, v191
	v_readlane_b32 s99, v34, 55
	v_fma_f32 v185, s42, v35, v185
	v_readlane_b32 s100, v36, 52
	v_fma_f32 v187, s43, v35, v187
	v_readlane_b32 s101, v36, 53
	v_fma_f32 v189, s98, v35, v189
	v_readlane_b32 s30, v36, 54
	v_fma_f32 v191, s99, v35, v191
	v_readlane_b32 s31, v36, 55
	v_fma_f32 v185, s100, v37, v185
	v_readlane_b32 s42, v38, 52
	v_fma_f32 v187, s101, v37, v187
	v_readlane_b32 s43, v38, 53
	v_fma_f32 v189, s30, v37, v189
	v_readlane_b32 s98, v38, 54
	v_fma_f32 v191, s31, v37, v191
	v_readlane_b32 s99, v38, 55
	v_fma_f32 v185, s42, v39, v185
	v_readlane_b32 s100, v40, 52
	v_fma_f32 v187, s43, v39, v187
	v_readlane_b32 s101, v40, 53
	v_fma_f32 v189, s98, v39, v189
	v_readlane_b32 s30, v40, 54
	v_fma_f32 v191, s99, v39, v191
	v_readlane_b32 s31, v40, 55
	v_fma_f32 v185, s100, v41, v185
	v_readlane_b32 s42, v42, 52
	v_fma_f32 v187, s101, v41, v187
	v_readlane_b32 s43, v42, 53
	v_fma_f32 v189, s30, v41, v189
	v_readlane_b32 s98, v42, 54
	v_fma_f32 v191, s31, v41, v191
	v_readlane_b32 s99, v42, 55
	v_fma_f32 v185, s42, v43, v185
	v_readlane_b32 s100, v44, 52
	v_fma_f32 v187, s43, v43, v187
	v_readlane_b32 s101, v44, 53
	v_fma_f32 v189, s98, v43, v189
	v_readlane_b32 s30, v44, 54
	v_fma_f32 v191, s99, v43, v191
	v_readlane_b32 s31, v44, 55
	v_fma_f32 v185, s100, v45, v185
	v_readlane_b32 s42, v46, 52
	v_fma_f32 v187, s101, v45, v187
	v_readlane_b32 s43, v46, 53
	v_fma_f32 v189, s30, v45, v189
	v_readlane_b32 s98, v46, 54
	v_fma_f32 v191, s31, v45, v191
	v_readlane_b32 s99, v46, 55
	v_fma_f32 v185, s42, v47, v185
	v_readlane_b32 s100, v48, 52
	v_fma_f32 v187, s43, v47, v187
	v_readlane_b32 s101, v48, 53
	v_fma_f32 v189, s98, v47, v189
	v_readlane_b32 s30, v48, 54
	v_fma_f32 v191, s99, v47, v191
	v_readlane_b32 s31, v48, 55
	v_fma_f32 v185, s100, v49, v185
	v_readlane_b32 s42, v50, 52
	v_fma_f32 v187, s101, v49, v187
	v_readlane_b32 s43, v50, 53
	v_fma_f32 v189, s30, v49, v189
	v_readlane_b32 s98, v50, 54
	v_fma_f32 v191, s31, v49, v191
	v_readlane_b32 s99, v50, 55
	v_fma_f32 v185, s42, v51, v185
	v_readlane_b32 s100, v52, 52
	v_fma_f32 v187, s43, v51, v187
	v_readlane_b32 s101, v52, 53
	v_fma_f32 v189, s98, v51, v189
	v_readlane_b32 s30, v52, 54
	v_fma_f32 v191, s99, v51, v191
	v_readlane_b32 s31, v52, 55
	v_fma_f32 v185, s100, v53, v185
	v_readlane_b32 s42, v54, 52
	v_fma_f32 v187, s101, v53, v187
	v_readlane_b32 s43, v54, 53
	v_fma_f32 v189, s30, v53, v189
	v_readlane_b32 s98, v54, 54
	v_fma_f32 v191, s31, v53, v191
	v_readlane_b32 s99, v54, 55
	v_fma_f32 v185, s42, v55, v185
	v_readlane_b32 s100, v56, 52
	v_fma_f32 v187, s43, v55, v187
	v_readlane_b32 s101, v56, 53
	v_fma_f32 v189, s98, v55, v189
	v_readlane_b32 s30, v56, 54
	v_fma_f32 v191, s99, v55, v191
	v_readlane_b32 s31, v56, 55
	v_fma_f32 v185, s100, v57, v185
	v_readlane_b32 s42, v118, 52
	v_fma_f32 v187, s101, v57, v187
	v_readlane_b32 s43, v118, 53
	v_fma_f32 v189, s30, v57, v189
	v_readlane_b32 s98, v118, 54
	v_fma_f32 v191, s31, v57, v191
	v_readlane_b32 s99, v118, 55
	v_fma_f32 v185, s42, v119, v185
	v_readlane_b32 s100, v120, 52
	v_fma_f32 v187, s43, v119, v187
	v_readlane_b32 s101, v120, 53
	v_fma_f32 v189, s98, v119, v189
	v_readlane_b32 s30, v120, 54
	v_fma_f32 v191, s99, v119, v191
	v_readlane_b32 s31, v120, 55
	v_fma_f32 v185, s100, v121, v185
	v_readlane_b32 s42, v122, 52
	v_fma_f32 v187, s101, v121, v187
	v_readlane_b32 s43, v122, 53
	v_fma_f32 v189, s30, v121, v189
	v_readlane_b32 s98, v122, 54
	v_fma_f32 v191, s31, v121, v191
	v_readlane_b32 s99, v122, 55
	v_fma_f32 v185, s42, v123, v185
	v_readlane_b32 s100, v124, 52
	v_fma_f32 v187, s43, v123, v187
	v_readlane_b32 s101, v124, 53
	v_fma_f32 v189, s98, v123, v189
	v_readlane_b32 s30, v124, 54
	v_fma_f32 v191, s99, v123, v191
	v_readlane_b32 s31, v124, 55
	v_fma_f32 v185, s100, v125, v185
	v_readlane_b32 s42, v126, 52
	v_fma_f32 v187, s101, v125, v187
	v_readlane_b32 s43, v126, 53
	v_fma_f32 v189, s30, v125, v189
	v_readlane_b32 s98, v126, 54
	v_fma_f32 v191, s31, v125, v191
	v_readlane_b32 s99, v126, 55
	v_fma_f32 v185, s42, v127, v185
	v_readlane_b32 s100, v128, 52
	v_fma_f32 v187, s43, v127, v187
	v_readlane_b32 s101, v128, 53
	v_fma_f32 v189, s98, v127, v189
	v_readlane_b32 s30, v128, 54
	v_fma_f32 v191, s99, v127, v191
	v_readlane_b32 s31, v128, 55
	v_fma_f32 v185, s100, v129, v185
	v_readlane_b32 s42, v130, 52
	v_fma_f32 v187, s101, v129, v187
	v_readlane_b32 s43, v130, 53
	v_fma_f32 v189, s30, v129, v189
	v_readlane_b32 s98, v130, 54
	v_fma_f32 v191, s31, v129, v191
	v_readlane_b32 s99, v130, 55
	v_fma_f32 v185, s42, v131, v185
	v_readlane_b32 s100, v132, 52
	v_fma_f32 v187, s43, v131, v187
	v_readlane_b32 s101, v132, 53
	v_fma_f32 v189, s98, v131, v189
	v_readlane_b32 s30, v132, 54
	v_fma_f32 v191, s99, v131, v191
	v_readlane_b32 s31, v132, 55
	v_fma_f32 v185, s100, v133, v185
	v_readlane_b32 s42, v134, 52
	v_fma_f32 v187, s101, v133, v187
	v_readlane_b32 s43, v134, 53
	v_fma_f32 v189, s30, v133, v189
	v_readlane_b32 s98, v134, 54
	v_fma_f32 v191, s31, v133, v191
	v_readlane_b32 s99, v134, 55
	v_fma_f32 v185, s42, v135, v185
	v_readlane_b32 s100, v136, 52
	v_fma_f32 v187, s43, v135, v187
	v_readlane_b32 s101, v136, 53
	v_fma_f32 v189, s98, v135, v189
	v_readlane_b32 s30, v136, 54
	v_fma_f32 v191, s99, v135, v191
	v_readlane_b32 s31, v136, 55
	v_fma_f32 v185, s100, v137, v185
	v_readlane_b32 s42, v138, 52
	v_fma_f32 v187, s101, v137, v187
	v_readlane_b32 s43, v138, 53
	v_fma_f32 v189, s30, v137, v189
	v_readlane_b32 s98, v138, 54
	v_fma_f32 v191, s31, v137, v191
	v_readlane_b32 s99, v138, 55
	v_fma_f32 v185, s42, v139, v185
	v_readlane_b32 s100, v140, 52
	v_fma_f32 v187, s43, v139, v187
	v_readlane_b32 s101, v140, 53
	v_fma_f32 v189, s98, v139, v189
	v_readlane_b32 s30, v140, 54
	v_fma_f32 v191, s99, v139, v191
	v_readlane_b32 s31, v140, 55
	v_fma_f32 v185, s100, v141, v185
	v_readlane_b32 s42, v142, 52
	v_fma_f32 v187, s101, v141, v187
	v_readlane_b32 s43, v142, 53
	v_fma_f32 v189, s30, v141, v189
	v_readlane_b32 s98, v142, 54
	v_fma_f32 v191, s31, v141, v191
	v_readlane_b32 s99, v142, 55
	v_fma_f32 v185, s42, v143, v185
	v_readlane_b32 s100, v144, 52
	v_fma_f32 v187, s43, v143, v187
	v_readlane_b32 s101, v144, 53
	v_fma_f32 v189, s98, v143, v189
	v_readlane_b32 s30, v144, 54
	v_fma_f32 v191, s99, v143, v191
	v_readlane_b32 s31, v144, 55
	v_fma_f32 v185, s100, v145, v185
	v_readlane_b32 s42, v146, 52
	v_fma_f32 v187, s101, v145, v187
	v_readlane_b32 s43, v146, 53
	v_fma_f32 v189, s30, v145, v189
	v_readlane_b32 s98, v146, 54
	v_fma_f32 v191, s31, v145, v191
	v_readlane_b32 s99, v146, 55
	v_fma_f32 v185, s42, v147, v185
	v_readlane_b32 s100, v148, 52
	v_fma_f32 v187, s43, v147, v187
	v_readlane_b32 s101, v148, 53
	v_fma_f32 v189, s98, v147, v189
	v_readlane_b32 s30, v148, 54
	v_fma_f32 v191, s99, v147, v191
	v_readlane_b32 s31, v148, 55
	v_fma_f32 v185, s100, v149, v185
	v_readlane_b32 s42, v150, 52
	v_fma_f32 v187, s101, v149, v187
	v_readlane_b32 s43, v150, 53
	v_fma_f32 v189, s30, v149, v189
	v_readlane_b32 s98, v150, 54
	v_fma_f32 v191, s31, v149, v191
	v_readlane_b32 s99, v150, 55
	v_fma_f32 v185, s42, v151, v185
	v_readlane_b32 s100, v152, 52
	v_fma_f32 v187, s43, v151, v187
	v_readlane_b32 s101, v152, 53
	v_fma_f32 v189, s98, v151, v189
	v_readlane_b32 s30, v152, 54
	v_fma_f32 v191, s99, v151, v191
	v_readlane_b32 s31, v152, 55
	v_fma_f32 v185, s100, v153, v185
	v_readlane_b32 s42, v154, 52
	v_fma_f32 v187, s101, v153, v187
	v_readlane_b32 s43, v154, 53
	v_fma_f32 v189, s30, v153, v189
	v_readlane_b32 s98, v154, 54
	v_fma_f32 v191, s31, v153, v191
	v_readlane_b32 s99, v154, 55
	v_fma_f32 v185, s42, v155, v185
	v_readlane_b32 s100, v156, 52
	v_fma_f32 v187, s43, v155, v187
	v_readlane_b32 s101, v156, 53
	v_fma_f32 v189, s98, v155, v189
	v_readlane_b32 s30, v156, 54
	v_fma_f32 v191, s99, v155, v191
	v_readlane_b32 s31, v156, 55
	v_fma_f32 v185, s100, v157, v185
	v_readlane_b32 s42, v158, 52
	v_fma_f32 v187, s101, v157, v187
	v_readlane_b32 s43, v158, 53
	v_fma_f32 v189, s30, v157, v189
	v_readlane_b32 s98, v158, 54
	v_fma_f32 v191, s31, v157, v191
	v_readlane_b32 s99, v158, 55
	v_fma_f32 v185, s42, v159, v185
	v_readlane_b32 s100, v160, 52
	v_fma_f32 v187, s43, v159, v187
	v_readlane_b32 s101, v160, 53
	v_fma_f32 v189, s98, v159, v189
	v_readlane_b32 s30, v160, 54
	v_fma_f32 v191, s99, v159, v191
	v_readlane_b32 s31, v160, 55
	v_fma_f32 v185, s100, v161, v185
	v_readlane_b32 s42, v162, 52
	v_fma_f32 v187, s101, v161, v187
	v_readlane_b32 s43, v162, 53
	v_fma_f32 v189, s30, v161, v189
	v_readlane_b32 s98, v162, 54
	v_fma_f32 v191, s31, v161, v191
	v_readlane_b32 s99, v162, 55
	v_fma_f32 v185, s42, v163, v185
	v_readlane_b32 s100, v164, 52
	v_fma_f32 v187, s43, v163, v187
	v_readlane_b32 s101, v164, 53
	v_fma_f32 v189, s98, v163, v189
	v_readlane_b32 s30, v164, 54
	v_fma_f32 v191, s99, v163, v191
	v_readlane_b32 s31, v164, 55
	v_fma_f32 v185, s100, v165, v185
	v_readlane_b32 s42, v166, 52
	v_fma_f32 v187, s101, v165, v187
	v_readlane_b32 s43, v166, 53
	v_fma_f32 v189, s30, v165, v189
	v_readlane_b32 s98, v166, 54
	v_fma_f32 v191, s31, v165, v191
	v_readlane_b32 s99, v166, 55
	v_fma_f32 v185, s42, v167, v185
	v_readlane_b32 s100, v168, 52
	v_fma_f32 v187, s43, v167, v187
	v_readlane_b32 s101, v168, 53
	v_fma_f32 v189, s98, v167, v189
	v_readlane_b32 s30, v168, 54
	v_fma_f32 v191, s99, v167, v191
	v_readlane_b32 s31, v168, 55
	v_fma_f32 v185, s100, v169, v185
	v_readlane_b32 s42, v170, 52
	v_fma_f32 v187, s101, v169, v187
	v_readlane_b32 s43, v170, 53
	v_fma_f32 v189, s30, v169, v189
	v_readlane_b32 s98, v170, 54
	v_fma_f32 v191, s31, v169, v191
	v_readlane_b32 s99, v170, 55
	v_fma_f32 v185, s42, v171, v185
	v_readlane_b32 s100, v172, 52
	v_fma_f32 v187, s43, v171, v187
	v_readlane_b32 s101, v172, 53
	v_fma_f32 v189, s98, v171, v189
	v_readlane_b32 s30, v172, 54
	v_fma_f32 v191, s99, v171, v191
	v_readlane_b32 s31, v172, 55
	v_fma_f32 v185, s100, v173, v185
	v_readlane_b32 s42, v174, 52
	v_fma_f32 v187, s101, v173, v187
	v_readlane_b32 s43, v174, 53
	v_fma_f32 v189, s30, v173, v189
	v_readlane_b32 s98, v174, 54
	v_fma_f32 v191, s31, v173, v191
	v_readlane_b32 s99, v174, 55
	v_fma_f32 v185, s42, v175, v185
	v_readlane_b32 s100, v176, 52
	v_fma_f32 v187, s43, v175, v187
	v_readlane_b32 s101, v176, 53
	v_fma_f32 v189, s98, v175, v189
	v_readlane_b32 s30, v176, 54
	v_fma_f32 v191, s99, v175, v191
	v_readlane_b32 s31, v176, 55
	v_fma_f32 v185, s100, v177, v185
	v_readlane_b32 s42, v178, 52
	v_fma_f32 v187, s101, v177, v187
	v_readlane_b32 s43, v178, 53
	v_fma_f32 v189, s30, v177, v189
	v_readlane_b32 s98, v178, 54
	v_fma_f32 v191, s31, v177, v191
	v_readlane_b32 s99, v178, 55
	v_fma_f32 v185, s42, v179, v185
	v_readlane_b32 s100, v180, 52
	v_fma_f32 v187, s43, v179, v187
	v_readlane_b32 s101, v180, 53
	v_fma_f32 v189, s98, v179, v189
	v_readlane_b32 s30, v180, 54
	v_fma_f32 v191, s99, v179, v191
	v_readlane_b32 s31, v180, 55
	v_fma_f32 v185, s100, v181, v185
	v_readlane_b32 s42, v182, 52
	v_fma_f32 v187, s101, v181, v187
	v_readlane_b32 s43, v182, 53
	v_fma_f32 v189, s30, v181, v189
	v_readlane_b32 s98, v182, 54
	v_fma_f32 v191, s31, v181, v191
	v_readlane_b32 s99, v182, 55
	v_fma_f32 v185, s42, v183, v185
	v_readlane_b32 s100, v184, 53
	v_fma_f32 v187, s43, v183, v187
	v_readlane_b32 s101, v184, 54
	v_fma_f32 v189, s98, v183, v189
	v_readlane_b32 s30, v184, 55
	v_fma_f32 v191, s99, v183, v191
	v_readlane_b32 s31, v186, 54
	v_fma_f32 v187, s100, v185, v187
	v_readlane_b32 s42, v186, 55
	v_fma_f32 v189, s101, v185, v189
	v_readlane_b32 s43, v188, 55
	v_fma_f32 v191, s30, v185, v191
	v_readlane_b32 s98, v20, 56
	v_fma_f32 v189, s31, v187, v189
	v_readlane_b32 s99, v20, 57
	v_fma_f32 v191, s42, v187, v191
	v_readlane_b32 s100, v20, 58
	v_fma_f32 v191, s43, v189, v191
	v_readlane_b32 s101, v20, 59
	v_fma_f32 v193, s98, v21, v193
	v_readlane_b32 s30, v22, 56
	v_fma_f32 v195, s99, v21, v195
	v_readlane_b32 s31, v22, 57
	v_fma_f32 v197, s100, v21, v197
	v_readlane_b32 s42, v22, 58
	v_fma_f32 v199, s101, v21, v199
	v_readlane_b32 s43, v22, 59
	v_fma_f32 v193, s30, v23, v193
	v_readlane_b32 s98, v24, 56
	v_fma_f32 v195, s31, v23, v195
	v_readlane_b32 s99, v24, 57
	v_fma_f32 v197, s42, v23, v197
	v_readlane_b32 s100, v24, 58
	v_fma_f32 v199, s43, v23, v199
	v_readlane_b32 s101, v24, 59
	v_fma_f32 v193, s98, v25, v193
	v_readlane_b32 s30, v26, 56
	v_fma_f32 v195, s99, v25, v195
	v_readlane_b32 s31, v26, 57
	v_fma_f32 v197, s100, v25, v197
	v_readlane_b32 s42, v26, 58
	v_fma_f32 v199, s101, v25, v199
	v_readlane_b32 s43, v26, 59
	v_fma_f32 v193, s30, v27, v193
	v_readlane_b32 s98, v28, 56
	v_fma_f32 v195, s31, v27, v195
	v_readlane_b32 s99, v28, 57
	v_fma_f32 v197, s42, v27, v197
	v_readlane_b32 s100, v28, 58
	v_fma_f32 v199, s43, v27, v199
	v_readlane_b32 s101, v28, 59
	v_fma_f32 v193, s98, v29, v193
	v_readlane_b32 s30, v30, 56
	v_fma_f32 v195, s99, v29, v195
	v_readlane_b32 s31, v30, 57
	v_fma_f32 v197, s100, v29, v197
	v_readlane_b32 s42, v30, 58
	v_fma_f32 v199, s101, v29, v199
	v_readlane_b32 s43, v30, 59
	v_fma_f32 v193, s30, v31, v193
	v_readlane_b32 s98, v32, 56
	v_fma_f32 v195, s31, v31, v195
	v_readlane_b32 s99, v32, 57
	v_fma_f32 v197, s42, v31, v197
	v_readlane_b32 s100, v32, 58
	v_fma_f32 v199, s43, v31, v199
	v_readlane_b32 s101, v32, 59
	v_fma_f32 v193, s98, v33, v193
	v_readlane_b32 s30, v34, 56
	v_fma_f32 v195, s99, v33, v195
	v_readlane_b32 s31, v34, 57
	v_fma_f32 v197, s100, v33, v197
	v_readlane_b32 s42, v34, 58
	v_fma_f32 v199, s101, v33, v199
	v_readlane_b32 s43, v34, 59
	v_fma_f32 v193, s30, v35, v193
	v_readlane_b32 s98, v36, 56
	v_fma_f32 v195, s31, v35, v195
	v_readlane_b32 s99, v36, 57
	v_fma_f32 v197, s42, v35, v197
	v_readlane_b32 s100, v36, 58
	v_fma_f32 v199, s43, v35, v199
	v_readlane_b32 s101, v36, 59
	v_fma_f32 v193, s98, v37, v193
	v_readlane_b32 s30, v38, 56
	v_fma_f32 v195, s99, v37, v195
	v_readlane_b32 s31, v38, 57
	v_fma_f32 v197, s100, v37, v197
	v_readlane_b32 s42, v38, 58
	v_fma_f32 v199, s101, v37, v199
	v_readlane_b32 s43, v38, 59
	v_fma_f32 v193, s30, v39, v193
	v_readlane_b32 s98, v40, 56
	v_fma_f32 v195, s31, v39, v195
	v_readlane_b32 s99, v40, 57
	v_fma_f32 v197, s42, v39, v197
	v_readlane_b32 s100, v40, 58
	v_fma_f32 v199, s43, v39, v199
	v_readlane_b32 s101, v40, 59
	v_fma_f32 v193, s98, v41, v193
	v_readlane_b32 s30, v42, 56
	v_fma_f32 v195, s99, v41, v195
	v_readlane_b32 s31, v42, 57
	v_fma_f32 v197, s100, v41, v197
	v_readlane_b32 s42, v42, 58
	v_fma_f32 v199, s101, v41, v199
	v_readlane_b32 s43, v42, 59
	v_fma_f32 v193, s30, v43, v193
	v_readlane_b32 s98, v44, 56
	v_fma_f32 v195, s31, v43, v195
	v_readlane_b32 s99, v44, 57
	v_fma_f32 v197, s42, v43, v197
	v_readlane_b32 s100, v44, 58
	v_fma_f32 v199, s43, v43, v199
	v_readlane_b32 s101, v44, 59
	v_fma_f32 v193, s98, v45, v193
	v_readlane_b32 s30, v46, 56
	v_fma_f32 v195, s99, v45, v195
	v_readlane_b32 s31, v46, 57
	v_fma_f32 v197, s100, v45, v197
	v_readlane_b32 s42, v46, 58
	v_fma_f32 v199, s101, v45, v199
	v_readlane_b32 s43, v46, 59
	v_fma_f32 v193, s30, v47, v193
	v_readlane_b32 s98, v48, 56
	v_fma_f32 v195, s31, v47, v195
	v_readlane_b32 s99, v48, 57
	v_fma_f32 v197, s42, v47, v197
	v_readlane_b32 s100, v48, 58
	v_fma_f32 v199, s43, v47, v199
	v_readlane_b32 s101, v48, 59
	v_fma_f32 v193, s98, v49, v193
	v_readlane_b32 s30, v50, 56
	v_fma_f32 v195, s99, v49, v195
	v_readlane_b32 s31, v50, 57
	v_fma_f32 v197, s100, v49, v197
	v_readlane_b32 s42, v50, 58
	v_fma_f32 v199, s101, v49, v199
	v_readlane_b32 s43, v50, 59
	v_fma_f32 v193, s30, v51, v193
	v_readlane_b32 s98, v52, 56
	v_fma_f32 v195, s31, v51, v195
	v_readlane_b32 s99, v52, 57
	v_fma_f32 v197, s42, v51, v197
	v_readlane_b32 s100, v52, 58
	v_fma_f32 v199, s43, v51, v199
	v_readlane_b32 s101, v52, 59
	v_fma_f32 v193, s98, v53, v193
	v_readlane_b32 s30, v54, 56
	v_fma_f32 v195, s99, v53, v195
	v_readlane_b32 s31, v54, 57
	v_fma_f32 v197, s100, v53, v197
	v_readlane_b32 s42, v54, 58
	v_fma_f32 v199, s101, v53, v199
	v_readlane_b32 s43, v54, 59
	v_fma_f32 v193, s30, v55, v193
	v_readlane_b32 s98, v56, 56
	v_fma_f32 v195, s31, v55, v195
	v_readlane_b32 s99, v56, 57
	v_fma_f32 v197, s42, v55, v197
	v_readlane_b32 s100, v56, 58
	v_fma_f32 v199, s43, v55, v199
	v_readlane_b32 s101, v56, 59
	v_fma_f32 v193, s98, v57, v193
	v_readlane_b32 s30, v118, 56
	v_fma_f32 v195, s99, v57, v195
	v_readlane_b32 s31, v118, 57
	v_fma_f32 v197, s100, v57, v197
	v_readlane_b32 s42, v118, 58
	v_fma_f32 v199, s101, v57, v199
	v_readlane_b32 s43, v118, 59
	v_fma_f32 v193, s30, v119, v193
	v_readlane_b32 s98, v120, 56
	v_fma_f32 v195, s31, v119, v195
	v_readlane_b32 s99, v120, 57
	v_fma_f32 v197, s42, v119, v197
	v_readlane_b32 s100, v120, 58
	v_fma_f32 v199, s43, v119, v199
	v_readlane_b32 s101, v120, 59
	v_fma_f32 v193, s98, v121, v193
	v_readlane_b32 s30, v122, 56
	v_fma_f32 v195, s99, v121, v195
	v_readlane_b32 s31, v122, 57
	v_fma_f32 v197, s100, v121, v197
	v_readlane_b32 s42, v122, 58
	v_fma_f32 v199, s101, v121, v199
	v_readlane_b32 s43, v122, 59
	v_fma_f32 v193, s30, v123, v193
	v_readlane_b32 s98, v124, 56
	v_fma_f32 v195, s31, v123, v195
	v_readlane_b32 s99, v124, 57
	v_fma_f32 v197, s42, v123, v197
	v_readlane_b32 s100, v124, 58
	v_fma_f32 v199, s43, v123, v199
	v_readlane_b32 s101, v124, 59
	v_fma_f32 v193, s98, v125, v193
	v_readlane_b32 s30, v126, 56
	v_fma_f32 v195, s99, v125, v195
	v_readlane_b32 s31, v126, 57
	v_fma_f32 v197, s100, v125, v197
	v_readlane_b32 s42, v126, 58
	v_fma_f32 v199, s101, v125, v199
	v_readlane_b32 s43, v126, 59
	v_fma_f32 v193, s30, v127, v193
	v_readlane_b32 s98, v128, 56
	v_fma_f32 v195, s31, v127, v195
	v_readlane_b32 s99, v128, 57
	v_fma_f32 v197, s42, v127, v197
	v_readlane_b32 s100, v128, 58
	v_fma_f32 v199, s43, v127, v199
	v_readlane_b32 s101, v128, 59
	v_fma_f32 v193, s98, v129, v193
	v_readlane_b32 s30, v130, 56
	v_fma_f32 v195, s99, v129, v195
	v_readlane_b32 s31, v130, 57
	v_fma_f32 v197, s100, v129, v197
	v_readlane_b32 s42, v130, 58
	v_fma_f32 v199, s101, v129, v199
	v_readlane_b32 s43, v130, 59
	v_fma_f32 v193, s30, v131, v193
	v_readlane_b32 s98, v132, 56
	v_fma_f32 v195, s31, v131, v195
	v_readlane_b32 s99, v132, 57
	v_fma_f32 v197, s42, v131, v197
	v_readlane_b32 s100, v132, 58
	v_fma_f32 v199, s43, v131, v199
	v_readlane_b32 s101, v132, 59
	v_fma_f32 v193, s98, v133, v193
	v_readlane_b32 s30, v134, 56
	v_fma_f32 v195, s99, v133, v195
	v_readlane_b32 s31, v134, 57
	v_fma_f32 v197, s100, v133, v197
	v_readlane_b32 s42, v134, 58
	v_fma_f32 v199, s101, v133, v199
	v_readlane_b32 s43, v134, 59
	v_fma_f32 v193, s30, v135, v193
	v_readlane_b32 s98, v136, 56
	v_fma_f32 v195, s31, v135, v195
	v_readlane_b32 s99, v136, 57
	v_fma_f32 v197, s42, v135, v197
	v_readlane_b32 s100, v136, 58
	v_fma_f32 v199, s43, v135, v199
	v_readlane_b32 s101, v136, 59
	v_fma_f32 v193, s98, v137, v193
	v_readlane_b32 s30, v138, 56
	v_fma_f32 v195, s99, v137, v195
	v_readlane_b32 s31, v138, 57
	v_fma_f32 v197, s100, v137, v197
	v_readlane_b32 s42, v138, 58
	v_fma_f32 v199, s101, v137, v199
	v_readlane_b32 s43, v138, 59
	v_fma_f32 v193, s30, v139, v193
	v_readlane_b32 s98, v140, 56
	v_fma_f32 v195, s31, v139, v195
	v_readlane_b32 s99, v140, 57
	v_fma_f32 v197, s42, v139, v197
	v_readlane_b32 s100, v140, 58
	v_fma_f32 v199, s43, v139, v199
	v_readlane_b32 s101, v140, 59
	v_fma_f32 v193, s98, v141, v193
	v_readlane_b32 s30, v142, 56
	v_fma_f32 v195, s99, v141, v195
	v_readlane_b32 s31, v142, 57
	v_fma_f32 v197, s100, v141, v197
	v_readlane_b32 s42, v142, 58
	v_fma_f32 v199, s101, v141, v199
	v_readlane_b32 s43, v142, 59
	v_fma_f32 v193, s30, v143, v193
	v_readlane_b32 s98, v144, 56
	v_fma_f32 v195, s31, v143, v195
	v_readlane_b32 s99, v144, 57
	v_fma_f32 v197, s42, v143, v197
	v_readlane_b32 s100, v144, 58
	v_fma_f32 v199, s43, v143, v199
	v_readlane_b32 s101, v144, 59
	v_fma_f32 v193, s98, v145, v193
	v_readlane_b32 s30, v146, 56
	v_fma_f32 v195, s99, v145, v195
	v_readlane_b32 s31, v146, 57
	v_fma_f32 v197, s100, v145, v197
	v_readlane_b32 s42, v146, 58
	v_fma_f32 v199, s101, v145, v199
	v_readlane_b32 s43, v146, 59
	v_fma_f32 v193, s30, v147, v193
	v_readlane_b32 s98, v148, 56
	v_fma_f32 v195, s31, v147, v195
	v_readlane_b32 s99, v148, 57
	v_fma_f32 v197, s42, v147, v197
	v_readlane_b32 s100, v148, 58
	v_fma_f32 v199, s43, v147, v199
	v_readlane_b32 s101, v148, 59
	v_fma_f32 v193, s98, v149, v193
	v_readlane_b32 s30, v150, 56
	v_fma_f32 v195, s99, v149, v195
	v_readlane_b32 s31, v150, 57
	v_fma_f32 v197, s100, v149, v197
	v_readlane_b32 s42, v150, 58
	v_fma_f32 v199, s101, v149, v199
	v_readlane_b32 s43, v150, 59
	v_fma_f32 v193, s30, v151, v193
	v_readlane_b32 s98, v152, 56
	v_fma_f32 v195, s31, v151, v195
	v_readlane_b32 s99, v152, 57
	v_fma_f32 v197, s42, v151, v197
	v_readlane_b32 s100, v152, 58
	v_fma_f32 v199, s43, v151, v199
	v_readlane_b32 s101, v152, 59
	v_fma_f32 v193, s98, v153, v193
	v_readlane_b32 s30, v154, 56
	v_fma_f32 v195, s99, v153, v195
	v_readlane_b32 s31, v154, 57
	v_fma_f32 v197, s100, v153, v197
	v_readlane_b32 s42, v154, 58
	v_fma_f32 v199, s101, v153, v199
	v_readlane_b32 s43, v154, 59
	v_fma_f32 v193, s30, v155, v193
	v_readlane_b32 s98, v156, 56
	v_fma_f32 v195, s31, v155, v195
	v_readlane_b32 s99, v156, 57
	v_fma_f32 v197, s42, v155, v197
	v_readlane_b32 s100, v156, 58
	v_fma_f32 v199, s43, v155, v199
	v_readlane_b32 s101, v156, 59
	v_fma_f32 v193, s98, v157, v193
	v_readlane_b32 s30, v158, 56
	v_fma_f32 v195, s99, v157, v195
	v_readlane_b32 s31, v158, 57
	v_fma_f32 v197, s100, v157, v197
	v_readlane_b32 s42, v158, 58
	v_fma_f32 v199, s101, v157, v199
	v_readlane_b32 s43, v158, 59
	v_fma_f32 v193, s30, v159, v193
	v_readlane_b32 s98, v160, 56
	v_fma_f32 v195, s31, v159, v195
	v_readlane_b32 s99, v160, 57
	v_fma_f32 v197, s42, v159, v197
	v_readlane_b32 s100, v160, 58
	v_fma_f32 v199, s43, v159, v199
	v_readlane_b32 s101, v160, 59
	v_fma_f32 v193, s98, v161, v193
	v_readlane_b32 s30, v162, 56
	v_fma_f32 v195, s99, v161, v195
	v_readlane_b32 s31, v162, 57
	v_fma_f32 v197, s100, v161, v197
	v_readlane_b32 s42, v162, 58
	v_fma_f32 v199, s101, v161, v199
	v_readlane_b32 s43, v162, 59
	v_fma_f32 v193, s30, v163, v193
	v_readlane_b32 s98, v164, 56
	v_fma_f32 v195, s31, v163, v195
	v_readlane_b32 s99, v164, 57
	v_fma_f32 v197, s42, v163, v197
	v_readlane_b32 s100, v164, 58
	v_fma_f32 v199, s43, v163, v199
	v_readlane_b32 s101, v164, 59
	v_fma_f32 v193, s98, v165, v193
	v_readlane_b32 s30, v166, 56
	v_fma_f32 v195, s99, v165, v195
	v_readlane_b32 s31, v166, 57
	v_fma_f32 v197, s100, v165, v197
	v_readlane_b32 s42, v166, 58
	v_fma_f32 v199, s101, v165, v199
	v_readlane_b32 s43, v166, 59
	v_fma_f32 v193, s30, v167, v193
	v_readlane_b32 s98, v168, 56
	v_fma_f32 v195, s31, v167, v195
	v_readlane_b32 s99, v168, 57
	v_fma_f32 v197, s42, v167, v197
	v_readlane_b32 s100, v168, 58
	v_fma_f32 v199, s43, v167, v199
	v_readlane_b32 s101, v168, 59
	v_fma_f32 v193, s98, v169, v193
	v_readlane_b32 s30, v170, 56
	v_fma_f32 v195, s99, v169, v195
	v_readlane_b32 s31, v170, 57
	v_fma_f32 v197, s100, v169, v197
	v_readlane_b32 s42, v170, 58
	v_fma_f32 v199, s101, v169, v199
	v_readlane_b32 s43, v170, 59
	v_fma_f32 v193, s30, v171, v193
	v_readlane_b32 s98, v172, 56
	v_fma_f32 v195, s31, v171, v195
	v_readlane_b32 s99, v172, 57
	v_fma_f32 v197, s42, v171, v197
	v_readlane_b32 s100, v172, 58
	v_fma_f32 v199, s43, v171, v199
	v_readlane_b32 s101, v172, 59
	v_fma_f32 v193, s98, v173, v193
	v_readlane_b32 s30, v174, 56
	v_fma_f32 v195, s99, v173, v195
	v_readlane_b32 s31, v174, 57
	v_fma_f32 v197, s100, v173, v197
	v_readlane_b32 s42, v174, 58
	v_fma_f32 v199, s101, v173, v199
	v_readlane_b32 s43, v174, 59
	v_fma_f32 v193, s30, v175, v193
	v_readlane_b32 s98, v176, 56
	v_fma_f32 v195, s31, v175, v195
	v_readlane_b32 s99, v176, 57
	v_fma_f32 v197, s42, v175, v197
	v_readlane_b32 s100, v176, 58
	v_fma_f32 v199, s43, v175, v199
	v_readlane_b32 s101, v176, 59
	v_fma_f32 v193, s98, v177, v193
	v_readlane_b32 s30, v178, 56
	v_fma_f32 v195, s99, v177, v195
	v_readlane_b32 s31, v178, 57
	v_fma_f32 v197, s100, v177, v197
	v_readlane_b32 s42, v178, 58
	v_fma_f32 v199, s101, v177, v199
	v_readlane_b32 s43, v178, 59
	v_fma_f32 v193, s30, v179, v193
	v_readlane_b32 s98, v180, 56
	v_fma_f32 v195, s31, v179, v195
	v_readlane_b32 s99, v180, 57
	v_fma_f32 v197, s42, v179, v197
	v_readlane_b32 s100, v180, 58
	v_fma_f32 v199, s43, v179, v199
	v_readlane_b32 s101, v180, 59
	v_fma_f32 v193, s98, v181, v193
	v_readlane_b32 s30, v182, 56
	v_fma_f32 v195, s99, v181, v195
	v_readlane_b32 s31, v182, 57
	v_fma_f32 v197, s100, v181, v197
	v_readlane_b32 s42, v182, 58
	v_fma_f32 v199, s101, v181, v199
	v_readlane_b32 s43, v182, 59
	v_fma_f32 v193, s30, v183, v193
	v_readlane_b32 s98, v184, 56
	v_fma_f32 v195, s31, v183, v195
	v_readlane_b32 s99, v184, 57
	v_fma_f32 v197, s42, v183, v197
	v_readlane_b32 s100, v184, 58
	v_fma_f32 v199, s43, v183, v199
	v_readlane_b32 s101, v184, 59
	v_fma_f32 v193, s98, v185, v193
	v_readlane_b32 s30, v186, 56
	v_fma_f32 v195, s99, v185, v195
	v_readlane_b32 s31, v186, 57
	v_fma_f32 v197, s100, v185, v197
	v_readlane_b32 s42, v186, 58
	v_fma_f32 v199, s101, v185, v199
	v_readlane_b32 s43, v186, 59
	v_fma_f32 v193, s30, v187, v193
	v_readlane_b32 s98, v188, 56
	v_fma_f32 v195, s31, v187, v195
	v_readlane_b32 s99, v188, 57
	v_fma_f32 v197, s42, v187, v197
	v_readlane_b32 s100, v188, 58
	v_fma_f32 v199, s43, v187, v199
	v_readlane_b32 s101, v188, 59
	v_fma_f32 v193, s98, v189, v193
	v_readlane_b32 s30, v190, 56
	v_fma_f32 v195, s99, v189, v195
	v_readlane_b32 s31, v190, 57
	v_fma_f32 v197, s100, v189, v197
	v_readlane_b32 s42, v190, 58
	v_fma_f32 v199, s101, v189, v199
	v_readlane_b32 s43, v190, 59
	v_fma_f32 v193, s30, v191, v193
	v_readlane_b32 s98, v192, 57
	v_fma_f32 v195, s31, v191, v195
	v_readlane_b32 s99, v192, 58
	v_fma_f32 v197, s42, v191, v197
	v_readlane_b32 s100, v192, 59
	v_fma_f32 v199, s43, v191, v199
	v_readlane_b32 s101, v194, 58
	v_fma_f32 v195, s98, v193, v195
	v_readlane_b32 s30, v194, 59
	v_fma_f32 v197, s99, v193, v197
	v_readlane_b32 s31, v196, 59
	v_fma_f32 v199, s100, v193, v199
	v_readlane_b32 s42, v20, 60
	v_fma_f32 v197, s101, v195, v197
	v_readlane_b32 s43, v20, 61
	v_fma_f32 v199, s30, v195, v199
	v_readlane_b32 s98, v20, 62
	v_fma_f32 v199, s31, v197, v199
	v_readlane_b32 s99, v20, 63
	v_fma_f32 v201, s42, v21, v201
	v_readlane_b32 s100, v22, 60
	v_fma_f32 v203, s43, v21, v203
	v_readlane_b32 s101, v22, 61
	v_fma_f32 v205, s98, v21, v205
	v_readlane_b32 s30, v22, 62
	v_fma_f32 v214, s99, v21, v214
	v_readlane_b32 s31, v22, 63
	v_fma_f32 v201, s100, v23, v201
	v_readlane_b32 s42, v24, 60
	v_fma_f32 v203, s101, v23, v203
	v_readlane_b32 s43, v24, 61
	v_fma_f32 v205, s30, v23, v205
	v_readlane_b32 s98, v24, 62
	v_fma_f32 v214, s31, v23, v214
	v_readlane_b32 s99, v24, 63
	v_fma_f32 v201, s42, v25, v201
	v_readlane_b32 s100, v26, 60
	v_fma_f32 v203, s43, v25, v203
	v_readlane_b32 s101, v26, 61
	v_fma_f32 v205, s98, v25, v205
	v_readlane_b32 s30, v26, 62
	v_fma_f32 v214, s99, v25, v214
	v_readlane_b32 s31, v26, 63
	v_fma_f32 v201, s100, v27, v201
	v_readlane_b32 s42, v28, 60
	v_fma_f32 v203, s101, v27, v203
	v_readlane_b32 s43, v28, 61
	v_fma_f32 v205, s30, v27, v205
	v_readlane_b32 s98, v28, 62
	v_fma_f32 v214, s31, v27, v214
	v_readlane_b32 s99, v28, 63
	v_fma_f32 v201, s42, v29, v201
	v_readlane_b32 s100, v30, 60
	v_fma_f32 v203, s43, v29, v203
	v_readlane_b32 s101, v30, 61
	v_fma_f32 v205, s98, v29, v205
	v_readlane_b32 s30, v30, 62
	v_fma_f32 v214, s99, v29, v214
	v_readlane_b32 s31, v30, 63
	v_fma_f32 v201, s100, v31, v201
	v_readlane_b32 s42, v32, 60
	v_fma_f32 v203, s101, v31, v203
	v_readlane_b32 s43, v32, 61
	v_fma_f32 v205, s30, v31, v205
	v_readlane_b32 s98, v32, 62
	v_fma_f32 v214, s31, v31, v214
	v_readlane_b32 s99, v32, 63
	v_fma_f32 v201, s42, v33, v201
	v_readlane_b32 s100, v34, 60
	v_fma_f32 v203, s43, v33, v203
	v_readlane_b32 s101, v34, 61
	v_fma_f32 v205, s98, v33, v205
	v_readlane_b32 s30, v34, 62
	v_fma_f32 v214, s99, v33, v214
	v_readlane_b32 s31, v34, 63
	v_fma_f32 v201, s100, v35, v201
	v_readlane_b32 s42, v36, 60
	v_fma_f32 v203, s101, v35, v203
	v_readlane_b32 s43, v36, 61
	v_fma_f32 v205, s30, v35, v205
	v_readlane_b32 s98, v36, 62
	v_fma_f32 v214, s31, v35, v214
	v_readlane_b32 s99, v36, 63
	v_fma_f32 v201, s42, v37, v201
	v_readlane_b32 s100, v38, 60
	v_fma_f32 v203, s43, v37, v203
	v_readlane_b32 s101, v38, 61
	v_fma_f32 v205, s98, v37, v205
	v_readlane_b32 s30, v38, 62
	v_fma_f32 v214, s99, v37, v214
	v_readlane_b32 s31, v38, 63
	v_fma_f32 v201, s100, v39, v201
	v_readlane_b32 s42, v40, 60
	v_fma_f32 v203, s101, v39, v203
	v_readlane_b32 s43, v40, 61
	v_fma_f32 v205, s30, v39, v205
	v_readlane_b32 s98, v40, 62
	v_fma_f32 v214, s31, v39, v214
	v_readlane_b32 s99, v40, 63
	v_fma_f32 v201, s42, v41, v201
	v_readlane_b32 s100, v42, 60
	v_fma_f32 v203, s43, v41, v203
	v_readlane_b32 s101, v42, 61
	v_fma_f32 v205, s98, v41, v205
	v_readlane_b32 s30, v42, 62
	v_fma_f32 v214, s99, v41, v214
	v_readlane_b32 s31, v42, 63
	v_fma_f32 v201, s100, v43, v201
	v_readlane_b32 s42, v44, 60
	v_fma_f32 v203, s101, v43, v203
	v_readlane_b32 s43, v44, 61
	v_fma_f32 v205, s30, v43, v205
	v_readlane_b32 s98, v44, 62
	v_fma_f32 v214, s31, v43, v214
	v_readlane_b32 s99, v44, 63
	v_fma_f32 v201, s42, v45, v201
	v_readlane_b32 s100, v46, 60
	v_fma_f32 v203, s43, v45, v203
	v_readlane_b32 s101, v46, 61
	v_fma_f32 v205, s98, v45, v205
	v_readlane_b32 s30, v46, 62
	v_fma_f32 v214, s99, v45, v214
	v_readlane_b32 s31, v46, 63
	v_fma_f32 v201, s100, v47, v201
	v_readlane_b32 s42, v48, 60
	v_fma_f32 v203, s101, v47, v203
	v_readlane_b32 s43, v48, 61
	v_fma_f32 v205, s30, v47, v205
	v_readlane_b32 s98, v48, 62
	v_fma_f32 v214, s31, v47, v214
	v_readlane_b32 s99, v48, 63
	v_fma_f32 v201, s42, v49, v201
	v_readlane_b32 s100, v50, 60
	v_fma_f32 v203, s43, v49, v203
	v_readlane_b32 s101, v50, 61
	v_fma_f32 v205, s98, v49, v205
	v_readlane_b32 s30, v50, 62
	v_fma_f32 v214, s99, v49, v214
	v_readlane_b32 s31, v50, 63
	v_fma_f32 v201, s100, v51, v201
	v_readlane_b32 s42, v52, 60
	v_fma_f32 v203, s101, v51, v203
	v_readlane_b32 s43, v52, 61
	v_fma_f32 v205, s30, v51, v205
	v_readlane_b32 s98, v52, 62
	v_fma_f32 v214, s31, v51, v214
	v_readlane_b32 s99, v52, 63
	v_fma_f32 v201, s42, v53, v201
	v_readlane_b32 s100, v54, 60
	v_fma_f32 v203, s43, v53, v203
	v_readlane_b32 s101, v54, 61
	v_fma_f32 v205, s98, v53, v205
	v_readlane_b32 s30, v54, 62
	v_fma_f32 v214, s99, v53, v214
	v_readlane_b32 s31, v54, 63
	v_fma_f32 v201, s100, v55, v201
	v_readlane_b32 s42, v56, 60
	v_fma_f32 v203, s101, v55, v203
	v_readlane_b32 s43, v56, 61
	v_fma_f32 v205, s30, v55, v205
	v_readlane_b32 s98, v56, 62
	v_fma_f32 v214, s31, v55, v214
	v_readlane_b32 s99, v56, 63
	v_fma_f32 v201, s42, v57, v201
	v_readlane_b32 s100, v118, 60
	v_fma_f32 v203, s43, v57, v203
	v_readlane_b32 s101, v118, 61
	v_fma_f32 v205, s98, v57, v205
	v_readlane_b32 s30, v118, 62
	v_fma_f32 v214, s99, v57, v214
	v_readlane_b32 s31, v118, 63
	v_fma_f32 v201, s100, v119, v201
	v_readlane_b32 s42, v120, 60
	v_fma_f32 v203, s101, v119, v203
	v_readlane_b32 s43, v120, 61
	v_fma_f32 v205, s30, v119, v205
	v_readlane_b32 s98, v120, 62
	v_fma_f32 v214, s31, v119, v214
	v_readlane_b32 s99, v120, 63
	v_fma_f32 v201, s42, v121, v201
	v_readlane_b32 s100, v122, 60
	v_fma_f32 v203, s43, v121, v203
	v_readlane_b32 s101, v122, 61
	v_fma_f32 v205, s98, v121, v205
	v_readlane_b32 s30, v122, 62
	v_fma_f32 v214, s99, v121, v214
	v_readlane_b32 s31, v122, 63
	v_fma_f32 v201, s100, v123, v201
	v_readlane_b32 s42, v124, 60
	v_fma_f32 v203, s101, v123, v203
	v_readlane_b32 s43, v124, 61
	v_fma_f32 v205, s30, v123, v205
	v_readlane_b32 s98, v124, 62
	v_fma_f32 v214, s31, v123, v214
	v_readlane_b32 s99, v124, 63
	v_fma_f32 v201, s42, v125, v201
	v_readlane_b32 s100, v126, 60
	v_fma_f32 v203, s43, v125, v203
	v_readlane_b32 s101, v126, 61
	v_fma_f32 v205, s98, v125, v205
	v_readlane_b32 s30, v126, 62
	v_fma_f32 v214, s99, v125, v214
	v_readlane_b32 s31, v126, 63
	v_fma_f32 v201, s100, v127, v201
	v_readlane_b32 s42, v128, 60
	v_fma_f32 v203, s101, v127, v203
	v_readlane_b32 s43, v128, 61
	v_fma_f32 v205, s30, v127, v205
	v_readlane_b32 s98, v128, 62
	v_fma_f32 v214, s31, v127, v214
	v_readlane_b32 s99, v128, 63
	v_fma_f32 v201, s42, v129, v201
	v_readlane_b32 s100, v130, 60
	v_fma_f32 v203, s43, v129, v203
	v_readlane_b32 s101, v130, 61
	v_fma_f32 v205, s98, v129, v205
	v_readlane_b32 s30, v130, 62
	v_fma_f32 v214, s99, v129, v214
	v_readlane_b32 s31, v130, 63
	v_fma_f32 v201, s100, v131, v201
	v_readlane_b32 s42, v132, 60
	v_fma_f32 v203, s101, v131, v203
	v_readlane_b32 s43, v132, 61
	v_fma_f32 v205, s30, v131, v205
	v_readlane_b32 s98, v132, 62
	v_fma_f32 v214, s31, v131, v214
	v_readlane_b32 s99, v132, 63
	v_fma_f32 v201, s42, v133, v201
	v_readlane_b32 s100, v134, 60
	v_fma_f32 v203, s43, v133, v203
	v_readlane_b32 s101, v134, 61
	v_fma_f32 v205, s98, v133, v205
	v_readlane_b32 s30, v134, 62
	v_fma_f32 v214, s99, v133, v214
	v_readlane_b32 s31, v134, 63
	v_fma_f32 v201, s100, v135, v201
	v_readlane_b32 s42, v136, 60
	v_fma_f32 v203, s101, v135, v203
	v_readlane_b32 s43, v136, 61
	v_fma_f32 v205, s30, v135, v205
	v_readlane_b32 s98, v136, 62
	v_fma_f32 v214, s31, v135, v214
	v_readlane_b32 s99, v136, 63
	v_fma_f32 v201, s42, v137, v201
	v_readlane_b32 s100, v138, 60
	v_fma_f32 v203, s43, v137, v203
	v_readlane_b32 s101, v138, 61
	v_fma_f32 v205, s98, v137, v205
	v_readlane_b32 s30, v138, 62
	v_fma_f32 v214, s99, v137, v214
	v_readlane_b32 s31, v138, 63
	v_fma_f32 v201, s100, v139, v201
	v_readlane_b32 s42, v140, 60
	v_fma_f32 v203, s101, v139, v203
	v_readlane_b32 s43, v140, 61
	v_fma_f32 v205, s30, v139, v205
	v_readlane_b32 s98, v140, 62
	v_fma_f32 v214, s31, v139, v214
	v_readlane_b32 s99, v140, 63
	v_fma_f32 v201, s42, v141, v201
	v_readlane_b32 s100, v142, 60
	v_fma_f32 v203, s43, v141, v203
	v_readlane_b32 s101, v142, 61
	v_fma_f32 v205, s98, v141, v205
	v_readlane_b32 s30, v142, 62
	v_fma_f32 v214, s99, v141, v214
	v_readlane_b32 s31, v142, 63
	v_fma_f32 v201, s100, v143, v201
	v_readlane_b32 s42, v144, 60
	v_fma_f32 v203, s101, v143, v203
	v_readlane_b32 s43, v144, 61
	v_fma_f32 v205, s30, v143, v205
	v_readlane_b32 s98, v144, 62
	v_fma_f32 v214, s31, v143, v214
	v_readlane_b32 s99, v144, 63
	v_fma_f32 v201, s42, v145, v201
	v_readlane_b32 s100, v146, 60
	v_fma_f32 v203, s43, v145, v203
	v_readlane_b32 s101, v146, 61
	v_fma_f32 v205, s98, v145, v205
	v_readlane_b32 s30, v146, 62
	v_fma_f32 v214, s99, v145, v214
	v_readlane_b32 s31, v146, 63
	v_fma_f32 v201, s100, v147, v201
	v_readlane_b32 s42, v148, 60
	v_fma_f32 v203, s101, v147, v203
	v_readlane_b32 s43, v148, 61
	v_fma_f32 v205, s30, v147, v205
	v_readlane_b32 s98, v148, 62
	v_fma_f32 v214, s31, v147, v214
	v_readlane_b32 s99, v148, 63
	v_fma_f32 v201, s42, v149, v201
	v_readlane_b32 s100, v150, 60
	v_fma_f32 v203, s43, v149, v203
	v_readlane_b32 s101, v150, 61
	v_fma_f32 v205, s98, v149, v205
	v_readlane_b32 s30, v150, 62
	v_fma_f32 v214, s99, v149, v214
	v_readlane_b32 s31, v150, 63
	v_fma_f32 v201, s100, v151, v201
	v_readlane_b32 s42, v152, 60
	v_fma_f32 v203, s101, v151, v203
	v_readlane_b32 s43, v152, 61
	v_fma_f32 v205, s30, v151, v205
	v_readlane_b32 s98, v152, 62
	v_fma_f32 v214, s31, v151, v214
	v_readlane_b32 s99, v152, 63
	v_fma_f32 v201, s42, v153, v201
	v_readlane_b32 s100, v154, 60
	v_fma_f32 v203, s43, v153, v203
	v_readlane_b32 s101, v154, 61
	v_fma_f32 v205, s98, v153, v205
	v_readlane_b32 s30, v154, 62
	v_fma_f32 v214, s99, v153, v214
	v_readlane_b32 s31, v154, 63
	v_fma_f32 v201, s100, v155, v201
	v_readlane_b32 s42, v156, 60
	v_fma_f32 v203, s101, v155, v203
	v_readlane_b32 s43, v156, 61
	v_fma_f32 v205, s30, v155, v205
	v_readlane_b32 s98, v156, 62
	v_fma_f32 v214, s31, v155, v214
	v_readlane_b32 s99, v156, 63
	v_fma_f32 v201, s42, v157, v201
	v_readlane_b32 s100, v158, 60
	v_fma_f32 v203, s43, v157, v203
	v_readlane_b32 s101, v158, 61
	v_fma_f32 v205, s98, v157, v205
	v_readlane_b32 s30, v158, 62
	v_fma_f32 v214, s99, v157, v214
	v_readlane_b32 s31, v158, 63
	v_fma_f32 v201, s100, v159, v201
	v_readlane_b32 s42, v160, 60
	v_fma_f32 v203, s101, v159, v203
	v_readlane_b32 s43, v160, 61
	v_fma_f32 v205, s30, v159, v205
	v_readlane_b32 s98, v160, 62
	v_fma_f32 v214, s31, v159, v214
	v_readlane_b32 s99, v160, 63
	v_fma_f32 v201, s42, v161, v201
	v_readlane_b32 s100, v162, 60
	v_fma_f32 v203, s43, v161, v203
	v_readlane_b32 s101, v162, 61
	v_fma_f32 v205, s98, v161, v205
	v_readlane_b32 s30, v162, 62
	v_fma_f32 v214, s99, v161, v214
	v_readlane_b32 s31, v162, 63
	v_fma_f32 v201, s100, v163, v201
	v_readlane_b32 s42, v164, 60
	v_fma_f32 v203, s101, v163, v203
	v_readlane_b32 s43, v164, 61
	v_fma_f32 v205, s30, v163, v205
	v_readlane_b32 s98, v164, 62
	v_fma_f32 v214, s31, v163, v214
	v_readlane_b32 s99, v164, 63
	v_fma_f32 v201, s42, v165, v201
	v_readlane_b32 s100, v166, 60
	v_fma_f32 v203, s43, v165, v203
	v_readlane_b32 s101, v166, 61
	v_fma_f32 v205, s98, v165, v205
	v_readlane_b32 s30, v166, 62
	v_fma_f32 v214, s99, v165, v214
	v_readlane_b32 s31, v166, 63
	v_fma_f32 v201, s100, v167, v201
	v_readlane_b32 s42, v168, 60
	v_fma_f32 v203, s101, v167, v203
	v_readlane_b32 s43, v168, 61
	v_fma_f32 v205, s30, v167, v205
	v_readlane_b32 s98, v168, 62
	v_fma_f32 v214, s31, v167, v214
	v_readlane_b32 s99, v168, 63
	v_fma_f32 v201, s42, v169, v201
	v_readlane_b32 s100, v170, 60
	v_fma_f32 v203, s43, v169, v203
	v_readlane_b32 s101, v170, 61
	v_fma_f32 v205, s98, v169, v205
	v_readlane_b32 s30, v170, 62
	v_fma_f32 v214, s99, v169, v214
	v_readlane_b32 s31, v170, 63
	v_fma_f32 v201, s100, v171, v201
	v_readlane_b32 s42, v172, 60
	v_fma_f32 v203, s101, v171, v203
	v_readlane_b32 s43, v172, 61
	v_fma_f32 v205, s30, v171, v205
	v_readlane_b32 s98, v172, 62
	v_fma_f32 v214, s31, v171, v214
	v_readlane_b32 s99, v172, 63
	v_fma_f32 v201, s42, v173, v201
	v_readlane_b32 s100, v174, 60
	v_fma_f32 v203, s43, v173, v203
	v_readlane_b32 s101, v174, 61
	v_fma_f32 v205, s98, v173, v205
	v_readlane_b32 s30, v174, 62
	v_fma_f32 v214, s99, v173, v214
	v_readlane_b32 s31, v174, 63
	v_fma_f32 v201, s100, v175, v201
	v_readlane_b32 s42, v176, 60
	v_fma_f32 v203, s101, v175, v203
	v_readlane_b32 s43, v176, 61
	v_fma_f32 v205, s30, v175, v205
	v_readlane_b32 s98, v176, 62
	v_fma_f32 v214, s31, v175, v214
	v_readlane_b32 s99, v176, 63
	v_fma_f32 v201, s42, v177, v201
	v_readlane_b32 s100, v178, 60
	v_fma_f32 v203, s43, v177, v203
	v_readlane_b32 s101, v178, 61
	v_fma_f32 v205, s98, v177, v205
	v_readlane_b32 s30, v178, 62
	v_fma_f32 v214, s99, v177, v214
	v_readlane_b32 s31, v178, 63
	v_fma_f32 v201, s100, v179, v201
	v_readlane_b32 s42, v180, 60
	v_fma_f32 v203, s101, v179, v203
	v_readlane_b32 s43, v180, 61
	v_fma_f32 v205, s30, v179, v205
	v_readlane_b32 s98, v180, 62
	v_fma_f32 v214, s31, v179, v214
	v_readlane_b32 s99, v180, 63
	v_fma_f32 v201, s42, v181, v201
	v_readlane_b32 s100, v182, 60
	v_fma_f32 v203, s43, v181, v203
	v_readlane_b32 s101, v182, 61
	v_fma_f32 v205, s98, v181, v205
	v_readlane_b32 s30, v182, 62
	v_fma_f32 v214, s99, v181, v214
	v_readlane_b32 s31, v182, 63
	v_fma_f32 v201, s100, v183, v201
	v_readlane_b32 s42, v184, 60
	v_fma_f32 v203, s101, v183, v203
	v_readlane_b32 s43, v184, 61
	v_fma_f32 v205, s30, v183, v205
	v_readlane_b32 s98, v184, 62
	v_fma_f32 v214, s31, v183, v214
	v_readlane_b32 s99, v184, 63
	v_fma_f32 v201, s42, v185, v201
	v_readlane_b32 s100, v186, 60
	v_fma_f32 v203, s43, v185, v203
	v_readlane_b32 s101, v186, 61
	v_fma_f32 v205, s98, v185, v205
	v_readlane_b32 s30, v186, 62
	v_fma_f32 v214, s99, v185, v214
	v_readlane_b32 s31, v186, 63
	v_fma_f32 v201, s100, v187, v201
	v_readlane_b32 s42, v188, 60
	v_fma_f32 v203, s101, v187, v203
	v_readlane_b32 s43, v188, 61
	v_fma_f32 v205, s30, v187, v205
	v_readlane_b32 s98, v188, 62
	v_fma_f32 v214, s31, v187, v214
	v_readlane_b32 s99, v188, 63
	v_fma_f32 v201, s42, v189, v201
	v_readlane_b32 s100, v190, 60
	v_fma_f32 v203, s43, v189, v203
	v_readlane_b32 s101, v190, 61
	v_fma_f32 v205, s98, v189, v205
	v_readlane_b32 s30, v190, 62
	v_fma_f32 v214, s99, v189, v214
	v_readlane_b32 s31, v190, 63
	v_fma_f32 v201, s100, v191, v201
	v_readlane_b32 s42, v192, 60
	v_fma_f32 v203, s101, v191, v203
	v_readlane_b32 s43, v192, 61
	v_fma_f32 v205, s30, v191, v205
	v_readlane_b32 s98, v192, 62
	v_fma_f32 v214, s31, v191, v214
	v_readlane_b32 s99, v192, 63
	v_fma_f32 v201, s42, v193, v201
	v_readlane_b32 s100, v194, 60
	v_fma_f32 v203, s43, v193, v203
	v_readlane_b32 s101, v194, 61
	v_fma_f32 v205, s98, v193, v205
	v_readlane_b32 s30, v194, 62
	v_fma_f32 v214, s99, v193, v214
	v_readlane_b32 s31, v194, 63
	v_fma_f32 v201, s100, v195, v201
	v_readlane_b32 s42, v196, 60
	v_fma_f32 v203, s101, v195, v203
	v_readlane_b32 s43, v196, 61
	v_fma_f32 v205, s30, v195, v205
	v_readlane_b32 s98, v196, 62
	v_fma_f32 v214, s31, v195, v214
	v_readlane_b32 s99, v196, 63
	v_fma_f32 v201, s42, v197, v201
	v_readlane_b32 s100, v198, 60
	v_fma_f32 v203, s43, v197, v203
	v_readlane_b32 s101, v198, 61
	v_fma_f32 v205, s98, v197, v205
	v_readlane_b32 s30, v198, 62
	v_fma_f32 v214, s99, v197, v214
	v_readlane_b32 s31, v198, 63
	v_fma_f32 v201, s100, v199, v201
	v_readlane_b32 s42, v200, 61
	v_fma_f32 v203, s101, v199, v203
	v_readlane_b32 s43, v200, 62
	v_fma_f32 v205, s30, v199, v205
	v_readlane_b32 s98, v200, 63
	v_fma_f32 v214, s31, v199, v214
	v_readlane_b32 s99, v202, 62
	v_fma_f32 v203, s42, v201, v203
	v_readlane_b32 s100, v202, 63
	v_fma_f32 v205, s43, v201, v205
	v_readlane_b32 s101, v204, 63
	v_fma_f32 v214, s98, v201, v214
	v_fma_f32 v205, s99, v203, v205
	v_fma_f32 v214, s100, v203, v214
	v_fma_f32 v214, s101, v205, v214
	ds_write_b32 v3, v21
	ds_write_b32 v3, v23 offset:260
	ds_write_b32 v3, v25 offset:520
	ds_write_b32 v3, v27 offset:780
	ds_write_b32 v3, v29 offset:1040
	ds_write_b32 v3, v31 offset:1300
	ds_write_b32 v3, v33 offset:1560
	ds_write_b32 v3, v35 offset:1820
	s_waitcnt lgkmcnt(8)
	ds_write_b32 v3, v37 offset:2080
	ds_write_b32 v3, v39 offset:2340
	ds_write_b32 v3, v41 offset:2600
	ds_write_b32 v3, v43 offset:2860
	ds_write_b32 v3, v45 offset:3120
	ds_write_b32 v3, v47 offset:3380
	ds_write_b32 v3, v49 offset:3640
	ds_write_b32 v3, v51 offset:3900
	s_waitcnt lgkmcnt(8)
	ds_write_b32 v3, v53 offset:4160
	ds_write_b32 v3, v55 offset:4420
	ds_write_b32 v3, v57 offset:4680
	ds_write_b32 v3, v119 offset:4940
	ds_write_b32 v3, v121 offset:5200
	ds_write_b32 v3, v123 offset:5460
	ds_write_b32 v3, v125 offset:5720
	ds_write_b32 v3, v127 offset:5980
	s_waitcnt lgkmcnt(8)
	ds_write_b32 v3, v129 offset:6240
	ds_write_b32 v3, v131 offset:6500
	ds_write_b32 v3, v133 offset:6760
	ds_write_b32 v3, v135 offset:7020
	ds_write_b32 v3, v137 offset:7280
	ds_write_b32 v3, v139 offset:7540
	ds_write_b32 v3, v141 offset:7800
	ds_write_b32 v3, v143 offset:8060
	s_waitcnt lgkmcnt(8)
	ds_write_b32 v3, v145 offset:8320
	ds_write_b32 v3, v147 offset:8580
	ds_write_b32 v3, v149 offset:8840
	ds_write_b32 v3, v151 offset:9100
	ds_write_b32 v3, v153 offset:9360
	ds_write_b32 v3, v155 offset:9620
	ds_write_b32 v3, v157 offset:9880
	ds_write_b32 v3, v159 offset:10140
	s_waitcnt lgkmcnt(8)
	ds_write_b32 v3, v161 offset:10400
	ds_write_b32 v3, v163 offset:10660
	ds_write_b32 v3, v165 offset:10920
	ds_write_b32 v3, v167 offset:11180
	ds_write_b32 v3, v169 offset:11440
	ds_write_b32 v3, v171 offset:11700
	ds_write_b32 v3, v173 offset:11960
	ds_write_b32 v3, v175 offset:12220
	s_waitcnt lgkmcnt(8)
	ds_write_b32 v3, v177 offset:12480
	ds_write_b32 v3, v179 offset:12740
	ds_write_b32 v3, v181 offset:13000
	ds_write_b32 v3, v183 offset:13260
	ds_write_b32 v3, v185 offset:13520
	ds_write_b32 v3, v187 offset:13780
	ds_write_b32 v3, v189 offset:14040
	ds_write_b32 v3, v191 offset:14300
	s_waitcnt lgkmcnt(8)
	ds_write_b32 v3, v193 offset:14560
	ds_write_b32 v3, v195 offset:14820
	ds_write_b32 v3, v197 offset:15080
	ds_write_b32 v3, v199 offset:15340
	ds_write_b32 v3, v201 offset:15600
	ds_write_b32 v3, v203 offset:15860
	ds_write_b32 v3, v205 offset:16120
	ds_write_b32 v3, v214 offset:16380
	s_mov_b32 s26, 60
	s_waitcnt lgkmcnt(0)
	ds_read2_b32 v[0:1], v247 offset1:1
	s_waitcnt lgkmcnt(0)
	v_cvt_pk_bf16_f32 v214, v0, v1
	ds_read2_b32 v[0:1], v247 offset0:2 offset1:3
	s_waitcnt lgkmcnt(0)
	v_cvt_pk_bf16_f32 v215, v0, v1
	ds_read2_b32 v[0:1], v247 offset0:4 offset1:5
	s_waitcnt lgkmcnt(0)
	v_cvt_pk_bf16_f32 v216, v0, v1
	ds_read2_b32 v[0:1], v247 offset0:6 offset1:7
	s_waitcnt lgkmcnt(0)
	v_cvt_pk_bf16_f32 v217, v0, v1
	ds_read2_b32 v[0:1], v93 offset1:1
	global_store_dwordx4 v[208:209], v[214:217], off
	v_lshl_add_u64 v[208:209], v[206:207], 0, v[58:59]
	s_mov_b64 s[30:31], -1
	s_waitcnt lgkmcnt(0)
	v_cvt_pk_bf16_f32 v214, v0, v1
	ds_read2_b32 v[0:1], v95 offset1:1
	s_waitcnt lgkmcnt(0)
	v_cvt_pk_bf16_f32 v215, v0, v1
	ds_read2_b32 v[0:1], v97 offset1:1
	s_waitcnt lgkmcnt(0)
	v_cvt_pk_bf16_f32 v216, v0, v1
	ds_read2_b32 v[0:1], v99 offset1:1
	s_waitcnt lgkmcnt(0)
	v_cvt_pk_bf16_f32 v217, v0, v1
	global_store_dwordx4 v[208:209], v[214:217], off
	ds_read2_b32 v[0:1], v101 offset1:1
	s_mov_b64 s[26:27], 0
	s_waitcnt lgkmcnt(0)
	v_cvt_pk_bf16_f32 v214, v0, v1
	ds_read2_b32 v[0:1], v103 offset1:1
	s_waitcnt lgkmcnt(0)
	v_cvt_pk_bf16_f32 v215, v0, v1
	ds_read2_b32 v[0:1], v105 offset1:1
	s_waitcnt lgkmcnt(0)
	v_cvt_pk_bf16_f32 v216, v0, v1
	ds_read2_b32 v[0:1], v107 offset1:1
	v_mov_b32_e32 v103, v59
	s_waitcnt lgkmcnt(0)
	v_cvt_pk_bf16_f32 v217, v0, v1
	ds_read2_b32 v[0:1], v109 offset1:1
	v_lshl_add_u64 v[208:209], v[206:207], 0, v[102:103]
	global_store_dwordx4 v[208:209], v[214:217], off
	v_mov_b32_e32 v105, v59
	v_mov_b32_e32 v107, v59
	s_waitcnt lgkmcnt(0)
	v_cvt_pk_bf16_f32 v214, v0, v1
	ds_read2_b32 v[0:1], v16 offset1:1
	s_waitcnt lgkmcnt(0)
	v_cvt_pk_bf16_f32 v215, v0, v1
	ds_read2_b32 v[0:1], v17 offset1:1
	v_lshl_add_u64 v[16:17], v[206:207], 0, v[104:105]
	s_waitcnt lgkmcnt(0)
	v_cvt_pk_bf16_f32 v216, v0, v1
	ds_read2_b32 v[0:1], v18 offset1:1
	s_waitcnt lgkmcnt(0)
	v_cvt_pk_bf16_f32 v217, v0, v1
	global_store_dwordx4 v[16:17], v[214:217], off
	ds_read2_b32 v[0:1], v19 offset1:1
	s_waitcnt lgkmcnt(0)
	v_cvt_pk_bf16_f32 v16, v0, v1
	ds_read2_b32 v[0:1], v111 offset1:1
	s_waitcnt lgkmcnt(0)
	v_cvt_pk_bf16_f32 v17, v0, v1
	ds_read2_b32 v[0:1], v113 offset1:1
	s_waitcnt lgkmcnt(0)
	v_cvt_pk_bf16_f32 v18, v0, v1
	ds_read2_b32 v[0:1], v115 offset1:1
	s_waitcnt lgkmcnt(0)
	v_cvt_pk_bf16_f32 v19, v0, v1
	ds_read2_b32 v[0:1], v15 offset1:1
	v_lshl_add_u64 v[208:209], v[206:207], 0, v[106:107]
	global_store_dwordx4 v[208:209], v[16:19], off
	v_mov_b32_e32 v109, v59
	v_mov_b32_e32 v111, v59
	s_waitcnt lgkmcnt(0)
	v_cvt_pk_bf16_f32 v16, v0, v1
	ds_read2_b32 v[0:1], v12 offset1:1
	s_waitcnt lgkmcnt(0)
	v_cvt_pk_bf16_f32 v17, v0, v1
	ds_read2_b32 v[0:1], v13 offset1:1
	v_lshl_add_u64 v[12:13], v[206:207], 0, v[108:109]
	s_waitcnt lgkmcnt(0)
	v_cvt_pk_bf16_f32 v18, v0, v1
	ds_read2_b32 v[0:1], v14 offset1:1
	s_waitcnt lgkmcnt(0)
	v_cvt_pk_bf16_f32 v19, v0, v1
	global_store_dwordx4 v[12:13], v[16:19], off
	ds_read2_b32 v[0:1], v8 offset1:1
	s_waitcnt lgkmcnt(0)
	v_cvt_pk_bf16_f32 v8, v0, v1
	ds_read2_b32 v[0:1], v9 offset1:1
	s_waitcnt lgkmcnt(0)
	v_cvt_pk_bf16_f32 v9, v0, v1
	ds_read2_b32 v[0:1], v10 offset1:1
	s_waitcnt lgkmcnt(0)
	v_cvt_pk_bf16_f32 v10, v0, v1
	ds_read2_b32 v[0:1], v11 offset1:1
	s_waitcnt lgkmcnt(0)
	v_cvt_pk_bf16_f32 v11, v0, v1
	ds_read2_b32 v[0:1], v6 offset1:1
	v_lshl_add_u64 v[6:7], v[206:207], 0, v[110:111]
	global_store_dwordx4 v[6:7], v[8:11], off
	s_waitcnt lgkmcnt(0)
	v_cvt_pk_bf16_f32 v6, v0, v1
	ds_read2_b32 v[0:1], v4 offset1:1
	s_waitcnt lgkmcnt(0)
	v_cvt_pk_bf16_f32 v7, v0, v1
	ds_read2_b32 v[0:1], v5 offset1:1
	v_mov_b32_e32 v113, v59
	s_waitcnt lgkmcnt(0)
	v_cvt_pk_bf16_f32 v8, v0, v1
	ds_read2_b32 v[0:1], v2 offset1:1
	v_lshl_add_u64 v[2:3], v[206:207], 0, v[112:113]
	s_waitcnt lgkmcnt(0)
	v_cvt_pk_bf16_f32 v9, v0, v1
	global_store_dwordx4 v[2:3], v[6:9], off
	s_waitcnt lgkmcnt(0)
	s_and_b64 vcc, exec, s[28:29]
	s_cbranch_vccz .LBB0_360
	s_add_u32 s0, s24, s0
	s_addc_u32 s1, s33, s1
	v_mov_b32_e32 v115, v59
	v_lshl_add_u64 v[0:1], s[0:1], 0, v[114:115]
	v_mov_b32_e32 v93, v59
	v_lshl_add_u64 v[34:35], v[0:1], 0, v[92:93]
	global_load_dwordx4 v[2:5], v[34:35], off
	global_load_dwordx4 v[6:9], v[34:35], off offset:1024
	global_load_dwordx4 v[10:13], v[34:35], off offset:2048
	global_load_dwordx4 v[14:17], v[34:35], off offset:3072
	v_mov_b32_e32 v95, v59
	v_mov_b32_e32 v97, v59
	v_mov_b32_e32 v99, v59
	v_mov_b32_e32 v101, v59
	v_lshl_add_u64 v[18:19], v[0:1], 0, v[94:95]
	v_lshl_add_u64 v[22:23], v[0:1], 0, v[96:97]
	v_lshl_add_u64 v[26:27], v[0:1], 0, v[98:99]
	v_lshl_add_u64 v[30:31], v[0:1], 0, v[100:101]
	global_load_dwordx4 v[18:21], v[18:19], off
	s_nop 0
	global_load_dwordx4 v[22:25], v[22:23], off
	s_nop 0
	global_load_dwordx4 v[26:29], v[26:27], off
	s_nop 0
	global_load_dwordx4 v[30:33], v[30:31], off
	ds_bpermute_b32 v38, v232, v89
	ds_bpermute_b32 v39, v233, v89
	ds_bpermute_b32 v40, v234, v89
	ds_bpermute_b32 v41, v235, v89
	v_lshl_add_u64 v[36:37], v[0:1], 0, v[58:59]
	s_add_i32 s2, s2, s86
	v_lshl_add_u64 v[60:61], v[60:61], 0, s[16:17]
	v_lshl_add_u64 v[62:63], v[62:63], 0, s[16:17]
	v_lshl_add_u64 v[64:65], v[64:65], 0, s[16:17]
	v_lshl_add_u64 v[66:67], v[66:67], 0, s[16:17]
	v_lshl_add_u64 v[68:69], v[68:69], 0, s[16:17]
	v_lshl_add_u64 v[70:71], v[70:71], 0, s[16:17]
	v_lshl_add_u64 v[72:73], v[72:73], 0, s[16:17]
	v_lshl_add_u64 v[74:75], v[74:75], 0, s[16:17]
	v_lshl_add_u64 v[76:77], v[76:77], 0, s[16:17]
	v_lshl_add_u64 v[78:79], v[78:79], 0, s[16:17]
	v_lshl_add_u64 v[80:81], v[80:81], 0, s[16:17]
	v_lshl_add_u64 v[82:83], v[82:83], 0, s[16:17]
	v_lshl_add_u64 v[84:85], v[84:85], 0, s[16:17]
	s_cmpk_lt_i32 s2, 0x2000
	v_lshl_add_u64 v[86:87], v[86:87], 0, s[16:17]
	s_waitcnt vmcnt(7)
	v_lshlrev_b32_e32 v42, 16, v2
	v_and_b32_e32 v2, 0xffff0000, v2
	v_lshlrev_b32_e32 v43, 16, v3
	v_and_b32_e32 v3, 0xffff0000, v3
	v_lshlrev_b32_e32 v44, 16, v4
	v_and_b32_e32 v4, 0xffff0000, v4
	v_lshlrev_b32_e32 v45, 16, v5
	v_and_b32_e32 v5, 0xffff0000, v5
	s_waitcnt lgkmcnt(3)
	v_mul_f32_e32 v2, v2, v38
	v_mul_f32_e32 v3, v3, v38
	s_waitcnt vmcnt(6)
	v_lshlrev_b32_e32 v46, 16, v6
	v_and_b32_e32 v6, 0xffff0000, v6
	v_lshlrev_b32_e32 v47, 16, v7
	v_and_b32_e32 v7, 0xffff0000, v7
	v_mul_f32_e32 v42, v42, v38
	v_mul_f32_e32 v43, v43, v38
	v_mul_f32_e32 v4, v4, v38
	v_mul_f32_e32 v5, v5, v38
	v_cvt_pk_bf16_f32 v2, v42, v2
	v_cvt_pk_bf16_f32 v3, v43, v3
	v_lshlrev_b32_e32 v48, 16, v8
	v_and_b32_e32 v8, 0xffff0000, v8
	v_lshlrev_b32_e32 v49, 16, v9
	v_and_b32_e32 v9, 0xffff0000, v9
	s_waitcnt vmcnt(5)
	v_lshlrev_b32_e32 v50, 16, v10
	v_and_b32_e32 v10, 0xffff0000, v10
	v_lshlrev_b32_e32 v51, 16, v11
	v_and_b32_e32 v11, 0xffff0000, v11
	v_mul_f32_e32 v44, v44, v38
	v_mul_f32_e32 v45, v45, v38
	s_waitcnt lgkmcnt(2)
	v_mul_f32_e32 v38, v46, v39
	v_mul_f32_e32 v6, v6, v39
	v_mul_f32_e32 v46, v47, v39
	v_mul_f32_e32 v7, v7, v39
	v_cvt_pk_bf16_f32 v4, v44, v4
	v_cvt_pk_bf16_f32 v5, v45, v5
	global_store_dwordx4 v[34:35], v[2:5], off
	v_lshlrev_b32_e32 v52, 16, v12
	v_and_b32_e32 v12, 0xffff0000, v12
	v_cvt_pk_bf16_f32 v2, v38, v6
	v_cvt_pk_bf16_f32 v3, v46, v7
	v_lshlrev_b32_e32 v53, 16, v13
	v_and_b32_e32 v13, 0xffff0000, v13
	v_mul_f32_e32 v47, v48, v39
	v_mul_f32_e32 v8, v8, v39
	v_mul_f32_e32 v48, v49, v39
	v_mul_f32_e32 v9, v9, v39
	s_waitcnt lgkmcnt(1)
	v_mul_f32_e32 v39, v50, v40
	v_mul_f32_e32 v10, v10, v40
	v_mul_f32_e32 v49, v51, v40
	v_mul_f32_e32 v11, v11, v40
	v_cvt_pk_bf16_f32 v4, v47, v8
	v_cvt_pk_bf16_f32 v5, v48, v9
	global_store_dwordx4 v[36:37], v[2:5], off
	v_lshl_add_u64 v[6:7], v[0:1], 0, v[102:103]
	v_mul_f32_e32 v50, v52, v40
	v_cvt_pk_bf16_f32 v2, v39, v10
	v_cvt_pk_bf16_f32 v3, v49, v11
	v_mul_f32_e32 v12, v12, v40
	v_mul_f32_e32 v51, v53, v40
	v_mul_f32_e32 v13, v13, v40
	v_cvt_pk_bf16_f32 v4, v50, v12
	v_cvt_pk_bf16_f32 v5, v51, v13
	global_store_dwordx4 v[6:7], v[2:5], off
	ds_bpermute_b32 v8, v236, v89
	s_waitcnt vmcnt(7)
	v_and_b32_e32 v6, 0xffff0000, v17
	v_lshlrev_b32_e32 v2, 16, v14
	v_and_b32_e32 v3, 0xffff0000, v14
	s_waitcnt lgkmcnt(1)
	v_mul_f32_e32 v2, v2, v41
	v_mul_f32_e32 v3, v3, v41
	v_cvt_pk_bf16_f32 v2, v2, v3
	v_lshlrev_b32_e32 v3, 16, v15
	v_and_b32_e32 v4, 0xffff0000, v15
	v_mul_f32_e32 v3, v3, v41
	v_mul_f32_e32 v4, v4, v41
	v_cvt_pk_bf16_f32 v3, v3, v4
	v_lshlrev_b32_e32 v4, 16, v16
	v_and_b32_e32 v5, 0xffff0000, v16
	v_mul_f32_e32 v4, v4, v41
	v_mul_f32_e32 v5, v5, v41
	v_cvt_pk_bf16_f32 v4, v4, v5
	v_lshlrev_b32_e32 v5, 16, v17
	v_mul_f32_e32 v5, v5, v41
	v_mul_f32_e32 v6, v6, v41
	v_cvt_pk_bf16_f32 v5, v5, v6
	v_lshl_add_u64 v[6:7], v[0:1], 0, v[104:105]
	global_store_dwordx4 v[6:7], v[2:5], off
	s_waitcnt vmcnt(7)
	v_and_b32_e32 v6, 0xffff0000, v21
	s_waitcnt lgkmcnt(0)
	v_mul_f32_e32 v6, v6, v8
	v_lshlrev_b32_e32 v2, 16, v18
	v_and_b32_e32 v3, 0xffff0000, v18
	v_mul_f32_e32 v2, v2, v8
	v_mul_f32_e32 v3, v3, v8
	v_cvt_pk_bf16_f32 v2, v2, v3
	v_lshlrev_b32_e32 v3, 16, v19
	v_and_b32_e32 v4, 0xffff0000, v19
	v_mul_f32_e32 v3, v3, v8
	v_mul_f32_e32 v4, v4, v8
	v_cvt_pk_bf16_f32 v3, v3, v4
	v_lshlrev_b32_e32 v4, 16, v20
	v_and_b32_e32 v5, 0xffff0000, v20
	v_mul_f32_e32 v4, v4, v8
	v_mul_f32_e32 v5, v5, v8
	v_cvt_pk_bf16_f32 v4, v4, v5
	v_lshlrev_b32_e32 v5, 16, v21
	v_mul_f32_e32 v5, v5, v8
	ds_bpermute_b32 v8, v237, v89
	v_cvt_pk_bf16_f32 v5, v5, v6
	v_lshl_add_u64 v[6:7], v[0:1], 0, v[106:107]
	global_store_dwordx4 v[6:7], v[2:5], off
	s_waitcnt vmcnt(7)
	v_and_b32_e32 v6, 0xffff0000, v25
	s_waitcnt lgkmcnt(0)
	v_mul_f32_e32 v6, v6, v8
	v_lshlrev_b32_e32 v2, 16, v22
	v_and_b32_e32 v3, 0xffff0000, v22
	v_mul_f32_e32 v2, v2, v8
	v_mul_f32_e32 v3, v3, v8
	v_cvt_pk_bf16_f32 v2, v2, v3
	v_lshlrev_b32_e32 v3, 16, v23
	v_and_b32_e32 v4, 0xffff0000, v23
	v_mul_f32_e32 v3, v3, v8
	v_mul_f32_e32 v4, v4, v8
	v_cvt_pk_bf16_f32 v3, v3, v4
	v_lshlrev_b32_e32 v4, 16, v24
	v_and_b32_e32 v5, 0xffff0000, v24
	v_mul_f32_e32 v4, v4, v8
	v_mul_f32_e32 v5, v5, v8
	v_cvt_pk_bf16_f32 v4, v4, v5
	v_lshlrev_b32_e32 v5, 16, v25
	v_mul_f32_e32 v5, v5, v8
	ds_bpermute_b32 v8, v238, v89
	v_cvt_pk_bf16_f32 v5, v5, v6
	v_lshl_add_u64 v[6:7], v[0:1], 0, v[108:109]
	global_store_dwordx4 v[6:7], v[2:5], off
	s_waitcnt vmcnt(7)
	v_and_b32_e32 v6, 0xffff0000, v29
	s_waitcnt lgkmcnt(0)
	v_mul_f32_e32 v6, v6, v8
	v_lshlrev_b32_e32 v2, 16, v26
	v_and_b32_e32 v3, 0xffff0000, v26
	v_mul_f32_e32 v2, v2, v8
	v_mul_f32_e32 v3, v3, v8
	v_cvt_pk_bf16_f32 v2, v2, v3
	v_lshlrev_b32_e32 v3, 16, v27
	v_and_b32_e32 v4, 0xffff0000, v27
	v_mul_f32_e32 v3, v3, v8
	v_mul_f32_e32 v4, v4, v8
	v_cvt_pk_bf16_f32 v3, v3, v4
	v_lshlrev_b32_e32 v4, 16, v28
	v_and_b32_e32 v5, 0xffff0000, v28
	v_mul_f32_e32 v4, v4, v8
	v_mul_f32_e32 v5, v5, v8
	v_cvt_pk_bf16_f32 v4, v4, v5
	v_lshlrev_b32_e32 v5, 16, v29
	v_mul_f32_e32 v5, v5, v8
	ds_bpermute_b32 v8, v239, v89
	v_cvt_pk_bf16_f32 v5, v5, v6
	v_lshl_add_u64 v[6:7], v[0:1], 0, v[110:111]
	global_store_dwordx4 v[6:7], v[2:5], off
	s_waitcnt vmcnt(7)
	v_and_b32_e32 v6, 0xffff0000, v33
	v_lshl_add_u64 v[0:1], v[0:1], 0, v[112:113]
	v_lshlrev_b32_e32 v2, 16, v30
	v_and_b32_e32 v3, 0xffff0000, v30
	s_waitcnt lgkmcnt(0)
	v_mul_f32_e32 v2, v2, v8
	v_mul_f32_e32 v3, v3, v8
	v_cvt_pk_bf16_f32 v2, v2, v3
	v_lshlrev_b32_e32 v3, 16, v31
	v_and_b32_e32 v4, 0xffff0000, v31
	v_mul_f32_e32 v3, v3, v8
	v_mul_f32_e32 v4, v4, v8
	v_cvt_pk_bf16_f32 v3, v3, v4
	v_lshlrev_b32_e32 v4, 16, v32
	v_and_b32_e32 v5, 0xffff0000, v32
	v_mul_f32_e32 v4, v4, v8
	v_mul_f32_e32 v5, v5, v8
	v_cvt_pk_bf16_f32 v4, v4, v5
	v_lshlrev_b32_e32 v5, 16, v33
	v_mul_f32_e32 v5, v5, v8
	v_mul_f32_e32 v6, v6, v8
	v_cvt_pk_bf16_f32 v5, v5, v6
	global_store_dwordx4 v[0:1], v[2:5], off
	s_waitcnt lgkmcnt(0)
	s_cbranch_scc1 .LBB0_346
	v_mbcnt_lo_u32_b32 v230, -1, 0

.LBB0_653:
	s_ashr_i32 s13, s12, 31
	v_cmp_lt_i64_e32 vcc, s[14:15], v[140:141]
	s_lshl_b64 s[14:15], s[12:13], 19
	s_add_u32 s14, s90, s14
	s_addc_u32 s15, s91, s15
	s_and_b64 s[16:17], vcc, exec
	s_cselect_b32 s13, s15, s23
	s_cselect_b32 s19, s14, s22
	s_ashr_i32 s3, s2, 31
	s_lshl_b64 s[16:17], s[2:3], 19
	v_readlane_b32 s26, v253, 55
	v_readlane_b32 s27, v253, 56
	s_add_u32 s16, s26, s16
	s_addc_u32 s17, s27, s17
	s_and_b64 s[26:27], vcc, exec
	s_cselect_b32 s3, s17, s25
	s_cselect_b32 s42, s16, s24
	s_add_u32 s22, s22, 0x40080
	s_addc_u32 s23, s23, 0
	s_add_u32 s43, s24, 0x100
	v_mov_b32_e32 v0, 0
	s_addc_u32 s48, s25, 0
	s_mov_b32 s49, -2
	s_waitcnt lgkmcnt(0)
	v_mov_b32_e32 v1, v0
	v_mov_b32_e32 v2, v0
	v_mov_b32_e32 v3, v0
	v_mov_b32_e32 v4, v0
	v_mov_b32_e32 v5, v0
	v_mov_b32_e32 v6, v0
	v_mov_b32_e32 v7, v0
	v_mov_b32_e32 v12, v0
	v_mov_b32_e32 v13, v0
	v_mov_b32_e32 v14, v0
	v_mov_b32_e32 v15, v0
	v_mov_b32_e32 v20, v0
	v_mov_b32_e32 v21, v0
	v_mov_b32_e32 v22, v0
	v_mov_b32_e32 v23, v0
	v_mov_b32_e32 v28, v0
	v_mov_b32_e32 v29, v0
	v_mov_b32_e32 v30, v0
	v_mov_b32_e32 v31, v0
	v_mov_b32_e32 v36, v0
	v_mov_b32_e32 v37, v0
	v_mov_b32_e32 v38, v0
	v_mov_b32_e32 v39, v0
	v_mov_b32_e32 v40, v0
	v_mov_b32_e32 v41, v0
	v_mov_b32_e32 v42, v0
	v_mov_b32_e32 v43, v0
	v_mov_b32_e32 v44, v0
	v_mov_b32_e32 v45, v0
	v_mov_b32_e32 v46, v0
	v_mov_b32_e32 v47, v0
	v_mov_b32_e32 v8, v0
	v_mov_b32_e32 v9, v0
	v_mov_b32_e32 v10, v0
	v_mov_b32_e32 v11, v0
	v_mov_b32_e32 v16, v0
	v_mov_b32_e32 v17, v0
	v_mov_b32_e32 v18, v0
	v_mov_b32_e32 v19, v0
	v_mov_b32_e32 v24, v0
	v_mov_b32_e32 v25, v0
	v_mov_b32_e32 v26, v0
	v_mov_b32_e32 v27, v0
	v_mov_b32_e32 v32, v0
	v_mov_b32_e32 v33, v0
	v_mov_b32_e32 v34, v0
	v_mov_b32_e32 v35, v0
	v_mov_b32_e32 v48, v0
	v_mov_b32_e32 v49, v0
	v_mov_b32_e32 v50, v0
	v_mov_b32_e32 v51, v0
	v_mov_b32_e32 v52, v0
	v_mov_b32_e32 v53, v0
	v_mov_b32_e32 v54, v0
	v_mov_b32_e32 v55, v0
	v_mov_b32_e32 v56, v0
	v_mov_b32_e32 v57, v0
	v_mov_b32_e32 v58, v0
	v_mov_b32_e32 v59, v0
	v_mov_b32_e32 v60, v0
	v_mov_b32_e32 v61, v0
	v_mov_b32_e32 v62, v0
	v_mov_b32_e32 v63, v0
	v_mov_b32_e32 v64, v0
	v_mov_b32_e32 v65, v0
	v_mov_b32_e32 v66, v0
	v_mov_b32_e32 v67, v0
	v_mov_b32_e32 v68, v0
	v_mov_b32_e32 v69, v0
	v_mov_b32_e32 v70, v0
	v_mov_b32_e32 v71, v0
	v_mov_b32_e32 v76, v0
	v_mov_b32_e32 v77, v0
	v_mov_b32_e32 v78, v0
	v_mov_b32_e32 v79, v0
	v_mov_b32_e32 v84, v0
	v_mov_b32_e32 v85, v0
	v_mov_b32_e32 v86, v0
	v_mov_b32_e32 v87, v0
	v_mov_b32_e32 v92, v0
	v_mov_b32_e32 v93, v0
	v_mov_b32_e32 v94, v0
	v_mov_b32_e32 v95, v0
	v_mov_b32_e32 v100, v0
	v_mov_b32_e32 v101, v0
	v_mov_b32_e32 v102, v0
	v_mov_b32_e32 v103, v0
	v_mov_b32_e32 v104, v0
	v_mov_b32_e32 v105, v0
	v_mov_b32_e32 v106, v0
	v_mov_b32_e32 v107, v0
	v_mov_b32_e32 v108, v0
	v_mov_b32_e32 v109, v0
	v_mov_b32_e32 v110, v0
	v_mov_b32_e32 v111, v0
	v_mov_b32_e32 v72, v0
	v_mov_b32_e32 v73, v0
	v_mov_b32_e32 v74, v0
	v_mov_b32_e32 v75, v0
	v_mov_b32_e32 v80, v0
	v_mov_b32_e32 v81, v0
	v_mov_b32_e32 v82, v0
	v_mov_b32_e32 v83, v0
	v_mov_b32_e32 v88, v0
	v_mov_b32_e32 v89, v0
	v_mov_b32_e32 v90, v0
	v_mov_b32_e32 v91, v0
	v_mov_b32_e32 v96, v0
	v_mov_b32_e32 v97, v0
	v_mov_b32_e32 v98, v0
	v_mov_b32_e32 v99, v0
	v_mov_b32_e32 v112, v0
	v_mov_b32_e32 v113, v0
	v_mov_b32_e32 v114, v0
	v_mov_b32_e32 v115, v0
	v_mov_b32_e32 v116, v0
	v_mov_b32_e32 v117, v0
	v_mov_b32_e32 v118, v0
	v_mov_b32_e32 v119, v0
	v_mov_b32_e32 v120, v0
	v_mov_b32_e32 v121, v0
	v_mov_b32_e32 v122, v0
	v_mov_b32_e32 v123, v0
	v_mov_b32_e32 v124, v0
	v_mov_b32_e32 v125, v0
	v_mov_b32_e32 v126, v0
	v_mov_b32_e32 v127, v0

.LBB0_711:
	s_ashr_i32 s21, s20, 31
	v_cmp_lt_i64_e32 vcc, s[22:23], v[140:141]
	s_lshl_b64 s[22:23], s[20:21], 19
	s_add_u32 s22, s10, s22
	s_addc_u32 s23, s11, s23
	s_and_b64 s[24:25], vcc, exec
	s_cselect_b32 s21, s23, s3
	s_cselect_b32 s52, s22, s2
	s_ashr_i32 s19, s18, 31
	s_lshl_b64 s[24:25], s[18:19], 19
	v_readlane_b32 s19, v253, 49
	s_add_u32 s24, s19, s24
	v_readlane_b32 s19, v253, 50
	s_addc_u32 s25, s19, s25
	s_and_b64 s[28:29], vcc, exec
	s_cselect_b32 s19, s25, s27
	s_cselect_b32 s53, s24, s26
	s_add_u32 s2, s2, 0x40080
	s_addc_u32 s3, s3, 0
	s_add_u32 s54, s26, 0x100
	v_mov_b32_e32 v0, 0
	s_addc_u32 s55, s27, 0
	s_mov_b32 s56, -2
	v_mov_b32_e32 v1, v0
	v_mov_b32_e32 v2, v0
	v_mov_b32_e32 v3, v0
	v_mov_b32_e32 v4, v0
	v_mov_b32_e32 v5, v0
	v_mov_b32_e32 v6, v0
	v_mov_b32_e32 v7, v0
	v_mov_b32_e32 v16, v0
	v_mov_b32_e32 v17, v0
	v_mov_b32_e32 v18, v0
	v_mov_b32_e32 v19, v0
	v_mov_b32_e32 v20, v0
	v_mov_b32_e32 v21, v0
	v_mov_b32_e32 v22, v0
	v_mov_b32_e32 v23, v0
	v_mov_b32_e32 v32, v0
	v_mov_b32_e32 v33, v0
	v_mov_b32_e32 v34, v0
	v_mov_b32_e32 v35, v0
	v_mov_b32_e32 v36, v0
	v_mov_b32_e32 v37, v0
	v_mov_b32_e32 v38, v0
	v_mov_b32_e32 v39, v0
	v_mov_b32_e32 v48, v0
	v_mov_b32_e32 v49, v0
	v_mov_b32_e32 v50, v0
	v_mov_b32_e32 v51, v0
	v_mov_b32_e32 v52, v0
	v_mov_b32_e32 v53, v0
	v_mov_b32_e32 v54, v0
	v_mov_b32_e32 v55, v0
	v_mov_b32_e32 v8, v0
	v_mov_b32_e32 v9, v0
	v_mov_b32_e32 v10, v0
	v_mov_b32_e32 v11, v0
	v_mov_b32_e32 v12, v0
	v_mov_b32_e32 v13, v0
	v_mov_b32_e32 v14, v0
	v_mov_b32_e32 v15, v0
	v_mov_b32_e32 v24, v0
	v_mov_b32_e32 v25, v0
	v_mov_b32_e32 v26, v0
	v_mov_b32_e32 v27, v0
	v_mov_b32_e32 v28, v0
	v_mov_b32_e32 v29, v0
	v_mov_b32_e32 v30, v0
	v_mov_b32_e32 v31, v0
	v_mov_b32_e32 v40, v0
	v_mov_b32_e32 v41, v0
	v_mov_b32_e32 v42, v0
	v_mov_b32_e32 v43, v0
	v_mov_b32_e32 v44, v0
	v_mov_b32_e32 v45, v0
	v_mov_b32_e32 v46, v0
	v_mov_b32_e32 v47, v0
	v_mov_b32_e32 v56, v0
	v_mov_b32_e32 v57, v0
	v_mov_b32_e32 v58, v0
	v_mov_b32_e32 v59, v0
	v_mov_b32_e32 v60, v0
	v_mov_b32_e32 v61, v0
	v_mov_b32_e32 v62, v0
	v_mov_b32_e32 v63, v0
	v_mov_b32_e32 v64, v0
	v_mov_b32_e32 v65, v0
	v_mov_b32_e32 v66, v0
	v_mov_b32_e32 v67, v0
	v_mov_b32_e32 v68, v0
	v_mov_b32_e32 v69, v0
	v_mov_b32_e32 v70, v0
	v_mov_b32_e32 v71, v0
	v_mov_b32_e32 v80, v0
	v_mov_b32_e32 v81, v0
	v_mov_b32_e32 v82, v0
	v_mov_b32_e32 v83, v0
	v_mov_b32_e32 v84, v0
	v_mov_b32_e32 v85, v0
	v_mov_b32_e32 v86, v0
	v_mov_b32_e32 v87, v0
	v_mov_b32_e32 v88, v0
	v_mov_b32_e32 v89, v0
	v_mov_b32_e32 v90, v0
	v_mov_b32_e32 v91, v0
	v_mov_b32_e32 v92, v0
	v_mov_b32_e32 v93, v0
	v_mov_b32_e32 v94, v0
	v_mov_b32_e32 v95, v0
	v_mov_b32_e32 v100, v0
	v_mov_b32_e32 v101, v0
	v_mov_b32_e32 v102, v0
	v_mov_b32_e32 v103, v0
	v_mov_b32_e32 v108, v0
	v_mov_b32_e32 v109, v0
	v_mov_b32_e32 v110, v0
	v_mov_b32_e32 v111, v0
	v_mov_b32_e32 v72, v0
	v_mov_b32_e32 v73, v0
	v_mov_b32_e32 v74, v0
	v_mov_b32_e32 v75, v0
	v_mov_b32_e32 v76, v0
	v_mov_b32_e32 v77, v0
	v_mov_b32_e32 v78, v0
	v_mov_b32_e32 v79, v0
	v_mov_b32_e32 v96, v0
	v_mov_b32_e32 v97, v0
	v_mov_b32_e32 v98, v0
	v_mov_b32_e32 v99, v0
	v_mov_b32_e32 v104, v0
	v_mov_b32_e32 v105, v0
	v_mov_b32_e32 v106, v0
	v_mov_b32_e32 v107, v0
	v_mov_b32_e32 v112, v0
	v_mov_b32_e32 v113, v0
	v_mov_b32_e32 v114, v0
	v_mov_b32_e32 v115, v0
	v_mov_b32_e32 v116, v0
	v_mov_b32_e32 v117, v0
	v_mov_b32_e32 v118, v0
	v_mov_b32_e32 v119, v0
	v_mov_b32_e32 v120, v0
	v_mov_b32_e32 v121, v0
	v_mov_b32_e32 v122, v0
	v_mov_b32_e32 v123, v0
	v_mov_b32_e32 v124, v0
	v_mov_b32_e32 v125, v0
	v_mov_b32_e32 v126, v0
	v_mov_b32_e32 v127, v0

.LBB0_791:
	s_ashr_i32 s27, s26, 31
	v_cmp_lt_i64_e32 vcc, s[28:29], v[140:141]
	s_lshl_b64 s[28:29], s[26:27], 18
	s_add_u32 s28, s71, s28
	s_addc_u32 s29, s72, s29
	s_and_b64 s[30:31], vcc, exec
	s_cselect_b32 s27, s29, s39
	s_cselect_b32 s35, s28, s38
	s_ashr_i32 s25, s24, 31
	s_lshl_b64 s[30:31], s[24:25], 18
	v_readlane_b32 s25, v253, 47
	s_add_u32 s30, s25, s30
	v_readlane_b32 s25, v253, 48
	s_addc_u32 s31, s25, s31
	s_and_b64 s[42:43], vcc, exec
	s_cselect_b32 s25, s31, s41
	s_cselect_b32 s60, s30, s40
	s_add_u32 s38, s38, 0x20080
	s_addc_u32 s39, s39, 0
	s_add_u32 s61, s40, 0x100
	v_mov_b32_e32 v0, 0
	s_addc_u32 s62, s41, 0
	s_mov_b32 s63, -2
	s_waitcnt lgkmcnt(0)
	v_mov_b32_e32 v1, v0
	v_mov_b32_e32 v2, v0
	v_mov_b32_e32 v3, v0
	v_mov_b32_e32 v4, v0
	v_mov_b32_e32 v5, v0
	v_mov_b32_e32 v6, v0
	v_mov_b32_e32 v7, v0
	v_mov_b32_e32 v12, v0
	v_mov_b32_e32 v13, v0
	v_mov_b32_e32 v14, v0
	v_mov_b32_e32 v15, v0
	v_mov_b32_e32 v20, v0
	v_mov_b32_e32 v21, v0
	v_mov_b32_e32 v22, v0
	v_mov_b32_e32 v23, v0
	v_mov_b32_e32 v28, v0
	v_mov_b32_e32 v29, v0
	v_mov_b32_e32 v30, v0
	v_mov_b32_e32 v31, v0
	v_mov_b32_e32 v36, v0
	v_mov_b32_e32 v37, v0
	v_mov_b32_e32 v38, v0
	v_mov_b32_e32 v39, v0
	v_mov_b32_e32 v48, v0
	v_mov_b32_e32 v49, v0
	v_mov_b32_e32 v50, v0
	v_mov_b32_e32 v51, v0
	v_mov_b32_e32 v52, v0
	v_mov_b32_e32 v53, v0
	v_mov_b32_e32 v54, v0
	v_mov_b32_e32 v55, v0
	v_mov_b32_e32 v8, v0
	v_mov_b32_e32 v9, v0
	v_mov_b32_e32 v10, v0
	v_mov_b32_e32 v11, v0
	v_mov_b32_e32 v16, v0
	v_mov_b32_e32 v17, v0
	v_mov_b32_e32 v18, v0
	v_mov_b32_e32 v19, v0
	v_mov_b32_e32 v24, v0
	v_mov_b32_e32 v25, v0
	v_mov_b32_e32 v26, v0
	v_mov_b32_e32 v27, v0
	v_mov_b32_e32 v32, v0
	v_mov_b32_e32 v33, v0
	v_mov_b32_e32 v34, v0
	v_mov_b32_e32 v35, v0
	v_mov_b32_e32 v40, v0
	v_mov_b32_e32 v41, v0
	v_mov_b32_e32 v42, v0
	v_mov_b32_e32 v43, v0
	v_mov_b32_e32 v44, v0
	v_mov_b32_e32 v45, v0
	v_mov_b32_e32 v46, v0
	v_mov_b32_e32 v47, v0
	v_mov_b32_e32 v56, v0
	v_mov_b32_e32 v57, v0
	v_mov_b32_e32 v58, v0
	v_mov_b32_e32 v59, v0
	v_mov_b32_e32 v60, v0
	v_mov_b32_e32 v61, v0
	v_mov_b32_e32 v62, v0
	v_mov_b32_e32 v63, v0
	v_mov_b32_e32 v64, v0
	v_mov_b32_e32 v65, v0
	v_mov_b32_e32 v66, v0
	v_mov_b32_e32 v67, v0
	v_mov_b32_e32 v68, v0
	v_mov_b32_e32 v69, v0
	v_mov_b32_e32 v70, v0
	v_mov_b32_e32 v71, v0
	v_mov_b32_e32 v76, v0
	v_mov_b32_e32 v77, v0
	v_mov_b32_e32 v78, v0
	v_mov_b32_e32 v79, v0
	v_mov_b32_e32 v84, v0
	v_mov_b32_e32 v85, v0
	v_mov_b32_e32 v86, v0
	v_mov_b32_e32 v87, v0
	v_mov_b32_e32 v92, v0
	v_mov_b32_e32 v93, v0
	v_mov_b32_e32 v94, v0
	v_mov_b32_e32 v95, v0
	v_mov_b32_e32 v100, v0
	v_mov_b32_e32 v101, v0
	v_mov_b32_e32 v102, v0
	v_mov_b32_e32 v103, v0
	v_mov_b32_e32 v112, v0
	v_mov_b32_e32 v113, v0
	v_mov_b32_e32 v114, v0
	v_mov_b32_e32 v115, v0
	v_mov_b32_e32 v116, v0
	v_mov_b32_e32 v117, v0
	v_mov_b32_e32 v118, v0
	v_mov_b32_e32 v119, v0
	v_mov_b32_e32 v72, v0
	v_mov_b32_e32 v73, v0
	v_mov_b32_e32 v74, v0
	v_mov_b32_e32 v75, v0
	v_mov_b32_e32 v80, v0
	v_mov_b32_e32 v81, v0
	v_mov_b32_e32 v82, v0
	v_mov_b32_e32 v83, v0
	v_mov_b32_e32 v88, v0
	v_mov_b32_e32 v89, v0
	v_mov_b32_e32 v90, v0
	v_mov_b32_e32 v91, v0
	v_mov_b32_e32 v96, v0
	v_mov_b32_e32 v97, v0
	v_mov_b32_e32 v98, v0
	v_mov_b32_e32 v99, v0
	v_mov_b32_e32 v104, v0
	v_mov_b32_e32 v105, v0
	v_mov_b32_e32 v106, v0
	v_mov_b32_e32 v107, v0
	v_mov_b32_e32 v108, v0
	v_mov_b32_e32 v109, v0
	v_mov_b32_e32 v110, v0
	v_mov_b32_e32 v111, v0
	v_mov_b32_e32 v120, v0
	v_mov_b32_e32 v121, v0
	v_mov_b32_e32 v122, v0
	v_mov_b32_e32 v123, v0
	v_mov_b32_e32 v124, v0
	v_mov_b32_e32 v125, v0
	v_mov_b32_e32 v126, v0
	v_mov_b32_e32 v127, v0

.LBB0_849:
	s_ashr_i32 s27, s26, 31
	v_cmp_lt_i64_e32 vcc, s[28:29], v[140:141]
	s_lshl_b64 s[28:29], s[26:27], 19
	s_add_u32 s28, s90, s28
	s_addc_u32 s29, s91, s29
	s_and_b64 s[30:31], vcc, exec
	s_cselect_b32 s27, s29, s35
	s_cselect_b32 s62, s28, s34
	s_ashr_i32 s25, s24, 31
	s_lshl_b64 s[30:31], s[24:25], 19
	v_readlane_b32 s25, v253, 45
	s_add_u32 s30, s25, s30
	v_readlane_b32 s25, v253, 46
	s_addc_u32 s31, s25, s31
	s_and_b64 s[38:39], vcc, exec
	s_cselect_b32 s25, s31, s37
	s_cselect_b32 s63, s30, s36
	s_add_u32 s34, s34, 0x40080
	s_addc_u32 s35, s35, 0
	s_add_u32 s64, s36, 0x100
	v_mov_b32_e32 v0, 0
	s_addc_u32 s65, s37, 0
	s_mov_b32 s66, -2
	v_mov_b32_e32 v1, v0
	v_mov_b32_e32 v2, v0
	v_mov_b32_e32 v3, v0
	v_mov_b32_e32 v4, v0
	v_mov_b32_e32 v5, v0
	v_mov_b32_e32 v6, v0
	v_mov_b32_e32 v7, v0
	v_mov_b32_e32 v16, v0
	v_mov_b32_e32 v17, v0
	v_mov_b32_e32 v18, v0
	v_mov_b32_e32 v19, v0
	v_mov_b32_e32 v20, v0
	v_mov_b32_e32 v21, v0
	v_mov_b32_e32 v22, v0
	v_mov_b32_e32 v23, v0
	v_mov_b32_e32 v32, v0
	v_mov_b32_e32 v33, v0
	v_mov_b32_e32 v34, v0
	v_mov_b32_e32 v35, v0
	v_mov_b32_e32 v36, v0
	v_mov_b32_e32 v37, v0
	v_mov_b32_e32 v38, v0
	v_mov_b32_e32 v39, v0
	v_mov_b32_e32 v48, v0
	v_mov_b32_e32 v49, v0
	v_mov_b32_e32 v50, v0
	v_mov_b32_e32 v51, v0
	v_mov_b32_e32 v52, v0
	v_mov_b32_e32 v53, v0
	v_mov_b32_e32 v54, v0
	v_mov_b32_e32 v55, v0
	v_mov_b32_e32 v8, v0
	v_mov_b32_e32 v9, v0
	v_mov_b32_e32 v10, v0
	v_mov_b32_e32 v11, v0
	v_mov_b32_e32 v12, v0
	v_mov_b32_e32 v13, v0
	v_mov_b32_e32 v14, v0
	v_mov_b32_e32 v15, v0
	v_mov_b32_e32 v24, v0
	v_mov_b32_e32 v25, v0
	v_mov_b32_e32 v26, v0
	v_mov_b32_e32 v27, v0
	v_mov_b32_e32 v28, v0
	v_mov_b32_e32 v29, v0
	v_mov_b32_e32 v30, v0
	v_mov_b32_e32 v31, v0
	v_mov_b32_e32 v40, v0
	v_mov_b32_e32 v41, v0
	v_mov_b32_e32 v42, v0
	v_mov_b32_e32 v43, v0
	v_mov_b32_e32 v44, v0
	v_mov_b32_e32 v45, v0
	v_mov_b32_e32 v46, v0
	v_mov_b32_e32 v47, v0
	v_mov_b32_e32 v56, v0
	v_mov_b32_e32 v57, v0
	v_mov_b32_e32 v58, v0
	v_mov_b32_e32 v59, v0
	v_mov_b32_e32 v60, v0
	v_mov_b32_e32 v61, v0
	v_mov_b32_e32 v62, v0
	v_mov_b32_e32 v63, v0
	v_mov_b32_e32 v64, v0
	v_mov_b32_e32 v65, v0
	v_mov_b32_e32 v66, v0
	v_mov_b32_e32 v67, v0
	v_mov_b32_e32 v68, v0
	v_mov_b32_e32 v69, v0
	v_mov_b32_e32 v70, v0
	v_mov_b32_e32 v71, v0
	v_mov_b32_e32 v80, v0
	v_mov_b32_e32 v81, v0
	v_mov_b32_e32 v82, v0
	v_mov_b32_e32 v83, v0
	v_mov_b32_e32 v84, v0
	v_mov_b32_e32 v85, v0
	v_mov_b32_e32 v86, v0
	v_mov_b32_e32 v87, v0
	v_mov_b32_e32 v96, v0
	v_mov_b32_e32 v97, v0
	v_mov_b32_e32 v98, v0
	v_mov_b32_e32 v99, v0
	v_mov_b32_e32 v100, v0
	v_mov_b32_e32 v101, v0
	v_mov_b32_e32 v102, v0
	v_mov_b32_e32 v103, v0
	v_mov_b32_e32 v104, v0
	v_mov_b32_e32 v105, v0
	v_mov_b32_e32 v106, v0
	v_mov_b32_e32 v107, v0
	v_mov_b32_e32 v108, v0
	v_mov_b32_e32 v109, v0
	v_mov_b32_e32 v110, v0
	v_mov_b32_e32 v111, v0
	v_mov_b32_e32 v72, v0
	v_mov_b32_e32 v73, v0
	v_mov_b32_e32 v74, v0
	v_mov_b32_e32 v75, v0
	v_mov_b32_e32 v76, v0
	v_mov_b32_e32 v77, v0
	v_mov_b32_e32 v78, v0
	v_mov_b32_e32 v79, v0
	v_mov_b32_e32 v88, v0
	v_mov_b32_e32 v89, v0
	v_mov_b32_e32 v90, v0
	v_mov_b32_e32 v91, v0
	v_mov_b32_e32 v92, v0
	v_mov_b32_e32 v93, v0
	v_mov_b32_e32 v94, v0
	v_mov_b32_e32 v95, v0
	v_mov_b32_e32 v112, v0
	v_mov_b32_e32 v113, v0
	v_mov_b32_e32 v114, v0
	v_mov_b32_e32 v115, v0
	v_mov_b32_e32 v116, v0
	v_mov_b32_e32 v117, v0
	v_mov_b32_e32 v118, v0
	v_mov_b32_e32 v119, v0
	v_mov_b32_e32 v120, v0
	v_mov_b32_e32 v121, v0
	v_mov_b32_e32 v122, v0
	v_mov_b32_e32 v123, v0
	v_mov_b32_e32 v124, v0
	v_mov_b32_e32 v125, v0
	v_mov_b32_e32 v126, v0
	v_mov_b32_e32 v127, v0

.LBB0_895:
	s_ashr_i32 s29, s28, 31
	v_cmp_lt_i64_e32 vcc, s[30:31], v[140:141]
	s_lshl_b64 s[30:31], s[28:29], 21
	s_add_u32 s30, s92, s30
	s_addc_u32 s31, s93, s31
	s_and_b64 s[34:35], vcc, exec
	s_cselect_b32 s29, s31, s41
	s_cselect_b32 s37, s30, s40
	s_ashr_i32 s27, s26, 31
	s_lshl_b64 s[34:35], s[26:27], 21
	v_readlane_b32 s27, v253, 57
	s_add_u32 s34, s27, s34
	v_readlane_b32 s27, v253, 58
	s_addc_u32 s35, s27, s35
	s_and_b64 s[48:49], vcc, exec
	s_cselect_b32 s27, s35, s43
	s_cselect_b32 s62, s34, s42
	s_add_u32 s40, s40, 0x100080
	s_addc_u32 s41, s41, 0
	s_add_u32 s63, s42, 0x100
	v_mov_b32_e32 v0, 0
	s_addc_u32 s64, s43, 0
	s_mov_b32 s65, -2
	s_waitcnt lgkmcnt(0)
	v_mov_b32_e32 v1, v0
	v_mov_b32_e32 v2, v0
	v_mov_b32_e32 v3, v0
	v_mov_b32_e32 v4, v0
	v_mov_b32_e32 v5, v0
	v_mov_b32_e32 v6, v0
	v_mov_b32_e32 v7, v0
	v_mov_b32_e32 v12, v0
	v_mov_b32_e32 v13, v0
	v_mov_b32_e32 v14, v0
	v_mov_b32_e32 v15, v0
	v_mov_b32_e32 v20, v0
	v_mov_b32_e32 v21, v0
	v_mov_b32_e32 v22, v0
	v_mov_b32_e32 v23, v0
	v_mov_b32_e32 v28, v0
	v_mov_b32_e32 v29, v0
	v_mov_b32_e32 v30, v0
	v_mov_b32_e32 v31, v0
	v_mov_b32_e32 v36, v0
	v_mov_b32_e32 v37, v0
	v_mov_b32_e32 v38, v0
	v_mov_b32_e32 v39, v0
	v_mov_b32_e32 v48, v0
	v_mov_b32_e32 v49, v0
	v_mov_b32_e32 v50, v0
	v_mov_b32_e32 v51, v0
	v_mov_b32_e32 v52, v0
	v_mov_b32_e32 v53, v0
	v_mov_b32_e32 v54, v0
	v_mov_b32_e32 v55, v0
	v_mov_b32_e32 v8, v0
	v_mov_b32_e32 v9, v0
	v_mov_b32_e32 v10, v0
	v_mov_b32_e32 v11, v0
	v_mov_b32_e32 v16, v0
	v_mov_b32_e32 v17, v0
	v_mov_b32_e32 v18, v0
	v_mov_b32_e32 v19, v0
	v_mov_b32_e32 v24, v0
	v_mov_b32_e32 v25, v0
	v_mov_b32_e32 v26, v0
	v_mov_b32_e32 v27, v0
	v_mov_b32_e32 v32, v0
	v_mov_b32_e32 v33, v0
	v_mov_b32_e32 v34, v0
	v_mov_b32_e32 v35, v0
	v_mov_b32_e32 v40, v0
	v_mov_b32_e32 v41, v0
	v_mov_b32_e32 v42, v0
	v_mov_b32_e32 v43, v0
	v_mov_b32_e32 v44, v0
	v_mov_b32_e32 v45, v0
	v_mov_b32_e32 v46, v0
	v_mov_b32_e32 v47, v0
	v_mov_b32_e32 v56, v0
	v_mov_b32_e32 v57, v0
	v_mov_b32_e32 v58, v0
	v_mov_b32_e32 v59, v0
	v_mov_b32_e32 v60, v0
	v_mov_b32_e32 v61, v0
	v_mov_b32_e32 v62, v0
	v_mov_b32_e32 v63, v0
	v_mov_b32_e32 v64, v0
	v_mov_b32_e32 v65, v0
	v_mov_b32_e32 v66, v0
	v_mov_b32_e32 v67, v0
	v_mov_b32_e32 v68, v0
	v_mov_b32_e32 v69, v0
	v_mov_b32_e32 v70, v0
	v_mov_b32_e32 v71, v0
	v_mov_b32_e32 v76, v0
	v_mov_b32_e32 v77, v0
	v_mov_b32_e32 v78, v0
	v_mov_b32_e32 v79, v0
	v_mov_b32_e32 v84, v0
	v_mov_b32_e32 v85, v0
	v_mov_b32_e32 v86, v0
	v_mov_b32_e32 v87, v0
	v_mov_b32_e32 v92, v0
	v_mov_b32_e32 v93, v0
	v_mov_b32_e32 v94, v0
	v_mov_b32_e32 v95, v0
	v_mov_b32_e32 v100, v0
	v_mov_b32_e32 v101, v0
	v_mov_b32_e32 v102, v0
	v_mov_b32_e32 v103, v0
	v_mov_b32_e32 v112, v0
	v_mov_b32_e32 v113, v0
	v_mov_b32_e32 v114, v0
	v_mov_b32_e32 v115, v0
	v_mov_b32_e32 v116, v0
	v_mov_b32_e32 v117, v0
	v_mov_b32_e32 v118, v0
	v_mov_b32_e32 v119, v0
	v_mov_b32_e32 v72, v0
	v_mov_b32_e32 v73, v0
	v_mov_b32_e32 v74, v0
	v_mov_b32_e32 v75, v0
	v_mov_b32_e32 v80, v0
	v_mov_b32_e32 v81, v0
	v_mov_b32_e32 v82, v0
	v_mov_b32_e32 v83, v0
	v_mov_b32_e32 v88, v0
	v_mov_b32_e32 v89, v0
	v_mov_b32_e32 v90, v0
	v_mov_b32_e32 v91, v0
	v_mov_b32_e32 v96, v0
	v_mov_b32_e32 v97, v0
	v_mov_b32_e32 v98, v0
	v_mov_b32_e32 v99, v0
	v_mov_b32_e32 v104, v0
	v_mov_b32_e32 v105, v0
	v_mov_b32_e32 v106, v0
	v_mov_b32_e32 v107, v0
	v_mov_b32_e32 v108, v0
	v_mov_b32_e32 v109, v0
	v_mov_b32_e32 v110, v0
	v_mov_b32_e32 v111, v0
	v_mov_b32_e32 v120, v0
	v_mov_b32_e32 v121, v0
	v_mov_b32_e32 v122, v0
	v_mov_b32_e32 v123, v0
	v_mov_b32_e32 v124, v0
	v_mov_b32_e32 v125, v0
	v_mov_b32_e32 v126, v0
	v_mov_b32_e32 v127, v0

.LBB0_945:
	s_ashr_i32 s23, s22, 31
	v_cmp_lt_i64_e32 vcc, s[24:25], v[140:141]
	s_lshl_b64 s[24:25], s[22:23], 19
	s_add_u32 s24, s10, s24
	s_addc_u32 s25, s11, s25
	s_and_b64 s[26:27], vcc, exec
	s_cselect_b32 s23, s25, s3
	s_cselect_b32 s54, s24, s2
	s_ashr_i32 s21, s20, 31
	s_lshl_b64 s[26:27], s[20:21], 19
	v_readlane_b32 s30, v253, 53
	v_readlane_b32 s31, v253, 54
	s_add_u32 s26, s30, s26
	s_addc_u32 s27, s31, s27
	s_and_b64 s[30:31], vcc, exec
	s_cselect_b32 s21, s27, s29
	s_cselect_b32 s55, s26, s28
	s_add_u32 s2, s2, 0x40080
	s_addc_u32 s3, s3, 0
	s_add_u32 s56, s28, 0x100
	v_mov_b32_e32 v0, 0
	s_addc_u32 s57, s29, 0
	s_mov_b32 s58, -2
	v_mov_b32_e32 v1, v0
	v_mov_b32_e32 v2, v0
	v_mov_b32_e32 v3, v0
	v_mov_b32_e32 v4, v0
	v_mov_b32_e32 v5, v0
	v_mov_b32_e32 v6, v0
	v_mov_b32_e32 v7, v0
	v_mov_b32_e32 v16, v0
	v_mov_b32_e32 v17, v0
	v_mov_b32_e32 v18, v0
	v_mov_b32_e32 v19, v0
	v_mov_b32_e32 v20, v0
	v_mov_b32_e32 v21, v0
	v_mov_b32_e32 v22, v0
	v_mov_b32_e32 v23, v0
	v_mov_b32_e32 v32, v0
	v_mov_b32_e32 v33, v0
	v_mov_b32_e32 v34, v0
	v_mov_b32_e32 v35, v0
	v_mov_b32_e32 v36, v0
	v_mov_b32_e32 v37, v0
	v_mov_b32_e32 v38, v0
	v_mov_b32_e32 v39, v0
	v_mov_b32_e32 v48, v0
	v_mov_b32_e32 v49, v0
	v_mov_b32_e32 v50, v0
	v_mov_b32_e32 v51, v0
	v_mov_b32_e32 v52, v0
	v_mov_b32_e32 v53, v0
	v_mov_b32_e32 v54, v0
	v_mov_b32_e32 v55, v0
	v_mov_b32_e32 v8, v0
	v_mov_b32_e32 v9, v0
	v_mov_b32_e32 v10, v0
	v_mov_b32_e32 v11, v0
	v_mov_b32_e32 v12, v0
	v_mov_b32_e32 v13, v0
	v_mov_b32_e32 v14, v0
	v_mov_b32_e32 v15, v0
	v_mov_b32_e32 v24, v0
	v_mov_b32_e32 v25, v0
	v_mov_b32_e32 v26, v0
	v_mov_b32_e32 v27, v0
	v_mov_b32_e32 v28, v0
	v_mov_b32_e32 v29, v0
	v_mov_b32_e32 v30, v0
	v_mov_b32_e32 v31, v0
	v_mov_b32_e32 v40, v0
	v_mov_b32_e32 v41, v0
	v_mov_b32_e32 v42, v0
	v_mov_b32_e32 v43, v0
	v_mov_b32_e32 v44, v0
	v_mov_b32_e32 v45, v0
	v_mov_b32_e32 v46, v0
	v_mov_b32_e32 v47, v0
	v_mov_b32_e32 v56, v0
	v_mov_b32_e32 v57, v0
	v_mov_b32_e32 v58, v0
	v_mov_b32_e32 v59, v0
	v_mov_b32_e32 v60, v0
	v_mov_b32_e32 v61, v0
	v_mov_b32_e32 v62, v0
	v_mov_b32_e32 v63, v0
	v_mov_b32_e32 v64, v0
	v_mov_b32_e32 v65, v0
	v_mov_b32_e32 v66, v0
	v_mov_b32_e32 v67, v0
	v_mov_b32_e32 v68, v0
	v_mov_b32_e32 v69, v0
	v_mov_b32_e32 v70, v0
	v_mov_b32_e32 v71, v0
	v_mov_b32_e32 v80, v0
	v_mov_b32_e32 v81, v0
	v_mov_b32_e32 v82, v0
	v_mov_b32_e32 v83, v0
	v_mov_b32_e32 v84, v0
	v_mov_b32_e32 v85, v0
	v_mov_b32_e32 v86, v0
	v_mov_b32_e32 v87, v0
	v_mov_b32_e32 v88, v0
	v_mov_b32_e32 v89, v0
	v_mov_b32_e32 v90, v0
	v_mov_b32_e32 v91, v0
	v_mov_b32_e32 v92, v0
	v_mov_b32_e32 v93, v0
	v_mov_b32_e32 v94, v0
	v_mov_b32_e32 v95, v0
	v_mov_b32_e32 v100, v0
	v_mov_b32_e32 v101, v0
	v_mov_b32_e32 v102, v0
	v_mov_b32_e32 v103, v0
	v_mov_b32_e32 v108, v0
	v_mov_b32_e32 v109, v0
	v_mov_b32_e32 v110, v0
	v_mov_b32_e32 v111, v0
	v_mov_b32_e32 v72, v0
	v_mov_b32_e32 v73, v0
	v_mov_b32_e32 v74, v0
	v_mov_b32_e32 v75, v0
	v_mov_b32_e32 v76, v0
	v_mov_b32_e32 v77, v0
	v_mov_b32_e32 v78, v0
	v_mov_b32_e32 v79, v0
	v_mov_b32_e32 v96, v0
	v_mov_b32_e32 v97, v0
	v_mov_b32_e32 v98, v0
	v_mov_b32_e32 v99, v0
	v_mov_b32_e32 v104, v0
	v_mov_b32_e32 v105, v0
	v_mov_b32_e32 v106, v0
	v_mov_b32_e32 v107, v0
	v_mov_b32_e32 v112, v0
	v_mov_b32_e32 v113, v0
	v_mov_b32_e32 v114, v0
	v_mov_b32_e32 v115, v0
	v_mov_b32_e32 v116, v0
	v_mov_b32_e32 v117, v0
	v_mov_b32_e32 v118, v0
	v_mov_b32_e32 v119, v0
	v_mov_b32_e32 v120, v0
	v_mov_b32_e32 v121, v0
	v_mov_b32_e32 v122, v0
	v_mov_b32_e32 v123, v0
	v_mov_b32_e32 v124, v0
	v_mov_b32_e32 v125, v0
	v_mov_b32_e32 v126, v0
	v_mov_b32_e32 v127, v0

.LBB0_1021:
	s_ashr_i32 s29, s28, 31
	v_cmp_lt_i64_e32 vcc, s[30:31], v[140:141]
	s_lshl_b64 s[30:31], s[28:29], 19
	s_add_u32 s30, s90, s30
	s_addc_u32 s31, s91, s31
	s_and_b64 s[34:35], vcc, exec
	s_cselect_b32 s29, s31, s41
	s_cselect_b32 s37, s30, s40
	s_ashr_i32 s27, s26, 31
	s_lshl_b64 s[34:35], s[26:27], 19
	v_readlane_b32 s48, v253, 51
	v_readlane_b32 s49, v253, 52
	s_add_u32 s34, s48, s34
	s_addc_u32 s35, s49, s35
	s_and_b64 s[48:49], vcc, exec
	s_cselect_b32 s27, s35, s43
	s_cselect_b32 s61, s34, s42
	s_add_u32 s40, s40, 0x40080
	s_addc_u32 s41, s41, 0
	s_add_u32 s62, s42, 0x100
	v_mov_b32_e32 v0, 0
	s_addc_u32 s63, s43, 0
	s_mov_b32 s64, -2
	s_waitcnt lgkmcnt(0)
	v_mov_b32_e32 v1, v0
	v_mov_b32_e32 v2, v0
	v_mov_b32_e32 v3, v0
	v_mov_b32_e32 v4, v0
	v_mov_b32_e32 v5, v0
	v_mov_b32_e32 v6, v0
	v_mov_b32_e32 v7, v0
	v_mov_b32_e32 v12, v0
	v_mov_b32_e32 v13, v0
	v_mov_b32_e32 v14, v0
	v_mov_b32_e32 v15, v0
	v_mov_b32_e32 v20, v0
	v_mov_b32_e32 v21, v0
	v_mov_b32_e32 v22, v0
	v_mov_b32_e32 v23, v0
	v_mov_b32_e32 v28, v0
	v_mov_b32_e32 v29, v0
	v_mov_b32_e32 v30, v0
	v_mov_b32_e32 v31, v0
	v_mov_b32_e32 v36, v0
	v_mov_b32_e32 v37, v0
	v_mov_b32_e32 v38, v0
	v_mov_b32_e32 v39, v0
	v_mov_b32_e32 v48, v0
	v_mov_b32_e32 v49, v0
	v_mov_b32_e32 v50, v0
	v_mov_b32_e32 v51, v0
	v_mov_b32_e32 v52, v0
	v_mov_b32_e32 v53, v0
	v_mov_b32_e32 v54, v0
	v_mov_b32_e32 v55, v0
	v_mov_b32_e32 v8, v0
	v_mov_b32_e32 v9, v0
	v_mov_b32_e32 v10, v0
	v_mov_b32_e32 v11, v0
	v_mov_b32_e32 v16, v0
	v_mov_b32_e32 v17, v0
	v_mov_b32_e32 v18, v0
	v_mov_b32_e32 v19, v0
	v_mov_b32_e32 v24, v0
	v_mov_b32_e32 v25, v0
	v_mov_b32_e32 v26, v0
	v_mov_b32_e32 v27, v0
	v_mov_b32_e32 v32, v0
	v_mov_b32_e32 v33, v0
	v_mov_b32_e32 v34, v0
	v_mov_b32_e32 v35, v0
	v_mov_b32_e32 v40, v0
	v_mov_b32_e32 v41, v0
	v_mov_b32_e32 v42, v0
	v_mov_b32_e32 v43, v0
	v_mov_b32_e32 v44, v0
	v_mov_b32_e32 v45, v0
	v_mov_b32_e32 v46, v0
	v_mov_b32_e32 v47, v0
	v_mov_b32_e32 v56, v0
	v_mov_b32_e32 v57, v0
	v_mov_b32_e32 v58, v0
	v_mov_b32_e32 v59, v0
	v_mov_b32_e32 v60, v0
	v_mov_b32_e32 v61, v0
	v_mov_b32_e32 v62, v0
	v_mov_b32_e32 v63, v0
	v_mov_b32_e32 v64, v0
	v_mov_b32_e32 v65, v0
	v_mov_b32_e32 v66, v0
	v_mov_b32_e32 v67, v0
	v_mov_b32_e32 v68, v0
	v_mov_b32_e32 v69, v0
	v_mov_b32_e32 v70, v0
	v_mov_b32_e32 v71, v0
	v_mov_b32_e32 v76, v0
	v_mov_b32_e32 v77, v0
	v_mov_b32_e32 v78, v0
	v_mov_b32_e32 v79, v0
	v_mov_b32_e32 v84, v0
	v_mov_b32_e32 v85, v0
	v_mov_b32_e32 v86, v0
	v_mov_b32_e32 v87, v0
	v_mov_b32_e32 v92, v0
	v_mov_b32_e32 v93, v0
	v_mov_b32_e32 v94, v0
	v_mov_b32_e32 v95, v0
	v_mov_b32_e32 v100, v0
	v_mov_b32_e32 v101, v0
	v_mov_b32_e32 v102, v0
	v_mov_b32_e32 v103, v0
	v_mov_b32_e32 v112, v0
	v_mov_b32_e32 v113, v0
	v_mov_b32_e32 v114, v0
	v_mov_b32_e32 v115, v0
	v_mov_b32_e32 v116, v0
	v_mov_b32_e32 v117, v0
	v_mov_b32_e32 v118, v0
	v_mov_b32_e32 v119, v0
	v_mov_b32_e32 v72, v0
	v_mov_b32_e32 v73, v0
	v_mov_b32_e32 v74, v0
	v_mov_b32_e32 v75, v0
	v_mov_b32_e32 v80, v0
	v_mov_b32_e32 v81, v0
	v_mov_b32_e32 v82, v0
	v_mov_b32_e32 v83, v0
	v_mov_b32_e32 v88, v0
	v_mov_b32_e32 v89, v0
	v_mov_b32_e32 v90, v0
	v_mov_b32_e32 v91, v0
	v_mov_b32_e32 v96, v0
	v_mov_b32_e32 v97, v0
	v_mov_b32_e32 v98, v0
	v_mov_b32_e32 v99, v0
	v_mov_b32_e32 v104, v0
	v_mov_b32_e32 v105, v0
	v_mov_b32_e32 v106, v0
	v_mov_b32_e32 v107, v0
	v_mov_b32_e32 v108, v0
	v_mov_b32_e32 v109, v0
	v_mov_b32_e32 v110, v0
	v_mov_b32_e32 v111, v0
	v_mov_b32_e32 v120, v0
	v_mov_b32_e32 v121, v0
	v_mov_b32_e32 v122, v0
	v_mov_b32_e32 v123, v0
	v_mov_b32_e32 v124, v0
	v_mov_b32_e32 v125, v0
	v_mov_b32_e32 v126, v0
	v_mov_b32_e32 v127, v0

.LBB0_1079:
	s_ashr_i32 s29, s28, 31
	v_cmp_lt_i64_e32 vcc, s[30:31], v[140:141]
	s_lshl_b64 s[30:31], s[28:29], 19
	s_add_u32 s30, s10, s30
	s_addc_u32 s31, s11, s31
	s_and_b64 s[34:35], vcc, exec
	s_cselect_b32 s29, s31, s3
	s_cselect_b32 s63, s30, s2
	s_ashr_i32 s27, s26, 31
	s_lshl_b64 s[34:35], s[26:27], 19
	s_add_u32 s34, s41, s34
	s_addc_u32 s35, s42, s35
	s_and_b64 s[38:39], vcc, exec
	s_cselect_b32 s27, s35, s37
	s_cselect_b32 s64, s34, s36
	s_add_u32 s2, s2, 0x40080
	s_addc_u32 s3, s3, 0
	s_add_u32 s65, s36, 0x100
	v_mov_b32_e32 v0, 0
	s_addc_u32 s66, s37, 0
	s_mov_b32 s67, -2
	v_mov_b32_e32 v1, v0
	v_mov_b32_e32 v2, v0
	v_mov_b32_e32 v3, v0
	v_mov_b32_e32 v4, v0
	v_mov_b32_e32 v5, v0
	v_mov_b32_e32 v6, v0
	v_mov_b32_e32 v7, v0
	v_mov_b32_e32 v16, v0
	v_mov_b32_e32 v17, v0
	v_mov_b32_e32 v18, v0
	v_mov_b32_e32 v19, v0
	v_mov_b32_e32 v20, v0
	v_mov_b32_e32 v21, v0
	v_mov_b32_e32 v22, v0
	v_mov_b32_e32 v23, v0
	v_mov_b32_e32 v32, v0
	v_mov_b32_e32 v33, v0
	v_mov_b32_e32 v34, v0
	v_mov_b32_e32 v35, v0
	v_mov_b32_e32 v36, v0
	v_mov_b32_e32 v37, v0
	v_mov_b32_e32 v38, v0
	v_mov_b32_e32 v39, v0
	v_mov_b32_e32 v48, v0
	v_mov_b32_e32 v49, v0
	v_mov_b32_e32 v50, v0
	v_mov_b32_e32 v51, v0
	v_mov_b32_e32 v52, v0
	v_mov_b32_e32 v53, v0
	v_mov_b32_e32 v54, v0
	v_mov_b32_e32 v55, v0
	v_mov_b32_e32 v8, v0
	v_mov_b32_e32 v9, v0
	v_mov_b32_e32 v10, v0
	v_mov_b32_e32 v11, v0
	v_mov_b32_e32 v12, v0
	v_mov_b32_e32 v13, v0
	v_mov_b32_e32 v14, v0
	v_mov_b32_e32 v15, v0
	v_mov_b32_e32 v24, v0
	v_mov_b32_e32 v25, v0
	v_mov_b32_e32 v26, v0
	v_mov_b32_e32 v27, v0
	v_mov_b32_e32 v28, v0
	v_mov_b32_e32 v29, v0
	v_mov_b32_e32 v30, v0
	v_mov_b32_e32 v31, v0
	v_mov_b32_e32 v40, v0
	v_mov_b32_e32 v41, v0
	v_mov_b32_e32 v42, v0
	v_mov_b32_e32 v43, v0
	v_mov_b32_e32 v44, v0
	v_mov_b32_e32 v45, v0
	v_mov_b32_e32 v46, v0
	v_mov_b32_e32 v47, v0
	v_mov_b32_e32 v56, v0
	v_mov_b32_e32 v57, v0
	v_mov_b32_e32 v58, v0
	v_mov_b32_e32 v59, v0
	v_mov_b32_e32 v60, v0
	v_mov_b32_e32 v61, v0
	v_mov_b32_e32 v62, v0
	v_mov_b32_e32 v63, v0
	v_mov_b32_e32 v64, v0
	v_mov_b32_e32 v65, v0
	v_mov_b32_e32 v66, v0
	v_mov_b32_e32 v67, v0
	v_mov_b32_e32 v68, v0
	v_mov_b32_e32 v69, v0
	v_mov_b32_e32 v70, v0
	v_mov_b32_e32 v71, v0
	v_mov_b32_e32 v80, v0
	v_mov_b32_e32 v81, v0
	v_mov_b32_e32 v82, v0
	v_mov_b32_e32 v83, v0
	v_mov_b32_e32 v84, v0
	v_mov_b32_e32 v85, v0
	v_mov_b32_e32 v86, v0
	v_mov_b32_e32 v87, v0
	v_mov_b32_e32 v88, v0
	v_mov_b32_e32 v89, v0
	v_mov_b32_e32 v90, v0
	v_mov_b32_e32 v91, v0
	v_mov_b32_e32 v92, v0
	v_mov_b32_e32 v93, v0
	v_mov_b32_e32 v94, v0
	v_mov_b32_e32 v95, v0
	v_mov_b32_e32 v100, v0
	v_mov_b32_e32 v101, v0
	v_mov_b32_e32 v102, v0
	v_mov_b32_e32 v103, v0
	v_mov_b32_e32 v108, v0
	v_mov_b32_e32 v109, v0
	v_mov_b32_e32 v110, v0
	v_mov_b32_e32 v111, v0
	v_mov_b32_e32 v72, v0
	v_mov_b32_e32 v73, v0
	v_mov_b32_e32 v74, v0
	v_mov_b32_e32 v75, v0
	v_mov_b32_e32 v76, v0
	v_mov_b32_e32 v77, v0
	v_mov_b32_e32 v78, v0
	v_mov_b32_e32 v79, v0
	v_mov_b32_e32 v96, v0
	v_mov_b32_e32 v97, v0
	v_mov_b32_e32 v98, v0
	v_mov_b32_e32 v99, v0
	v_mov_b32_e32 v104, v0
	v_mov_b32_e32 v105, v0
	v_mov_b32_e32 v106, v0
	v_mov_b32_e32 v107, v0
	v_mov_b32_e32 v112, v0
	v_mov_b32_e32 v113, v0
	v_mov_b32_e32 v114, v0
	v_mov_b32_e32 v115, v0
	v_mov_b32_e32 v116, v0
	v_mov_b32_e32 v117, v0
	v_mov_b32_e32 v118, v0
	v_mov_b32_e32 v119, v0
	v_mov_b32_e32 v120, v0
	v_mov_b32_e32 v121, v0
	v_mov_b32_e32 v122, v0
	v_mov_b32_e32 v123, v0
	v_mov_b32_e32 v124, v0
	v_mov_b32_e32 v125, v0
	v_mov_b32_e32 v126, v0
	v_mov_b32_e32 v127, v0

.LBB0_1159:
	s_ashr_i32 s25, s24, 31
	v_cmp_lt_i64_e32 vcc, s[26:27], v[140:141]
	s_lshl_b64 s[26:27], s[24:25], 18
	s_add_u32 s26, s71, s26
	s_addc_u32 s27, s72, s27
	s_and_b64 s[28:29], vcc, exec
	s_cselect_b32 s25, s27, s37
	s_cselect_b32 s31, s26, s36
	s_ashr_i32 s23, s22, 31
	s_lshl_b64 s[28:29], s[22:23], 18
	s_add_u32 s28, s42, s28
	s_addc_u32 s29, s43, s29
	s_and_b64 s[40:41], vcc, exec
	s_cselect_b32 s23, s29, s39
	s_cselect_b32 s59, s28, s38
	s_add_u32 s36, s36, 0x20080
	s_addc_u32 s37, s37, 0
	s_add_u32 s60, s38, 0x100
	v_mov_b32_e32 v0, 0
	s_addc_u32 s61, s39, 0
	s_mov_b32 s62, -2
	s_waitcnt lgkmcnt(0)
	v_mov_b32_e32 v1, v0
	v_mov_b32_e32 v2, v0
	v_mov_b32_e32 v3, v0
	v_mov_b32_e32 v4, v0
	v_mov_b32_e32 v5, v0
	v_mov_b32_e32 v6, v0
	v_mov_b32_e32 v7, v0
	v_mov_b32_e32 v12, v0
	v_mov_b32_e32 v13, v0
	v_mov_b32_e32 v14, v0
	v_mov_b32_e32 v15, v0
	v_mov_b32_e32 v20, v0
	v_mov_b32_e32 v21, v0
	v_mov_b32_e32 v22, v0
	v_mov_b32_e32 v23, v0
	v_mov_b32_e32 v28, v0
	v_mov_b32_e32 v29, v0
	v_mov_b32_e32 v30, v0
	v_mov_b32_e32 v31, v0
	v_mov_b32_e32 v36, v0
	v_mov_b32_e32 v37, v0
	v_mov_b32_e32 v38, v0
	v_mov_b32_e32 v39, v0
	v_mov_b32_e32 v48, v0
	v_mov_b32_e32 v49, v0
	v_mov_b32_e32 v50, v0
	v_mov_b32_e32 v51, v0
	v_mov_b32_e32 v52, v0
	v_mov_b32_e32 v53, v0
	v_mov_b32_e32 v54, v0
	v_mov_b32_e32 v55, v0
	v_mov_b32_e32 v8, v0
	v_mov_b32_e32 v9, v0
	v_mov_b32_e32 v10, v0
	v_mov_b32_e32 v11, v0
	v_mov_b32_e32 v16, v0
	v_mov_b32_e32 v17, v0
	v_mov_b32_e32 v18, v0
	v_mov_b32_e32 v19, v0
	v_mov_b32_e32 v24, v0
	v_mov_b32_e32 v25, v0
	v_mov_b32_e32 v26, v0
	v_mov_b32_e32 v27, v0
	v_mov_b32_e32 v32, v0
	v_mov_b32_e32 v33, v0
	v_mov_b32_e32 v34, v0
	v_mov_b32_e32 v35, v0
	v_mov_b32_e32 v40, v0
	v_mov_b32_e32 v41, v0
	v_mov_b32_e32 v42, v0
	v_mov_b32_e32 v43, v0
	v_mov_b32_e32 v44, v0
	v_mov_b32_e32 v45, v0
	v_mov_b32_e32 v46, v0
	v_mov_b32_e32 v47, v0
	v_mov_b32_e32 v56, v0
	v_mov_b32_e32 v57, v0
	v_mov_b32_e32 v58, v0
	v_mov_b32_e32 v59, v0
	v_mov_b32_e32 v60, v0
	v_mov_b32_e32 v61, v0
	v_mov_b32_e32 v62, v0
	v_mov_b32_e32 v63, v0
	v_mov_b32_e32 v64, v0
	v_mov_b32_e32 v65, v0
	v_mov_b32_e32 v66, v0
	v_mov_b32_e32 v67, v0
	v_mov_b32_e32 v68, v0
	v_mov_b32_e32 v69, v0
	v_mov_b32_e32 v70, v0
	v_mov_b32_e32 v71, v0
	v_mov_b32_e32 v76, v0
	v_mov_b32_e32 v77, v0
	v_mov_b32_e32 v78, v0
	v_mov_b32_e32 v79, v0
	v_mov_b32_e32 v84, v0
	v_mov_b32_e32 v85, v0
	v_mov_b32_e32 v86, v0
	v_mov_b32_e32 v87, v0
	v_mov_b32_e32 v92, v0
	v_mov_b32_e32 v93, v0
	v_mov_b32_e32 v94, v0
	v_mov_b32_e32 v95, v0
	v_mov_b32_e32 v100, v0
	v_mov_b32_e32 v101, v0
	v_mov_b32_e32 v102, v0
	v_mov_b32_e32 v103, v0
	v_mov_b32_e32 v112, v0
	v_mov_b32_e32 v113, v0
	v_mov_b32_e32 v114, v0
	v_mov_b32_e32 v115, v0
	v_mov_b32_e32 v116, v0
	v_mov_b32_e32 v117, v0
	v_mov_b32_e32 v118, v0
	v_mov_b32_e32 v119, v0
	v_mov_b32_e32 v72, v0
	v_mov_b32_e32 v73, v0
	v_mov_b32_e32 v74, v0
	v_mov_b32_e32 v75, v0
	v_mov_b32_e32 v80, v0
	v_mov_b32_e32 v81, v0
	v_mov_b32_e32 v82, v0
	v_mov_b32_e32 v83, v0
	v_mov_b32_e32 v88, v0
	v_mov_b32_e32 v89, v0
	v_mov_b32_e32 v90, v0
	v_mov_b32_e32 v91, v0
	v_mov_b32_e32 v96, v0
	v_mov_b32_e32 v97, v0
	v_mov_b32_e32 v98, v0
	v_mov_b32_e32 v99, v0
	v_mov_b32_e32 v104, v0
	v_mov_b32_e32 v105, v0
	v_mov_b32_e32 v106, v0
	v_mov_b32_e32 v107, v0
	v_mov_b32_e32 v108, v0
	v_mov_b32_e32 v109, v0
	v_mov_b32_e32 v110, v0
	v_mov_b32_e32 v111, v0
	v_mov_b32_e32 v120, v0
	v_mov_b32_e32 v121, v0
	v_mov_b32_e32 v122, v0
	v_mov_b32_e32 v123, v0
	v_mov_b32_e32 v124, v0
	v_mov_b32_e32 v125, v0
	v_mov_b32_e32 v126, v0
	v_mov_b32_e32 v127, v0

.LBB0_1217:
	s_ashr_i32 s23, s22, 31
	v_cmp_lt_i64_e32 vcc, s[24:25], v[140:141]
	s_lshl_b64 s[24:25], s[22:23], 19
	s_add_u32 s24, s90, s24
	s_addc_u32 s25, s91, s25
	s_and_b64 s[26:27], vcc, exec
	s_cselect_b32 s23, s25, s29
	s_cselect_b32 s59, s24, s28
	s_ashr_i32 s21, s20, 31
	s_lshl_b64 s[26:27], s[20:21], 19
	s_add_u32 s26, s37, s26
	s_addc_u32 s27, s38, s27
	s_and_b64 s[34:35], vcc, exec
	s_cselect_b32 s21, s27, s31
	s_cselect_b32 s60, s26, s30
	s_add_u32 s28, s28, 0x40080
	s_addc_u32 s29, s29, 0
	s_add_u32 s61, s30, 0x100
	v_mov_b32_e32 v0, 0
	s_addc_u32 s62, s31, 0
	s_mov_b32 s63, -2
	v_mov_b32_e32 v1, v0
	v_mov_b32_e32 v2, v0
	v_mov_b32_e32 v3, v0
	v_mov_b32_e32 v4, v0
	v_mov_b32_e32 v5, v0
	v_mov_b32_e32 v6, v0
	v_mov_b32_e32 v7, v0
	v_mov_b32_e32 v16, v0
	v_mov_b32_e32 v17, v0
	v_mov_b32_e32 v18, v0
	v_mov_b32_e32 v19, v0
	v_mov_b32_e32 v20, v0
	v_mov_b32_e32 v21, v0
	v_mov_b32_e32 v22, v0
	v_mov_b32_e32 v23, v0
	v_mov_b32_e32 v32, v0
	v_mov_b32_e32 v33, v0
	v_mov_b32_e32 v34, v0
	v_mov_b32_e32 v35, v0
	v_mov_b32_e32 v36, v0
	v_mov_b32_e32 v37, v0
	v_mov_b32_e32 v38, v0
	v_mov_b32_e32 v39, v0
	v_mov_b32_e32 v48, v0
	v_mov_b32_e32 v49, v0
	v_mov_b32_e32 v50, v0
	v_mov_b32_e32 v51, v0
	v_mov_b32_e32 v52, v0
	v_mov_b32_e32 v53, v0
	v_mov_b32_e32 v54, v0
	v_mov_b32_e32 v55, v0
	v_mov_b32_e32 v8, v0
	v_mov_b32_e32 v9, v0
	v_mov_b32_e32 v10, v0
	v_mov_b32_e32 v11, v0
	v_mov_b32_e32 v12, v0
	v_mov_b32_e32 v13, v0
	v_mov_b32_e32 v14, v0
	v_mov_b32_e32 v15, v0
	v_mov_b32_e32 v24, v0
	v_mov_b32_e32 v25, v0
	v_mov_b32_e32 v26, v0
	v_mov_b32_e32 v27, v0
	v_mov_b32_e32 v28, v0
	v_mov_b32_e32 v29, v0
	v_mov_b32_e32 v30, v0
	v_mov_b32_e32 v31, v0
	v_mov_b32_e32 v40, v0
	v_mov_b32_e32 v41, v0
	v_mov_b32_e32 v42, v0
	v_mov_b32_e32 v43, v0
	v_mov_b32_e32 v44, v0
	v_mov_b32_e32 v45, v0
	v_mov_b32_e32 v46, v0
	v_mov_b32_e32 v47, v0
	v_mov_b32_e32 v56, v0
	v_mov_b32_e32 v57, v0
	v_mov_b32_e32 v58, v0
	v_mov_b32_e32 v59, v0
	v_mov_b32_e32 v60, v0
	v_mov_b32_e32 v61, v0
	v_mov_b32_e32 v62, v0
	v_mov_b32_e32 v63, v0
	v_mov_b32_e32 v64, v0
	v_mov_b32_e32 v65, v0
	v_mov_b32_e32 v66, v0
	v_mov_b32_e32 v67, v0
	v_mov_b32_e32 v68, v0
	v_mov_b32_e32 v69, v0
	v_mov_b32_e32 v70, v0
	v_mov_b32_e32 v71, v0
	v_mov_b32_e32 v80, v0
	v_mov_b32_e32 v81, v0
	v_mov_b32_e32 v82, v0
	v_mov_b32_e32 v83, v0
	v_mov_b32_e32 v84, v0
	v_mov_b32_e32 v85, v0
	v_mov_b32_e32 v86, v0
	v_mov_b32_e32 v87, v0
	v_mov_b32_e32 v96, v0
	v_mov_b32_e32 v97, v0
	v_mov_b32_e32 v98, v0
	v_mov_b32_e32 v99, v0
	v_mov_b32_e32 v100, v0
	v_mov_b32_e32 v101, v0
	v_mov_b32_e32 v102, v0
	v_mov_b32_e32 v103, v0
	v_mov_b32_e32 v104, v0
	v_mov_b32_e32 v105, v0
	v_mov_b32_e32 v106, v0
	v_mov_b32_e32 v107, v0
	v_mov_b32_e32 v108, v0
	v_mov_b32_e32 v109, v0
	v_mov_b32_e32 v110, v0
	v_mov_b32_e32 v111, v0
	v_mov_b32_e32 v72, v0
	v_mov_b32_e32 v73, v0
	v_mov_b32_e32 v74, v0
	v_mov_b32_e32 v75, v0
	v_mov_b32_e32 v76, v0
	v_mov_b32_e32 v77, v0
	v_mov_b32_e32 v78, v0
	v_mov_b32_e32 v79, v0
	v_mov_b32_e32 v88, v0
	v_mov_b32_e32 v89, v0
	v_mov_b32_e32 v90, v0
	v_mov_b32_e32 v91, v0
	v_mov_b32_e32 v92, v0
	v_mov_b32_e32 v93, v0
	v_mov_b32_e32 v94, v0
	v_mov_b32_e32 v95, v0
	v_mov_b32_e32 v112, v0
	v_mov_b32_e32 v113, v0
	v_mov_b32_e32 v114, v0
	v_mov_b32_e32 v115, v0
	v_mov_b32_e32 v116, v0
	v_mov_b32_e32 v117, v0
	v_mov_b32_e32 v118, v0
	v_mov_b32_e32 v119, v0
	v_mov_b32_e32 v120, v0
	v_mov_b32_e32 v121, v0
	v_mov_b32_e32 v122, v0
	v_mov_b32_e32 v123, v0
	v_mov_b32_e32 v124, v0
	v_mov_b32_e32 v125, v0
	v_mov_b32_e32 v126, v0
	v_mov_b32_e32 v127, v0

.LBB0_1263:
	s_ashr_i32 s21, s20, 31
	v_cmp_lt_i64_e32 vcc, s[22:23], v[140:141]
	s_lshl_b64 s[22:23], s[20:21], 21
	s_add_u32 s22, s92, s22
	s_addc_u32 s23, s93, s23
	s_and_b64 s[24:25], vcc, exec
	s_cselect_b32 s21, s23, s31
	s_cselect_b32 s27, s22, s30
	s_ashr_i32 s19, s18, 31
	s_lshl_b64 s[24:25], s[18:19], 21
	s_add_u32 s24, s38, s24
	s_addc_u32 s25, s39, s25
	s_and_b64 s[36:37], vcc, exec
	s_cselect_b32 s19, s25, s35
	s_cselect_b32 s55, s24, s34
	s_add_u32 s30, s30, 0x100080
	s_addc_u32 s31, s31, 0
	s_add_u32 s56, s34, 0x100
	v_mov_b32_e32 v0, 0
	s_addc_u32 s57, s35, 0
	s_mov_b32 s58, -2
	s_waitcnt lgkmcnt(0)
	v_mov_b32_e32 v1, v0
	v_mov_b32_e32 v2, v0
	v_mov_b32_e32 v3, v0
	v_mov_b32_e32 v4, v0
	v_mov_b32_e32 v5, v0
	v_mov_b32_e32 v6, v0
	v_mov_b32_e32 v7, v0
	v_mov_b32_e32 v12, v0
	v_mov_b32_e32 v13, v0
	v_mov_b32_e32 v14, v0
	v_mov_b32_e32 v15, v0
	v_mov_b32_e32 v20, v0
	v_mov_b32_e32 v21, v0
	v_mov_b32_e32 v22, v0
	v_mov_b32_e32 v23, v0
	v_mov_b32_e32 v28, v0
	v_mov_b32_e32 v29, v0
	v_mov_b32_e32 v30, v0
	v_mov_b32_e32 v31, v0
	v_mov_b32_e32 v36, v0
	v_mov_b32_e32 v37, v0
	v_mov_b32_e32 v38, v0
	v_mov_b32_e32 v39, v0
	v_mov_b32_e32 v48, v0
	v_mov_b32_e32 v49, v0
	v_mov_b32_e32 v50, v0
	v_mov_b32_e32 v51, v0
	v_mov_b32_e32 v52, v0
	v_mov_b32_e32 v53, v0
	v_mov_b32_e32 v54, v0
	v_mov_b32_e32 v55, v0
	v_mov_b32_e32 v8, v0
	v_mov_b32_e32 v9, v0
	v_mov_b32_e32 v10, v0
	v_mov_b32_e32 v11, v0
	v_mov_b32_e32 v16, v0
	v_mov_b32_e32 v17, v0
	v_mov_b32_e32 v18, v0
	v_mov_b32_e32 v19, v0
	v_mov_b32_e32 v24, v0
	v_mov_b32_e32 v25, v0
	v_mov_b32_e32 v26, v0
	v_mov_b32_e32 v27, v0
	v_mov_b32_e32 v32, v0
	v_mov_b32_e32 v33, v0
	v_mov_b32_e32 v34, v0
	v_mov_b32_e32 v35, v0
	v_mov_b32_e32 v40, v0
	v_mov_b32_e32 v41, v0
	v_mov_b32_e32 v42, v0
	v_mov_b32_e32 v43, v0
	v_mov_b32_e32 v44, v0
	v_mov_b32_e32 v45, v0
	v_mov_b32_e32 v46, v0
	v_mov_b32_e32 v47, v0
	v_mov_b32_e32 v56, v0
	v_mov_b32_e32 v57, v0
	v_mov_b32_e32 v58, v0
	v_mov_b32_e32 v59, v0
	v_mov_b32_e32 v60, v0
	v_mov_b32_e32 v61, v0
	v_mov_b32_e32 v62, v0
	v_mov_b32_e32 v63, v0
	v_mov_b32_e32 v64, v0
	v_mov_b32_e32 v65, v0
	v_mov_b32_e32 v66, v0
	v_mov_b32_e32 v67, v0
	v_mov_b32_e32 v68, v0
	v_mov_b32_e32 v69, v0
	v_mov_b32_e32 v70, v0
	v_mov_b32_e32 v71, v0
	v_mov_b32_e32 v76, v0
	v_mov_b32_e32 v77, v0
	v_mov_b32_e32 v78, v0
	v_mov_b32_e32 v79, v0
	v_mov_b32_e32 v84, v0
	v_mov_b32_e32 v85, v0
	v_mov_b32_e32 v86, v0
	v_mov_b32_e32 v87, v0
	v_mov_b32_e32 v92, v0
	v_mov_b32_e32 v93, v0
	v_mov_b32_e32 v94, v0
	v_mov_b32_e32 v95, v0
	v_mov_b32_e32 v100, v0
	v_mov_b32_e32 v101, v0
	v_mov_b32_e32 v102, v0
	v_mov_b32_e32 v103, v0
	v_mov_b32_e32 v112, v0
	v_mov_b32_e32 v113, v0
	v_mov_b32_e32 v114, v0
	v_mov_b32_e32 v115, v0
	v_mov_b32_e32 v116, v0
	v_mov_b32_e32 v117, v0
	v_mov_b32_e32 v118, v0
	v_mov_b32_e32 v119, v0
	v_mov_b32_e32 v72, v0
	v_mov_b32_e32 v73, v0
	v_mov_b32_e32 v74, v0
	v_mov_b32_e32 v75, v0
	v_mov_b32_e32 v80, v0
	v_mov_b32_e32 v81, v0
	v_mov_b32_e32 v82, v0
	v_mov_b32_e32 v83, v0
	v_mov_b32_e32 v88, v0
	v_mov_b32_e32 v89, v0
	v_mov_b32_e32 v90, v0
	v_mov_b32_e32 v91, v0
	v_mov_b32_e32 v96, v0
	v_mov_b32_e32 v97, v0
	v_mov_b32_e32 v98, v0
	v_mov_b32_e32 v99, v0
	v_mov_b32_e32 v104, v0
	v_mov_b32_e32 v105, v0
	v_mov_b32_e32 v106, v0
	v_mov_b32_e32 v107, v0
	v_mov_b32_e32 v108, v0
	v_mov_b32_e32 v109, v0
	v_mov_b32_e32 v110, v0
	v_mov_b32_e32 v111, v0
	v_mov_b32_e32 v120, v0
	v_mov_b32_e32 v121, v0
	v_mov_b32_e32 v122, v0
	v_mov_b32_e32 v123, v0
	v_mov_b32_e32 v124, v0
	v_mov_b32_e32 v125, v0
	v_mov_b32_e32 v126, v0
	v_mov_b32_e32 v127, v0

	.amdhsa_kernel _Z10hybrid_fwd6Params
		.amdhsa_group_segment_fixed_size 0
		.amdhsa_private_segment_fixed_size 0
		.amdhsa_kernarg_size 504
		.amdhsa_user_sgpr_count 2
		.amdhsa_user_sgpr_dispatch_ptr 0
		.amdhsa_user_sgpr_queue_ptr 0
		.amdhsa_user_sgpr_kernarg_segment_ptr 1
		.amdhsa_user_sgpr_dispatch_id 0
		.amdhsa_user_sgpr_kernarg_preload_length 0
		.amdhsa_user_sgpr_kernarg_preload_offset 0
		.amdhsa_user_sgpr_private_segment_size 0
		.amdhsa_uses_dynamic_stack 0
		.amdhsa_enable_private_segment 0
		.amdhsa_system_sgpr_workgroup_id_x 1
		.amdhsa_system_sgpr_workgroup_id_y 0
		.amdhsa_system_sgpr_workgroup_id_z 0
		.amdhsa_system_sgpr_workgroup_info 0
		.amdhsa_system_vgpr_workitem_id 2
		.amdhsa_next_free_vgpr 256
		.amdhsa_next_free_sgpr 102
		.amdhsa_accum_offset 256
		.amdhsa_reserve_vcc 1
		.amdhsa_float_round_mode_32 0
		.amdhsa_float_round_mode_16_64 0
		.amdhsa_float_denorm_mode_32 3
		.amdhsa_float_denorm_mode_16_64 3
		.amdhsa_dx10_clamp 1
		.amdhsa_ieee_mode 1
		.amdhsa_fp16_overflow 0
		.amdhsa_tg_split 0
		.amdhsa_exception_fp_ieee_invalid_op 0
		.amdhsa_exception_fp_denorm_src 0
		.amdhsa_exception_fp_ieee_div_zero 0
		.amdhsa_exception_fp_ieee_overflow 0
		.amdhsa_exception_fp_ieee_underflow 0
		.amdhsa_exception_fp_ieee_inexact 0
		.amdhsa_exception_int_div_zero 0
	.end_amdhsa_kernel

amdhsa.kernels:
  - .agpr_count:     0
    .args:
      - .offset:         0
        .size:           248
        .value_kind:     by_value
      - .offset:         248
        .size:           4
        .value_kind:     hidden_block_count_x
      - .offset:         252
        .size:           4
        .value_kind:     hidden_block_count_y
      - .offset:         256
        .size:           4
        .value_kind:     hidden_block_count_z
      - .offset:         260
        .size:           2
        .value_kind:     hidden_group_size_x
      - .offset:         262
        .size:           2
        .value_kind:     hidden_group_size_y
      - .offset:         264
        .size:           2
        .value_kind:     hidden_group_size_z
      - .offset:         266
        .size:           2
        .value_kind:     hidden_remainder_x
      - .offset:         268
        .size:           2
        .value_kind:     hidden_remainder_y
      - .offset:         270
        .size:           2
        .value_kind:     hidden_remainder_z
      - .offset:         288
        .size:           8
        .value_kind:     hidden_global_offset_x
      - .offset:         296
        .size:           8
        .value_kind:     hidden_global_offset_y
      - .offset:         304
        .size:           8
        .value_kind:     hidden_global_offset_z
      - .offset:         312
        .size:           2
        .value_kind:     hidden_grid_dims
      - .offset:         336
        .size:           8
        .value_kind:     hidden_multigrid_sync_arg
      - .offset:         368
        .size:           4
        .value_kind:     hidden_dynamic_lds_size
    .group_segment_fixed_size: 0
    .kernarg_segment_align: 8
    .kernarg_segment_size: 504
    .language:       OpenCL C
    .language_version:
      - 2
      - 0
    .max_flat_workgroup_size: 512
    .name:           _Z10hybrid_fwd6Params
    .private_segment_fixed_size: 0
    .sgpr_count:     108
    .sgpr_spill_count: 146
    .symbol:         _Z10hybrid_fwd6Params.kd
    .uniform_work_group_size: 1
    .uses_dynamic_stack: false
    .vgpr_count:     256
    .vgpr_spill_count: 0
    .wavefront_size: 64
